# GEMM MMA-block edges: duplicate lgkmcnt(0) before each block removed and the scalar/address group after each block moved into its MFMA shadow (stack of two clean-ups)
# speedup vs baseline: 1.0054x; 1.0009x over previous
; #define STG(P, GB) do { const char* _gb = (GB); \
;     _Pragma("unroll") for (int _i = 0; _i < 2; ++_i) { \
;       __builtin_amdgcn_global_load_lds((const unsigned*)(_gb + voff[_i]), \
;         (LAS unsigned*)((LAS char*)(P) + ldsw + _i * 8192), 16, 0, 0); } } while (0)
; #define LDA(dst, b, h) _Pragma("unroll") for (int m = 0; m < 4; ++m) _Pragma("unroll") for (int k = 0; k < 2; ++k) \
;     dst[m][k] = *(const LAS bf16x8*)((LAS char*)SA(b, h) + aoff + m * 2048 + k * 1024)
; #define LDB(dst, b, h) _Pragma("unroll") for (int n = 0; n < 2; ++n) _Pragma("unroll") for (int k = 0; k < 2; ++k) \
;     dst[n][k] = *(const LAS bf16x8*)((LAS char*)SB(b, h) + boff + n * 2048 + k * 1024)
; #define MMA(ai, bj, At_, Bt_) do { __builtin_amdgcn_s_setprio(1); \
;     _Pragma("unroll") for (int m = 0; m < 4; ++m) _Pragma("unroll") for (int n = 0; n < 2; ++n) _Pragma("unroll") for (int k = 0; k < 2; ++k) \
;       acc[ai][bj][m][n] = __builtin_amdgcn_mfma_f32_16x16x32_bf16(Bt_[n][k], At_[m][k], acc[ai][bj][m][n], 0, 0, 0); \
;     __builtin_amdgcn_s_setprio(0); } while (0)
; #define WAIT_L(n) asm volatile("s_waitcnt lgkmcnt(" #n ")" ::: "memory")
; #define BAR __builtin_amdgcn_s_barrier()
; #define SCHED __builtin_amdgcn_sched_barrier(0)
; __device__ __forceinline__ void gemm_phase(const bf16_t* __restrict__ A, const bf16_t* __restrict__ Bt, bf16_t* __restrict__ C, int M, int N, int K,
;                                            int ldc, const int EPI, char* smem, const int wid_u) {
;     ...
;       const bool last = (t == nt - 2);
;       const char* a1 = cA + (size_t)(t + 1) * kstep;
;       const char* a2 = last ? nA : cA + (size_t)(t + 2) * kstep;
;       const char* b2 = last ? nB : cB + (size_t)(t + 2) * kstep;
;       const char* a3 = a2 + kstep;
;       const char* b3 = b2 + kstep;
;       LDB(B0, 0, 0); SCHED; LDA(At, 0, 0); STG(SA(1, 1), a1 + hstep);
;       WAIT_L(8); BAR; WAIT_L(0); MMA(0, 0, At, B0); BAR; SCHED;
;       LDB(B1, 0, 1); STG(SB(0, 0), b2);
;       BAR; WAIT_L(0); MMA(0, 1, At, B1); BAR;
;       LDA(At, 0, 1); STG(SA(0, 0), a2);
;       BAR; WAIT_L(0); MMA(1, 0, At, B0); BAR; SCHED;
.LBB0_145:
	ds_read_b128 v[150:153], v146
	ds_read_b128 v[154:157], v146 offset:1024
	ds_read_b128 v[158:161], v146 offset:2048
	ds_read_b128 v[162:165], v146 offset:3072
	s_add_u32 s18, s16, 0x100
	s_addc_u32 s19, s17, 0
	s_cmp_eq_u32 s49, 12
	s_cselect_b32 s23, s44, s19
	s_cselect_b32 s22, s45, s18
	s_cselect_b32 s21, s11, s48
	s_cselect_b32 s20, s46, s47
	v_lshl_add_u64 v[142:143], s[16:17], 0, v[136:137]
	s_add_i32 m0, s28, 0xc000
	ds_read_b128 v[166:169], v147
	ds_read_b128 v[170:173], v147 offset:1024
	ds_read_b128 v[174:177], v147 offset:2048
	ds_read_b128 v[178:181], v147 offset:3072
	ds_read_b128 v[182:185], v147 offset:4096
	ds_read_b128 v[186:189], v147 offset:5120
	ds_read_b128 v[190:193], v147 offset:6144
	ds_read_b128 v[194:197], v147 offset:7168
	global_load_lds_dwordx4 v[142:143], off
	v_lshl_add_u64 v[142:143], s[16:17], 0, v[134:135]
	s_add_i32 m0, s28, 0xe000
	s_nop 0
	global_load_lds_dwordx4 v[142:143], off
	s_waitcnt lgkmcnt(8)
	s_barrier
	s_waitcnt lgkmcnt(0)
	v_mfma_f32_16x16x32_bf16 v[124:127], v[150:153], v[166:169], v[124:127]
	v_mfma_f32_16x16x32_bf16 v[120:123], v[158:161], v[166:169], v[120:123]
	v_mfma_f32_16x16x32_bf16 v[108:111], v[150:153], v[174:177], v[108:111]
	v_mfma_f32_16x16x32_bf16 v[104:107], v[158:161], v[174:177], v[104:107]
	v_mfma_f32_16x16x32_bf16 v[92:95], v[150:153], v[182:185], v[92:95]
	v_mfma_f32_16x16x32_bf16 v[88:91], v[158:161], v[182:185], v[88:91]
	v_mfma_f32_16x16x32_bf16 v[76:79], v[150:153], v[190:193], v[76:79]
	v_mfma_f32_16x16x32_bf16 v[72:75], v[158:161], v[190:193], v[72:75]
	v_mfma_f32_16x16x32_bf16 v[124:127], v[154:157], v[170:173], v[124:127]
	v_mfma_f32_16x16x32_bf16 v[120:123], v[162:165], v[170:173], v[120:123]
	v_mfma_f32_16x16x32_bf16 v[108:111], v[154:157], v[178:181], v[108:111]
	v_mfma_f32_16x16x32_bf16 v[104:107], v[162:165], v[178:181], v[104:107]
	v_mfma_f32_16x16x32_bf16 v[92:95], v[154:157], v[186:189], v[92:95]
	v_mfma_f32_16x16x32_bf16 v[88:91], v[162:165], v[186:189], v[88:91]
	v_mfma_f32_16x16x32_bf16 v[76:79], v[154:157], v[194:197], v[76:79]
	v_mfma_f32_16x16x32_bf16 v[72:75], v[162:165], v[194:197], v[72:75]
	s_barrier
	s_add_i32 s16, s36, s27
	v_lshl_add_u64 v[142:143], s[20:21], 0, v[130:131]
	s_mov_b32 m0, s16
	ds_read_b128 v[198:201], v148
	ds_read_b128 v[202:205], v148 offset:1024
	ds_read_b128 v[206:209], v148 offset:2048
	ds_read_b128 v[210:213], v148 offset:3072
	global_load_lds_dwordx4 v[142:143], off
	v_lshl_add_u64 v[214:215], s[20:21], 0, v[128:129]
	s_add_i32 m0, s16, 0x2000
	s_nop 0
	global_load_lds_dwordx4 v[214:215], off
	s_barrier
	s_waitcnt lgkmcnt(0)
	v_mfma_f32_16x16x32_bf16 v[116:119], v[198:201], v[166:169], v[116:119]
	v_mfma_f32_16x16x32_bf16 v[112:115], v[206:209], v[166:169], v[112:115]
	v_mfma_f32_16x16x32_bf16 v[100:103], v[198:201], v[174:177], v[100:103]
	v_mfma_f32_16x16x32_bf16 v[96:99], v[206:209], v[174:177], v[96:99]
	v_mfma_f32_16x16x32_bf16 v[84:87], v[198:201], v[182:185], v[84:87]
	v_mfma_f32_16x16x32_bf16 v[80:83], v[206:209], v[182:185], v[80:83]
	v_mfma_f32_16x16x32_bf16 v[68:71], v[198:201], v[190:193], v[68:71]
	v_mfma_f32_16x16x32_bf16 v[64:67], v[206:209], v[190:193], v[64:67]
	v_mfma_f32_16x16x32_bf16 v[116:119], v[202:205], v[170:173], v[116:119]
	v_mfma_f32_16x16x32_bf16 v[112:115], v[210:213], v[170:173], v[112:115]
	v_mfma_f32_16x16x32_bf16 v[100:103], v[202:205], v[178:181], v[100:103]
	v_mfma_f32_16x16x32_bf16 v[96:99], v[210:213], v[178:181], v[96:99]
	v_mfma_f32_16x16x32_bf16 v[84:87], v[202:205], v[186:189], v[84:87]
	v_mfma_f32_16x16x32_bf16 v[80:83], v[210:213], v[186:189], v[80:83]
	s_mov_b32 m0, s28
	v_lshl_add_u64 v[216:217], s[22:23], 0, v[130:131]
	v_mfma_f32_16x16x32_bf16 v[68:71], v[202:205], v[194:197], v[68:71]
	v_mfma_f32_16x16x32_bf16 v[64:67], v[210:213], v[194:197], v[64:67]
	s_barrier
	ds_read_b128 v[166:169], v147 offset:16384
	ds_read_b128 v[170:173], v147 offset:17408
	ds_read_b128 v[174:177], v147 offset:18432
	ds_read_b128 v[178:181], v147 offset:19456
	ds_read_b128 v[182:185], v147 offset:20480
	ds_read_b128 v[186:189], v147 offset:21504
	ds_read_b128 v[190:193], v147 offset:22528
	ds_read_b128 v[194:197], v147 offset:23552
	global_load_lds_dwordx4 v[216:217], off
	v_lshl_add_u64 v[218:219], s[22:23], 0, v[128:129]
	s_mov_b32 m0, s29
	s_nop 0
	global_load_lds_dwordx4 v[218:219], off
	s_barrier
	s_waitcnt lgkmcnt(0)
	v_mfma_f32_16x16x32_bf16 v[60:63], v[150:153], v[166:169], v[60:63]
	v_mfma_f32_16x16x32_bf16 v[56:59], v[158:161], v[166:169], v[56:59]
	v_mfma_f32_16x16x32_bf16 v[44:47], v[150:153], v[174:177], v[44:47]
	v_mfma_f32_16x16x32_bf16 v[40:43], v[158:161], v[174:177], v[40:43]
	v_mfma_f32_16x16x32_bf16 v[28:31], v[150:153], v[182:185], v[28:31]
	v_mfma_f32_16x16x32_bf16 v[24:27], v[158:161], v[182:185], v[24:27]
	v_mfma_f32_16x16x32_bf16 v[12:15], v[150:153], v[190:193], v[12:15]
	v_mfma_f32_16x16x32_bf16 v[8:11], v[158:161], v[190:193], v[8:11]
	v_mfma_f32_16x16x32_bf16 v[60:63], v[154:157], v[170:173], v[60:63]
	v_mfma_f32_16x16x32_bf16 v[56:59], v[162:165], v[170:173], v[56:59]
	v_mfma_f32_16x16x32_bf16 v[44:47], v[154:157], v[178:181], v[44:47]
	v_mfma_f32_16x16x32_bf16 v[40:43], v[162:165], v[178:181], v[40:43]
	v_mfma_f32_16x16x32_bf16 v[28:31], v[154:157], v[186:189], v[28:31]
	v_mfma_f32_16x16x32_bf16 v[24:27], v[162:165], v[186:189], v[24:27]
	v_mfma_f32_16x16x32_bf16 v[12:15], v[154:157], v[194:197], v[12:15]
	v_mfma_f32_16x16x32_bf16 v[8:11], v[162:165], v[194:197], v[8:11]
	s_barrier
; #define STG(P, GB) do { const char* _gb = (GB); \
;     _Pragma("unroll") for (int _i = 0; _i < 2; ++_i) { \
;       __builtin_amdgcn_global_load_lds((const unsigned*)(_gb + voff[_i]), \
;         (LAS unsigned*)((LAS char*)(P) + ldsw + _i * 8192), 16, 0, 0); } } while (0)
; #define LDA(dst, b, h) _Pragma("unroll") for (int m = 0; m < 4; ++m) _Pragma("unroll") for (int k = 0; k < 2; ++k) \
;     dst[m][k] = *(const LAS bf16x8*)((LAS char*)SA(b, h) + aoff + m * 2048 + k * 1024)
; #define LDB(dst, b, h) _Pragma("unroll") for (int n = 0; n < 2; ++n) _Pragma("unroll") for (int k = 0; k < 2; ++k) \
;     dst[n][k] = *(const LAS bf16x8*)((LAS char*)SB(b, h) + boff + n * 2048 + k * 1024)
; #define MMA(ai, bj, At_, Bt_) do { __builtin_amdgcn_s_setprio(1); \
;     _Pragma("unroll") for (int m = 0; m < 4; ++m) _Pragma("unroll") for (int n = 0; n < 2; ++n) _Pragma("unroll") for (int k = 0; k < 2; ++k) \
;       acc[ai][bj][m][n] = __builtin_amdgcn_mfma_f32_16x16x32_bf16(Bt_[n][k], At_[m][k], acc[ai][bj][m][n], 0, 0, 0); \
;     __builtin_amdgcn_s_setprio(0); } while (0)
; #define WAIT_V(n) asm volatile("s_waitcnt vmcnt(" #n ")" ::: "memory")
; #define WAIT_L(n) asm volatile("s_waitcnt lgkmcnt(" #n ")" ::: "memory")
; #define BAR __builtin_amdgcn_s_barrier()
; #define SCHED __builtin_amdgcn_sched_barrier(0)
; __device__ __forceinline__ void gemm_phase(const bf16_t* __restrict__ A, const bf16_t* __restrict__ Bt, bf16_t* __restrict__ C, int M, int N, int K,
;                                            int ldc, const int EPI, char* smem, const int wid_u) {
;     ...
;       STG(SB(0, 1), b2 + hstep);
;       WAIT_V(6); BAR; MMA(1, 1, At, B1); BAR;
;       LDB(B0, 1, 0); SCHED; LDA(At, 1, 0); STG(SA(0, 1), a2 + hstep);
;       WAIT_L(8); BAR; WAIT_L(0); MMA(0, 0, At, B0); BAR; SCHED;
;       LDB(B1, 1, 1); STG(SB(1, 0), b3);
;       BAR; WAIT_L(0); MMA(0, 1, At, B1); BAR;
;       LDA(At, 1, 1); STG(SA(1, 0), a3);
	s_add_u32 s16, s20, 0x40000
	s_addc_u32 s17, s21, 0
	s_add_i32 s50, s37, s27
	v_lshl_add_u64 v[150:151], s[16:17], 0, v[130:131]
	s_mov_b32 m0, s50
	s_nop 0
	global_load_lds_dwordx4 v[150:151], off
	v_lshl_add_u64 v[150:151], s[16:17], 0, v[128:129]
	s_add_i32 m0, s50, 0x2000
	s_nop 0
	global_load_lds_dwordx4 v[150:151], off
	s_waitcnt vmcnt(6)
	s_barrier
	v_mfma_f32_16x16x32_bf16 v[52:55], v[198:201], v[166:169], v[52:55]
	v_mfma_f32_16x16x32_bf16 v[48:51], v[206:209], v[166:169], v[48:51]
	v_mfma_f32_16x16x32_bf16 v[36:39], v[198:201], v[174:177], v[36:39]
	v_mfma_f32_16x16x32_bf16 v[32:35], v[206:209], v[174:177], v[32:35]
	v_mfma_f32_16x16x32_bf16 v[20:23], v[198:201], v[182:185], v[20:23]
	v_mfma_f32_16x16x32_bf16 v[16:19], v[206:209], v[182:185], v[16:19]
	v_mfma_f32_16x16x32_bf16 v[4:7], v[198:201], v[190:193], v[4:7]
	v_mfma_f32_16x16x32_bf16 v[0:3], v[206:209], v[190:193], v[0:3]
	v_mfma_f32_16x16x32_bf16 v[52:55], v[202:205], v[170:173], v[52:55]
	v_mfma_f32_16x16x32_bf16 v[48:51], v[210:213], v[170:173], v[48:51]
	v_mfma_f32_16x16x32_bf16 v[36:39], v[202:205], v[178:181], v[36:39]
	v_mfma_f32_16x16x32_bf16 v[32:35], v[210:213], v[178:181], v[32:35]
	v_mfma_f32_16x16x32_bf16 v[20:23], v[202:205], v[186:189], v[20:23]
	v_mfma_f32_16x16x32_bf16 v[16:19], v[210:213], v[186:189], v[16:19]
	s_add_i32 s50, 0, 0x18000
	v_add_u32_e32 v149, s50, v145
	v_mfma_f32_16x16x32_bf16 v[4:7], v[202:205], v[194:197], v[4:7]
	v_mfma_f32_16x16x32_bf16 v[0:3], v[210:213], v[194:197], v[0:3]
	s_barrier
	ds_read_b128 v[150:153], v149
	ds_read_b128 v[154:157], v149 offset:1024
	ds_read_b128 v[158:161], v149 offset:2048
	ds_read_b128 v[162:165], v149 offset:3072
	s_add_u32 s16, s22, 0x40000
	s_addc_u32 s17, s23, 0
	s_mov_b32 m0, s30
	v_lshl_add_u64 v[198:199], s[16:17], 0, v[130:131]
	ds_read_b128 v[166:169], v147 offset:32768
	ds_read_b128 v[170:173], v147 offset:33792
	ds_read_b128 v[174:177], v147 offset:34816
	ds_read_b128 v[178:181], v147 offset:35840
	ds_read_b128 v[182:185], v147 offset:36864
	ds_read_b128 v[186:189], v147 offset:37888
	ds_read_b128 v[190:193], v147 offset:38912
	ds_read_b128 v[194:197], v147 offset:39936
	global_load_lds_dwordx4 v[198:199], off
	v_lshl_add_u64 v[198:199], s[16:17], 0, v[128:129]
	s_mov_b32 m0, s31
	s_nop 0
	global_load_lds_dwordx4 v[198:199], off
	s_waitcnt lgkmcnt(8)
	s_barrier
	s_waitcnt lgkmcnt(0)
	v_mfma_f32_16x16x32_bf16 v[124:127], v[150:153], v[166:169], v[124:127]
	v_mfma_f32_16x16x32_bf16 v[120:123], v[158:161], v[166:169], v[120:123]
	v_mfma_f32_16x16x32_bf16 v[108:111], v[150:153], v[174:177], v[108:111]
	v_mfma_f32_16x16x32_bf16 v[104:107], v[158:161], v[174:177], v[104:107]
	v_mfma_f32_16x16x32_bf16 v[92:95], v[150:153], v[182:185], v[92:95]
	v_mfma_f32_16x16x32_bf16 v[88:91], v[158:161], v[182:185], v[88:91]
	v_mfma_f32_16x16x32_bf16 v[76:79], v[150:153], v[190:193], v[76:79]
	v_mfma_f32_16x16x32_bf16 v[72:75], v[158:161], v[190:193], v[72:75]
	v_mfma_f32_16x16x32_bf16 v[124:127], v[154:157], v[170:173], v[124:127]
	v_mfma_f32_16x16x32_bf16 v[120:123], v[162:165], v[170:173], v[120:123]
	v_mfma_f32_16x16x32_bf16 v[108:111], v[154:157], v[178:181], v[108:111]
	v_mfma_f32_16x16x32_bf16 v[104:107], v[162:165], v[178:181], v[104:107]
	v_mfma_f32_16x16x32_bf16 v[92:95], v[154:157], v[186:189], v[92:95]
	v_mfma_f32_16x16x32_bf16 v[88:91], v[162:165], v[186:189], v[88:91]
	v_mfma_f32_16x16x32_bf16 v[76:79], v[154:157], v[194:197], v[76:79]
	v_mfma_f32_16x16x32_bf16 v[72:75], v[162:165], v[194:197], v[72:75]
	s_barrier
	s_add_i32 s22, 0, 0x1c000
	s_add_i32 s16, s50, s27
	v_add_u32_e32 v149, s22, v145
	v_lshl_add_u64 v[142:143], v[142:143], 0, s[6:7]
	s_mov_b32 m0, s16
	ds_read_b128 v[198:201], v149
	ds_read_b128 v[202:205], v149 offset:1024
	ds_read_b128 v[206:209], v149 offset:2048
	ds_read_b128 v[210:213], v149 offset:3072
	global_load_lds_dwordx4 v[142:143], off
	v_lshl_add_u64 v[142:143], v[214:215], 0, s[6:7]
	s_add_i32 m0, s16, 0x2000
	s_nop 0
	global_load_lds_dwordx4 v[142:143], off
	s_barrier
	s_waitcnt lgkmcnt(0)
	v_mfma_f32_16x16x32_bf16 v[116:119], v[198:201], v[166:169], v[116:119]
	v_mfma_f32_16x16x32_bf16 v[112:115], v[206:209], v[166:169], v[112:115]
	v_mfma_f32_16x16x32_bf16 v[100:103], v[198:201], v[174:177], v[100:103]
	v_mfma_f32_16x16x32_bf16 v[96:99], v[206:209], v[174:177], v[96:99]
	v_mfma_f32_16x16x32_bf16 v[84:87], v[198:201], v[182:185], v[84:87]
	v_mfma_f32_16x16x32_bf16 v[80:83], v[206:209], v[182:185], v[80:83]
	v_mfma_f32_16x16x32_bf16 v[68:71], v[198:201], v[190:193], v[68:71]
	v_mfma_f32_16x16x32_bf16 v[64:67], v[206:209], v[190:193], v[64:67]
	v_mfma_f32_16x16x32_bf16 v[116:119], v[202:205], v[170:173], v[116:119]
	v_mfma_f32_16x16x32_bf16 v[112:115], v[210:213], v[170:173], v[112:115]
	v_mfma_f32_16x16x32_bf16 v[100:103], v[202:205], v[178:181], v[100:103]
	v_mfma_f32_16x16x32_bf16 v[96:99], v[210:213], v[178:181], v[96:99]
	v_mfma_f32_16x16x32_bf16 v[84:87], v[202:205], v[186:189], v[84:87]
	v_mfma_f32_16x16x32_bf16 v[80:83], v[210:213], v[186:189], v[80:83]
	s_mov_b32 m0, s34
	v_lshl_add_u64 v[142:143], v[216:217], 0, s[6:7]
	v_mfma_f32_16x16x32_bf16 v[68:71], v[202:205], v[194:197], v[68:71]
	v_mfma_f32_16x16x32_bf16 v[64:67], v[210:213], v[194:197], v[64:67]
	s_barrier
	ds_read_b128 v[166:169], v147 offset:49152
	ds_read_b128 v[170:173], v147 offset:50176
	ds_read_b128 v[174:177], v147 offset:51200
	ds_read_b128 v[178:181], v147 offset:52224
	ds_read_b128 v[182:185], v147 offset:53248
	ds_read_b128 v[186:189], v147 offset:54272
	ds_read_b128 v[190:193], v147 offset:55296
	ds_read_b128 v[194:197], v147 offset:56320
	global_load_lds_dwordx4 v[142:143], off
	v_lshl_add_u64 v[142:143], v[218:219], 0, s[6:7]
	s_mov_b32 m0, s35
	s_nop 0
	global_load_lds_dwordx4 v[142:143], off
	s_barrier
; #define STG(P, GB) do { const char* _gb = (GB); \
;     _Pragma("unroll") for (int _i = 0; _i < 2; ++_i) { \
;       __builtin_amdgcn_global_load_lds((const unsigned*)(_gb + voff[_i]), \
;         (LAS unsigned*)((LAS char*)(P) + ldsw + _i * 8192), 16, 0, 0); } } while (0)
; #define MMA(ai, bj, At_, Bt_) do { __builtin_amdgcn_s_setprio(1); \
;     _Pragma("unroll") for (int m = 0; m < 4; ++m) _Pragma("unroll") for (int n = 0; n < 2; ++n) _Pragma("unroll") for (int k = 0; k < 2; ++k) \
;       acc[ai][bj][m][n] = __builtin_amdgcn_mfma_f32_16x16x32_bf16(Bt_[n][k], At_[m][k], acc[ai][bj][m][n], 0, 0, 0); \
;     __builtin_amdgcn_s_setprio(0); } while (0)
; #define WAIT_V(n) asm volatile("s_waitcnt vmcnt(" #n ")" ::: "memory")
; #define WAIT_L(n) asm volatile("s_waitcnt lgkmcnt(" #n ")" ::: "memory")
; #define BAR __builtin_amdgcn_s_barrier()
; #define SCHED __builtin_amdgcn_sched_barrier(0)
; __device__ __forceinline__ void gemm_phase(const bf16_t* __restrict__ A, const bf16_t* __restrict__ Bt, bf16_t* __restrict__ C, int M, int N, int K,
;                                            int ldc, const int EPI, char* smem, const int wid_u) {
;     ...
;       BAR; WAIT_L(0); MMA(1, 0, At, B0); BAR; SCHED;
;       STG(SB(1, 1), b3 + hstep);
;       WAIT_V(6); BAR; MMA(1, 1, At, B1); BAR;
;     }
;     {
;       const int brow = pm * BM, bcol = pn * BM;
; #pragma unroll
;       for (int ai = 0; ai < 2; ++ai)
; #pragma unroll
;         for (int m = 0; m < 4; ++m) {
;           const size_t row = (size_t)(brow + ai * HALF + wr * 64 + m * 16 + fr);
;           if (EPI == 0) {
; #pragma unroll
;             for (int bj = 0; bj < 2; ++bj) {
;               const f32x4 v0 = acc[ai][bj][m][0], v1 = acc[ai][bj][m][1];
;               uint4 u; u.x = cvt_pk_bf16(v0[0], v0[1]); u.y = cvt_pk_bf16(v0[2], v0[3]); u.z = cvt_pk_bf16(v1[0], v1[1]); u.w = cvt_pk_bf16(v1[2], v1[3]);
;               *(uint4*)(C + row * ldc + bcol + bj * HALF + wc * 32 + fq * 8) = u;
;             }
;           } else {
;             float o[8];
; #pragma unroll
;             for (int n = 0; n < 2; ++n) {
;               const f32x4 a = acc[ai][0][m][n], b = acc[ai][1][m][n];
; #pragma unroll
;               for (int j = 0; j < 4; ++j) o[n * 4 + j] = a[j] * __builtin_amdgcn_rcpf(1.f + __expf(-a[j])) * b[j];
;             }
;             *(uint4*)(C + row * ldc + (bcol >> 1) + wc * 32 + fq * 8) = pack8(o);
	s_waitcnt lgkmcnt(0)
	v_mfma_f32_16x16x32_bf16 v[60:63], v[150:153], v[166:169], v[60:63]
	v_mfma_f32_16x16x32_bf16 v[56:59], v[158:161], v[166:169], v[56:59]
	v_mfma_f32_16x16x32_bf16 v[44:47], v[150:153], v[174:177], v[44:47]
	v_mfma_f32_16x16x32_bf16 v[40:43], v[158:161], v[174:177], v[40:43]
	v_mfma_f32_16x16x32_bf16 v[28:31], v[150:153], v[182:185], v[28:31]
	v_mfma_f32_16x16x32_bf16 v[24:27], v[158:161], v[182:185], v[24:27]
	v_mfma_f32_16x16x32_bf16 v[12:15], v[150:153], v[190:193], v[12:15]
	v_mfma_f32_16x16x32_bf16 v[8:11], v[158:161], v[190:193], v[8:11]
	v_mfma_f32_16x16x32_bf16 v[60:63], v[154:157], v[170:173], v[60:63]
	v_mfma_f32_16x16x32_bf16 v[56:59], v[162:165], v[170:173], v[56:59]
	v_mfma_f32_16x16x32_bf16 v[44:47], v[154:157], v[178:181], v[44:47]
	v_mfma_f32_16x16x32_bf16 v[40:43], v[162:165], v[178:181], v[40:43]
	v_mfma_f32_16x16x32_bf16 v[28:31], v[154:157], v[186:189], v[28:31]
	v_mfma_f32_16x16x32_bf16 v[24:27], v[162:165], v[186:189], v[24:27]
	v_mfma_f32_16x16x32_bf16 v[12:15], v[154:157], v[194:197], v[12:15]
	v_mfma_f32_16x16x32_bf16 v[8:11], v[162:165], v[194:197], v[8:11]
	s_barrier
	s_add_u32 s16, s20, 0x40080
	s_addc_u32 s17, s21, 0
	s_add_i32 s20, s22, s27
	v_lshl_add_u64 v[142:143], s[16:17], 0, v[130:131]
	s_mov_b32 m0, s20
	s_nop 0
	global_load_lds_dwordx4 v[142:143], off
	v_lshl_add_u64 v[142:143], s[16:17], 0, v[128:129]
	s_add_i32 m0, s20, 0x2000
	s_nop 0
	global_load_lds_dwordx4 v[142:143], off
	s_waitcnt vmcnt(6)
	s_barrier
	v_mfma_f32_16x16x32_bf16 v[52:55], v[198:201], v[166:169], v[52:55]
	v_mfma_f32_16x16x32_bf16 v[48:51], v[206:209], v[166:169], v[48:51]
	v_mfma_f32_16x16x32_bf16 v[36:39], v[198:201], v[174:177], v[36:39]
	v_mfma_f32_16x16x32_bf16 v[32:35], v[206:209], v[174:177], v[32:35]
	v_mfma_f32_16x16x32_bf16 v[20:23], v[198:201], v[182:185], v[20:23]
	v_mfma_f32_16x16x32_bf16 v[16:19], v[206:209], v[182:185], v[16:19]
	v_mfma_f32_16x16x32_bf16 v[4:7], v[198:201], v[190:193], v[4:7]
	v_mfma_f32_16x16x32_bf16 v[0:3], v[206:209], v[190:193], v[0:3]
	v_mfma_f32_16x16x32_bf16 v[52:55], v[202:205], v[170:173], v[52:55]
	v_mfma_f32_16x16x32_bf16 v[48:51], v[210:213], v[170:173], v[48:51]
	v_mfma_f32_16x16x32_bf16 v[36:39], v[202:205], v[178:181], v[36:39]
	v_mfma_f32_16x16x32_bf16 v[32:35], v[210:213], v[178:181], v[32:35]
	v_mfma_f32_16x16x32_bf16 v[20:23], v[202:205], v[186:189], v[20:23]
	v_mfma_f32_16x16x32_bf16 v[16:19], v[210:213], v[186:189], v[16:19]
	s_add_i32 s49, s49, 2
	s_add_u32 s47, s47, 0x100
	s_addc_u32 s48, s48, 0
	s_cmp_gt_u32 s49, 13
	s_mov_b64 s[16:17], s[18:19]
	v_mfma_f32_16x16x32_bf16 v[4:7], v[202:205], v[194:197], v[4:7]
	v_mfma_f32_16x16x32_bf16 v[0:3], v[210:213], v[194:197], v[0:3]
	s_barrier
	s_cbranch_scc0 .LBB0_145
	v_mul_f32_e32 v142, 0xbfb8aa3b, v124
	v_exp_f32_e32 v142, v142
	v_mul_f32_e32 v143, 0xbfb8aa3b, v125
	v_exp_f32_e32 v143, v143
	s_lshl_b32 s16, s40, 8
	v_add_f32_e32 v142, 1.0, v142
	v_rcp_f32_e32 v150, v142
	v_add_f32_e32 v142, 1.0, v143
	v_rcp_f32_e32 v151, v142
	s_mov_b32 s17, s9
	v_lshl_add_u32 v149, s41, 8, v144
	v_lshl_add_u64 v[142:143], v[132:133], 0, s[16:17]
	v_pk_mul_f32 v[124:125], v[124:125], v[150:151]
	v_mul_f32_e32 v150, 0xbfb8aa3b, v126
	v_mul_f32_e32 v151, 0xbfb8aa3b, v127
	v_exp_f32_e32 v150, v150
	v_exp_f32_e32 v151, v151
	v_pk_mul_f32 v[116:117], v[124:125], v[116:117]
	s_and_b64 vcc, exec, s[2:3]
	v_add_f32_e32 v124, 1.0, v150
	v_add_f32_e32 v125, 1.0, v151
	v_mul_f32_e32 v150, 0xbfb8aa3b, v120
	v_mul_f32_e32 v151, 0xbfb8aa3b, v121
	v_rcp_f32_e32 v124, v124
	v_rcp_f32_e32 v125, v125
	v_exp_f32_e32 v150, v150
	v_exp_f32_e32 v151, v151
	s_mov_b32 s41, s8
	v_pk_mul_f32 v[124:125], v[126:127], v[124:125]
	v_add_f32_e32 v126, 1.0, v150
	v_add_f32_e32 v127, 1.0, v151
	v_mul_f32_e32 v150, 0xbfb8aa3b, v122
	v_mul_f32_e32 v151, 0xbfb8aa3b, v123
	v_exp_f32_e32 v150, v150
	v_exp_f32_e32 v151, v151
	v_rcp_f32_e32 v126, v126
	v_rcp_f32_e32 v127, v127
	v_add_f32_e32 v150, 1.0, v150
	v_add_f32_e32 v151, 1.0, v151
	v_rcp_f32_e32 v150, v150
	v_rcp_f32_e32 v151, v151
	v_pk_mul_f32 v[120:121], v[120:121], v[126:127]
	v_pk_mul_f32 v[118:119], v[124:125], v[118:119]
	v_pk_mul_f32 v[120:121], v[120:121], v[112:113]
	v_pk_mul_f32 v[112:113], v[122:123], v[150:151]
	s_mov_b32 s40, s10
	v_pk_mul_f32 v[122:123], v[112:113], v[114:115]
	v_mul_f32_e32 v115, 0xbfb8aa3b, v108
	v_cvt_pk_bf16_f32 v112, v116, v117
	v_exp_f32_e32 v116, v115
	v_mul_f32_e32 v115, 0xbfb8aa3b, v109
	v_exp_f32_e32 v117, v115
	v_cvt_pk_bf16_f32 v113, v118, v119
	v_cvt_pk_bf16_f32 v114, v120, v121
	v_cvt_pk_bf16_f32 v115, v122, v123
	v_add_f32_e32 v116, 1.0, v116
	v_add_f32_e32 v117, 1.0, v117
	v_mad_i64_i32 v[118:119], s[16:17], v149, s38, v[142:143]
	v_rcp_f32_e32 v116, v116
	v_rcp_f32_e32 v117, v117
	global_store_dwordx4 v[118:119], v[112:115], off
	s_mov_b64 s[18:19], s[14:15]
	v_pk_mul_f32 v[108:109], v[108:109], v[116:117]
	v_mul_f32_e32 v112, 0xbfb8aa3b, v110
	v_mul_f32_e32 v113, 0xbfb8aa3b, v111
	v_exp_f32_e32 v112, v112
	v_exp_f32_e32 v113, v113
	v_pk_mul_f32 v[100:101], v[108:109], v[100:101]
	v_or_b32_e32 v114, 16, v149
	v_add_f32_e32 v108, 1.0, v112
	v_add_f32_e32 v109, 1.0, v113
	v_mul_f32_e32 v112, 0xbfb8aa3b, v104
	v_mul_f32_e32 v113, 0xbfb8aa3b, v105
	v_rcp_f32_e32 v108, v108
	v_rcp_f32_e32 v109, v109
	v_exp_f32_e32 v112, v112
	v_exp_f32_e32 v113, v113
	v_pk_mul_f32 v[108:109], v[110:111], v[108:109]
	v_add_f32_e32 v110, 1.0, v112
	v_add_f32_e32 v111, 1.0, v113
	v_mul_f32_e32 v112, 0xbfb8aa3b, v106
	v_mul_f32_e32 v113, 0xbfb8aa3b, v107
	v_exp_f32_e32 v112, v112
	v_exp_f32_e32 v113, v113
	v_rcp_f32_e32 v110, v110
	v_rcp_f32_e32 v111, v111
	v_add_f32_e32 v112, 1.0, v112
; __device__ __forceinline__ void gemm_phase(const bf16_t* __restrict__ A, const bf16_t* __restrict__ Bt, bf16_t* __restrict__ C, int M, int N, int K,
;                                            int ldc, const int EPI, char* smem, const int wid_u) {
;     ...
;       for (int ai = 0; ai < 2; ++ai)
; #pragma unroll
;         for (int m = 0; m < 4; ++m) {
;           const size_t row = (size_t)(brow + ai * HALF + wr * 64 + m * 16 + fr);
;           if (EPI == 0) {
; #pragma unroll
;             for (int bj = 0; bj < 2; ++bj) {
;               const f32x4 v0 = acc[ai][bj][m][0], v1 = acc[ai][bj][m][1];
;               uint4 u; u.x = cvt_pk_bf16(v0[0], v0[1]); u.y = cvt_pk_bf16(v0[2], v0[3]); u.z = cvt_pk_bf16(v1[0], v1[1]); u.w = cvt_pk_bf16(v1[2], v1[3]);
;               *(uint4*)(C + row * ldc + bcol + bj * HALF + wc * 32 + fq * 8) = u;
;             }
;           } else {
;             float o[8];
; #pragma unroll
;             for (int n = 0; n < 2; ++n) {
;               const f32x4 a = acc[ai][0][m][n], b = acc[ai][1][m][n];
; #pragma unroll
;               for (int j = 0; j < 4; ++j) o[n * 4 + j] = a[j] * __builtin_amdgcn_rcpf(1.f + __expf(-a[j])) * b[j];
;             }
;             *(uint4*)(C + row * ldc + (bcol >> 1) + wc * 32 + fq * 8) = pack8(o);
	v_add_f32_e32 v113, 1.0, v113
	v_rcp_f32_e32 v112, v112
	v_rcp_f32_e32 v113, v113
	v_pk_mul_f32 v[104:105], v[104:105], v[110:111]
	v_pk_mul_f32 v[102:103], v[108:109], v[102:103]
	v_pk_mul_f32 v[104:105], v[104:105], v[96:97]
	v_pk_mul_f32 v[96:97], v[106:107], v[112:113]
	s_nop 0
	v_pk_mul_f32 v[106:107], v[96:97], v[98:99]
	v_mul_f32_e32 v99, 0xbfb8aa3b, v92
	v_cvt_pk_bf16_f32 v96, v100, v101
	v_exp_f32_e32 v100, v99
	v_mul_f32_e32 v99, 0xbfb8aa3b, v93
	v_exp_f32_e32 v101, v99
	v_cvt_pk_bf16_f32 v97, v102, v103
	v_cvt_pk_bf16_f32 v98, v104, v105
	v_cvt_pk_bf16_f32 v99, v106, v107
	v_add_f32_e32 v100, 1.0, v100
	v_add_f32_e32 v101, 1.0, v101
	v_mad_i64_i32 v[102:103], s[16:17], v114, s38, v[142:143]
	v_rcp_f32_e32 v100, v100
	v_rcp_f32_e32 v101, v101
	global_store_dwordx4 v[102:103], v[96:99], off
	v_pk_mul_f32 v[92:93], v[92:93], v[100:101]
	s_nop 0
	v_mul_f32_e32 v96, 0xbfb8aa3b, v94
	v_mul_f32_e32 v97, 0xbfb8aa3b, v95
	v_exp_f32_e32 v96, v96
	v_exp_f32_e32 v97, v97
	v_pk_mul_f32 v[84:85], v[92:93], v[84:85]
	v_or_b32_e32 v98, 32, v149
	v_add_f32_e32 v92, 1.0, v96
	v_add_f32_e32 v93, 1.0, v97
	v_mul_f32_e32 v96, 0xbfb8aa3b, v88
	v_mul_f32_e32 v97, 0xbfb8aa3b, v89
	v_rcp_f32_e32 v92, v92
	v_rcp_f32_e32 v93, v93
	v_exp_f32_e32 v96, v96
	v_exp_f32_e32 v97, v97
	v_pk_mul_f32 v[92:93], v[94:95], v[92:93]
	v_add_f32_e32 v94, 1.0, v96
	v_add_f32_e32 v95, 1.0, v97
	v_mul_f32_e32 v96, 0xbfb8aa3b, v90
	v_mul_f32_e32 v97, 0xbfb8aa3b, v91
	v_exp_f32_e32 v96, v96
	v_exp_f32_e32 v97, v97
	v_rcp_f32_e32 v94, v94
	v_rcp_f32_e32 v95, v95
	v_add_f32_e32 v96, 1.0, v96
	v_add_f32_e32 v97, 1.0, v97
	v_rcp_f32_e32 v96, v96
	v_rcp_f32_e32 v97, v97
	v_pk_mul_f32 v[88:89], v[88:89], v[94:95]
	v_pk_mul_f32 v[86:87], v[92:93], v[86:87]
	v_pk_mul_f32 v[88:89], v[88:89], v[80:81]
	v_pk_mul_f32 v[80:81], v[90:91], v[96:97]
	s_nop 0
	v_pk_mul_f32 v[90:91], v[80:81], v[82:83]
	v_mul_f32_e32 v83, 0xbfb8aa3b, v76
	v_cvt_pk_bf16_f32 v80, v84, v85
	v_exp_f32_e32 v84, v83
	v_mul_f32_e32 v83, 0xbfb8aa3b, v77
	v_exp_f32_e32 v85, v83
	v_cvt_pk_bf16_f32 v81, v86, v87
	v_cvt_pk_bf16_f32 v82, v88, v89
	v_cvt_pk_bf16_f32 v83, v90, v91
	v_add_f32_e32 v84, 1.0, v84
	v_add_f32_e32 v85, 1.0, v85
	v_mad_i64_i32 v[86:87], s[16:17], v98, s38, v[142:143]
	v_rcp_f32_e32 v84, v84
	v_rcp_f32_e32 v85, v85
	global_store_dwordx4 v[86:87], v[80:83], off
	v_pk_mul_f32 v[76:77], v[76:77], v[84:85]
	s_nop 0
	v_mul_f32_e32 v80, 0xbfb8aa3b, v78
	v_mul_f32_e32 v81, 0xbfb8aa3b, v79
	v_exp_f32_e32 v80, v80
	v_exp_f32_e32 v81, v81
	v_pk_mul_f32 v[68:69], v[76:77], v[68:69]
	v_or_b32_e32 v82, 48, v149
	v_add_f32_e32 v76, 1.0, v80
	v_add_f32_e32 v77, 1.0, v81
	v_mul_f32_e32 v80, 0xbfb8aa3b, v72
	v_mul_f32_e32 v81, 0xbfb8aa3b, v73
	v_rcp_f32_e32 v76, v76
	v_rcp_f32_e32 v77, v77
	v_exp_f32_e32 v80, v80
	v_exp_f32_e32 v81, v81
	v_pk_mul_f32 v[76:77], v[78:79], v[76:77]
	v_add_f32_e32 v78, 1.0, v80
	v_add_f32_e32 v79, 1.0, v81
	v_mul_f32_e32 v80, 0xbfb8aa3b, v74
	v_mul_f32_e32 v81, 0xbfb8aa3b, v75
	v_exp_f32_e32 v80, v80
	v_exp_f32_e32 v81, v81
	v_rcp_f32_e32 v78, v78
	v_rcp_f32_e32 v79, v79
	v_add_f32_e32 v80, 1.0, v80
	v_add_f32_e32 v81, 1.0, v81
	v_rcp_f32_e32 v80, v80
	v_rcp_f32_e32 v81, v81
	v_pk_mul_f32 v[72:73], v[72:73], v[78:79]
	v_pk_mul_f32 v[70:71], v[76:77], v[70:71]
	v_pk_mul_f32 v[72:73], v[72:73], v[64:65]
	v_pk_mul_f32 v[64:65], v[74:75], v[80:81]
	s_nop 0
	v_pk_mul_f32 v[74:75], v[64:65], v[66:67]
	v_mul_f32_e32 v67, 0xbfb8aa3b, v60
	v_cvt_pk_bf16_f32 v64, v68, v69
	v_exp_f32_e32 v68, v67
	v_mul_f32_e32 v67, 0xbfb8aa3b, v61
	v_exp_f32_e32 v69, v67
	v_cvt_pk_bf16_f32 v65, v70, v71
	v_cvt_pk_bf16_f32 v66, v72, v73
	v_cvt_pk_bf16_f32 v67, v74, v75
	v_add_f32_e32 v68, 1.0, v68
	v_add_f32_e32 v69, 1.0, v69
	v_mad_i64_i32 v[70:71], s[16:17], v82, s38, v[142:143]
	v_rcp_f32_e32 v68, v68
	v_rcp_f32_e32 v69, v69
	global_store_dwordx4 v[70:71], v[64:67], off
	v_pk_mul_f32 v[60:61], v[60:61], v[68:69]
	s_nop 0
	v_mul_f32_e32 v64, 0xbfb8aa3b, v62
	v_mul_f32_e32 v65, 0xbfb8aa3b, v63
	v_exp_f32_e32 v64, v64
	v_exp_f32_e32 v65, v65
	v_pk_mul_f32 v[52:53], v[60:61], v[52:53]
	v_add_u32_e32 v66, 0x80, v149
	v_add_f32_e32 v60, 1.0, v64
	v_add_f32_e32 v61, 1.0, v65
	v_mul_f32_e32 v64, 0xbfb8aa3b, v56
	v_mul_f32_e32 v65, 0xbfb8aa3b, v57
	v_rcp_f32_e32 v60, v60
	v_rcp_f32_e32 v61, v61
	v_exp_f32_e32 v64, v64
	v_exp_f32_e32 v65, v65
	v_pk_mul_f32 v[60:61], v[62:63], v[60:61]
	v_add_f32_e32 v62, 1.0, v64
	v_add_f32_e32 v63, 1.0, v65
	v_mul_f32_e32 v64, 0xbfb8aa3b, v58
	v_mul_f32_e32 v65, 0xbfb8aa3b, v59
	v_exp_f32_e32 v64, v64
	v_exp_f32_e32 v65, v65
	v_rcp_f32_e32 v62, v62
	v_rcp_f32_e32 v63, v63
	v_add_f32_e32 v64, 1.0, v64
	v_add_f32_e32 v65, 1.0, v65
	v_rcp_f32_e32 v64, v64
	v_rcp_f32_e32 v65, v65
	v_pk_mul_f32 v[56:57], v[56:57], v[62:63]
	v_pk_mul_f32 v[54:55], v[60:61], v[54:55]
	v_pk_mul_f32 v[56:57], v[56:57], v[48:49]
	v_pk_mul_f32 v[48:49], v[58:59], v[64:65]
	s_nop 0
	v_pk_mul_f32 v[58:59], v[48:49], v[50:51]
; #define WAIT_V(n) asm volatile("s_waitcnt vmcnt(" #n ")" ::: "memory")
; #define BAR __builtin_amdgcn_s_barrier()
; __device__ __forceinline__ void gemm_phase(const bf16_t* __restrict__ A, const bf16_t* __restrict__ Bt, bf16_t* __restrict__ C, int M, int N, int K,
;                                            int ldc, const int EPI, char* smem, const int wid_u) {
;     ...
;       for (int ai = 0; ai < 2; ++ai)
; #pragma unroll
;         for (int m = 0; m < 4; ++m) {
;           const size_t row = (size_t)(brow + ai * HALF + wr * 64 + m * 16 + fr);
;           if (EPI == 0) {
; #pragma unroll
;             for (int bj = 0; bj < 2; ++bj) {
;               const f32x4 v0 = acc[ai][bj][m][0], v1 = acc[ai][bj][m][1];
;               uint4 u; u.x = cvt_pk_bf16(v0[0], v0[1]); u.y = cvt_pk_bf16(v0[2], v0[3]); u.z = cvt_pk_bf16(v1[0], v1[1]); u.w = cvt_pk_bf16(v1[2], v1[3]);
;               *(uint4*)(C + row * ldc + bcol + bj * HALF + wc * 32 + fq * 8) = u;
;             }
;           } else {
;             float o[8];
; #pragma unroll
;             for (int n = 0; n < 2; ++n) {
;               const f32x4 a = acc[ai][0][m][n], b = acc[ai][1][m][n];
; #pragma unroll
;               for (int j = 0; j < 4; ++j) o[n * 4 + j] = a[j] * __builtin_amdgcn_rcpf(1.f + __expf(-a[j])) * b[j];
;             }
;             *(uint4*)(C + row * ldc + (bcol >> 1) + wc * 32 + fq * 8) = pack8(o);
;           }
;         }
;     }
;     if (!has_next) break;
; #pragma unroll
;     for (int a = 0; a < 2; ++a)
; #pragma unroll
;       for (int b = 0; b < 2; ++b)
; #pragma unroll
;         for (int m = 0; m < 4; ++m)
; #pragma unroll
;           for (int n = 0; n < 2; ++n) acc[a][b][m][n] = (f32x4){0.f, 0.f, 0.f, 0.f};
;     pm = npm; pn = npn; cA = nA; cB = nB; ++ui;
;   }
;   WAIT_V(0);
;   if (wr == 0) BAR;
;   BAR;
	v_mul_f32_e32 v51, 0xbfb8aa3b, v44
	v_cvt_pk_bf16_f32 v48, v52, v53
	v_exp_f32_e32 v52, v51
	v_mul_f32_e32 v51, 0xbfb8aa3b, v45
	v_exp_f32_e32 v53, v51
	v_cvt_pk_bf16_f32 v49, v54, v55
	v_cvt_pk_bf16_f32 v50, v56, v57
	v_cvt_pk_bf16_f32 v51, v58, v59
	v_add_f32_e32 v52, 1.0, v52
	v_add_f32_e32 v53, 1.0, v53
	v_mad_i64_i32 v[54:55], s[16:17], v66, s38, v[142:143]
	v_rcp_f32_e32 v52, v52
	v_rcp_f32_e32 v53, v53
	global_store_dwordx4 v[54:55], v[48:51], off
	v_pk_mul_f32 v[44:45], v[44:45], v[52:53]
	s_nop 0
	v_mul_f32_e32 v48, 0xbfb8aa3b, v46
	v_mul_f32_e32 v49, 0xbfb8aa3b, v47
	v_exp_f32_e32 v48, v48
	v_exp_f32_e32 v49, v49
	v_pk_mul_f32 v[36:37], v[44:45], v[36:37]
	v_add_u32_e32 v50, 0x90, v149
	v_add_f32_e32 v44, 1.0, v48
	v_add_f32_e32 v45, 1.0, v49
	v_mul_f32_e32 v48, 0xbfb8aa3b, v40
	v_mul_f32_e32 v49, 0xbfb8aa3b, v41
	v_rcp_f32_e32 v44, v44
	v_rcp_f32_e32 v45, v45
	v_exp_f32_e32 v48, v48
	v_exp_f32_e32 v49, v49
	v_pk_mul_f32 v[44:45], v[46:47], v[44:45]
	v_add_f32_e32 v46, 1.0, v48
	v_add_f32_e32 v47, 1.0, v49
	v_mul_f32_e32 v48, 0xbfb8aa3b, v42
	v_mul_f32_e32 v49, 0xbfb8aa3b, v43
	v_exp_f32_e32 v48, v48
	v_exp_f32_e32 v49, v49
	v_rcp_f32_e32 v46, v46
	v_rcp_f32_e32 v47, v47
	v_add_f32_e32 v48, 1.0, v48
	v_add_f32_e32 v49, 1.0, v49
	v_rcp_f32_e32 v48, v48
	v_rcp_f32_e32 v49, v49
	v_pk_mul_f32 v[40:41], v[40:41], v[46:47]
	v_pk_mul_f32 v[38:39], v[44:45], v[38:39]
	v_pk_mul_f32 v[40:41], v[40:41], v[32:33]
	v_pk_mul_f32 v[32:33], v[42:43], v[48:49]
	s_nop 0
	v_pk_mul_f32 v[42:43], v[32:33], v[34:35]
	v_mul_f32_e32 v35, 0xbfb8aa3b, v28
	v_cvt_pk_bf16_f32 v32, v36, v37
	v_exp_f32_e32 v36, v35
	v_mul_f32_e32 v35, 0xbfb8aa3b, v29
	v_exp_f32_e32 v37, v35
	v_cvt_pk_bf16_f32 v33, v38, v39
	v_cvt_pk_bf16_f32 v34, v40, v41
	v_cvt_pk_bf16_f32 v35, v42, v43
	v_add_f32_e32 v36, 1.0, v36
	v_add_f32_e32 v37, 1.0, v37
	v_mad_i64_i32 v[38:39], s[16:17], v50, s38, v[142:143]
	v_rcp_f32_e32 v36, v36
	v_rcp_f32_e32 v37, v37
	global_store_dwordx4 v[38:39], v[32:35], off
	v_pk_mul_f32 v[28:29], v[28:29], v[36:37]
	s_nop 0
	v_mul_f32_e32 v32, 0xbfb8aa3b, v30
	v_mul_f32_e32 v33, 0xbfb8aa3b, v31
	v_exp_f32_e32 v32, v32
	v_exp_f32_e32 v33, v33
	v_pk_mul_f32 v[20:21], v[28:29], v[20:21]
	v_add_u32_e32 v34, 0xa0, v149
	v_add_f32_e32 v28, 1.0, v32
	v_add_f32_e32 v29, 1.0, v33
	v_mul_f32_e32 v32, 0xbfb8aa3b, v24
	v_mul_f32_e32 v33, 0xbfb8aa3b, v25
	v_rcp_f32_e32 v28, v28
	v_rcp_f32_e32 v29, v29
	v_exp_f32_e32 v32, v32
	v_exp_f32_e32 v33, v33
	v_pk_mul_f32 v[28:29], v[30:31], v[28:29]
	v_add_f32_e32 v30, 1.0, v32
	v_add_f32_e32 v31, 1.0, v33
	v_mul_f32_e32 v32, 0xbfb8aa3b, v26
	v_mul_f32_e32 v33, 0xbfb8aa3b, v27
	v_exp_f32_e32 v32, v32
	v_exp_f32_e32 v33, v33
	v_rcp_f32_e32 v30, v30
	v_rcp_f32_e32 v31, v31
	v_add_f32_e32 v32, 1.0, v32
	v_add_f32_e32 v33, 1.0, v33
	v_rcp_f32_e32 v32, v32
	v_rcp_f32_e32 v33, v33
	v_pk_mul_f32 v[24:25], v[24:25], v[30:31]
	v_pk_mul_f32 v[22:23], v[28:29], v[22:23]
	v_pk_mul_f32 v[24:25], v[24:25], v[16:17]
	v_pk_mul_f32 v[16:17], v[26:27], v[32:33]
	s_nop 0
	v_pk_mul_f32 v[26:27], v[16:17], v[18:19]
	v_mul_f32_e32 v19, 0xbfb8aa3b, v12
	v_cvt_pk_bf16_f32 v16, v20, v21
	v_exp_f32_e32 v20, v19
	v_mul_f32_e32 v19, 0xbfb8aa3b, v13
	v_exp_f32_e32 v21, v19
	v_cvt_pk_bf16_f32 v17, v22, v23
	v_cvt_pk_bf16_f32 v18, v24, v25
	v_cvt_pk_bf16_f32 v19, v26, v27
	v_add_f32_e32 v20, 1.0, v20
	v_add_f32_e32 v21, 1.0, v21
	v_mad_i64_i32 v[22:23], s[16:17], v34, s38, v[142:143]
	v_rcp_f32_e32 v20, v20
	v_rcp_f32_e32 v21, v21
	global_store_dwordx4 v[22:23], v[16:19], off
	v_pk_mul_f32 v[12:13], v[12:13], v[20:21]
	s_nop 0
	v_mul_f32_e32 v16, 0xbfb8aa3b, v14
	v_mul_f32_e32 v17, 0xbfb8aa3b, v15
	v_exp_f32_e32 v16, v16
	v_exp_f32_e32 v17, v17
	v_pk_mul_f32 v[4:5], v[12:13], v[4:5]
	v_add_u32_e32 v18, 0xb0, v149
	v_add_f32_e32 v12, 1.0, v16
	v_add_f32_e32 v13, 1.0, v17
	v_mul_f32_e32 v16, 0xbfb8aa3b, v8
	v_mul_f32_e32 v17, 0xbfb8aa3b, v9
	v_rcp_f32_e32 v12, v12
	v_rcp_f32_e32 v13, v13
	v_exp_f32_e32 v16, v16
	v_exp_f32_e32 v17, v17
	v_pk_mul_f32 v[12:13], v[14:15], v[12:13]
	v_add_f32_e32 v14, 1.0, v16
	v_add_f32_e32 v15, 1.0, v17
	v_mul_f32_e32 v16, 0xbfb8aa3b, v10
	v_mul_f32_e32 v17, 0xbfb8aa3b, v11
	v_exp_f32_e32 v16, v16
	v_exp_f32_e32 v17, v17
	v_rcp_f32_e32 v14, v14
	v_rcp_f32_e32 v15, v15
	v_add_f32_e32 v16, 1.0, v16
	v_add_f32_e32 v17, 1.0, v17
	v_rcp_f32_e32 v16, v16
	v_rcp_f32_e32 v17, v17
	v_pk_mul_f32 v[8:9], v[8:9], v[14:15]
	v_pk_mul_f32 v[6:7], v[12:13], v[6:7]
	v_pk_mul_f32 v[8:9], v[8:9], v[0:1]
	v_pk_mul_f32 v[0:1], v[10:11], v[16:17]
	s_nop 0
	v_pk_mul_f32 v[10:11], v[0:1], v[2:3]
	v_cvt_pk_bf16_f32 v0, v4, v5
	v_mad_i64_i32 v[4:5], s[16:17], v18, s38, v[142:143]
	v_cvt_pk_bf16_f32 v1, v6, v7
	v_cvt_pk_bf16_f32 v2, v8, v9
	v_cvt_pk_bf16_f32 v3, v10, v11
	s_mov_b64 s[16:17], s[12:13]
	global_store_dwordx4 v[4:5], v[0:3], off
	s_cbranch_vccz .LBB0_142
	s_waitcnt vmcnt(0)
	s_cmpk_gt_u32 s24, 0xff
	s_cbranch_scc1 .LBB0_149
	s_barrier

; #define STG(P, GB) do { const char* _gb = (GB); \
;     _Pragma("unroll") for (int _i = 0; _i < 2; ++_i) { \
;       __builtin_amdgcn_global_load_lds((const unsigned*)(_gb + voff[_i]), \
;         (LAS unsigned*)((LAS char*)(P) + ldsw + _i * 8192), 16, 0, 0); } } while (0)
; #define LDA(dst, b, h) _Pragma("unroll") for (int m = 0; m < 4; ++m) _Pragma("unroll") for (int k = 0; k < 2; ++k) \
;     dst[m][k] = *(const LAS bf16x8*)((LAS char*)SA(b, h) + aoff + m * 2048 + k * 1024)
; #define LDB(dst, b, h) _Pragma("unroll") for (int n = 0; n < 2; ++n) _Pragma("unroll") for (int k = 0; k < 2; ++k) \
;     dst[n][k] = *(const LAS bf16x8*)((LAS char*)SB(b, h) + boff + n * 2048 + k * 1024)
; #define MMA(ai, bj, At_, Bt_) do { __builtin_amdgcn_s_setprio(1); \
;     _Pragma("unroll") for (int m = 0; m < 4; ++m) _Pragma("unroll") for (int n = 0; n < 2; ++n) _Pragma("unroll") for (int k = 0; k < 2; ++k) \
;       acc[ai][bj][m][n] = __builtin_amdgcn_mfma_f32_16x16x32_bf16(Bt_[n][k], At_[m][k], acc[ai][bj][m][n], 0, 0, 0); \
;     __builtin_amdgcn_s_setprio(0); } while (0)
; #define WAIT_V(n) asm volatile("s_waitcnt vmcnt(" #n ")" ::: "memory")
; #define WAIT_L(n) asm volatile("s_waitcnt lgkmcnt(" #n ")" ::: "memory")
; #define BAR __builtin_amdgcn_s_barrier()
; #define SCHED __builtin_amdgcn_sched_barrier(0)
; __device__ __forceinline__ void gemm_phase(const bf16_t* __restrict__ A, const bf16_t* __restrict__ Bt, bf16_t* __restrict__ C, int M, int N, int K,
;                                            int ldc, const int EPI, char* smem, const int wid_u) {
;     ...
;     for (int t = 0; t < nt; t += 2) {
;       const bool last = (t == nt - 2);
;       const char* a1 = cA + (size_t)(t + 1) * kstep;
;       const char* a2 = last ? nA : cA + (size_t)(t + 2) * kstep;
;       const char* b2 = last ? nB : cB + (size_t)(t + 2) * kstep;
;       const char* a3 = a2 + kstep;
;       const char* b3 = b2 + kstep;
;       LDB(B0, 0, 0); SCHED; LDA(At, 0, 0); STG(SA(1, 1), a1 + hstep);
;       WAIT_L(8); BAR; WAIT_L(0); MMA(0, 0, At, B0); BAR; SCHED;
;       LDB(B1, 0, 1); STG(SB(0, 0), b2);
;       BAR; WAIT_L(0); MMA(0, 1, At, B1); BAR;
;       LDA(At, 0, 1); STG(SA(0, 0), a2);
;       BAR; WAIT_L(0); MMA(1, 0, At, B0); BAR; SCHED;
;       STG(SB(0, 1), b2 + hstep);
;       WAIT_V(6); BAR; MMA(1, 1, At, B1); BAR;
.LBB0_213:
	ds_read_b128 v[148:151], v143
	ds_read_b128 v[152:155], v143 offset:1024
	ds_read_b128 v[156:159], v143 offset:2048
	ds_read_b128 v[160:163], v143 offset:3072
	s_add_u32 s16, s14, 0x100
	s_addc_u32 s17, s15, 0
	s_cmp_eq_u32 s53, 40
	s_cselect_b32 s21, s5, s17
	s_cselect_b32 s20, s4, s16
	s_cselect_b32 s19, s7, s52
	s_cselect_b32 s18, s6, s51
	s_mov_b32 m0, s36
	v_lshl_add_u64 v[196:197], s[14:15], 0, v[136:137]
	ds_read_b128 v[164:167], v144
	ds_read_b128 v[168:171], v144 offset:1024
	ds_read_b128 v[172:175], v144 offset:2048
	ds_read_b128 v[176:179], v144 offset:3072
	ds_read_b128 v[180:183], v144 offset:4096
	ds_read_b128 v[184:187], v144 offset:5120
	ds_read_b128 v[188:191], v144 offset:6144
	ds_read_b128 v[192:195], v144 offset:7168
	global_load_lds_dwordx4 v[196:197], off
	v_lshl_add_u64 v[196:197], s[14:15], 0, v[134:135]
	s_mov_b32 m0, s37
	s_nop 0
	global_load_lds_dwordx4 v[196:197], off
	s_waitcnt lgkmcnt(8)
	s_barrier
	s_waitcnt lgkmcnt(0)
	v_mfma_f32_16x16x32_bf16 v[124:127], v[148:151], v[164:167], v[124:127]
	v_mfma_f32_16x16x32_bf16 v[120:123], v[156:159], v[164:167], v[120:123]
	v_mfma_f32_16x16x32_bf16 v[116:119], v[148:151], v[172:175], v[116:119]
	v_mfma_f32_16x16x32_bf16 v[112:115], v[156:159], v[172:175], v[112:115]
	v_mfma_f32_16x16x32_bf16 v[100:103], v[148:151], v[180:183], v[100:103]
	v_mfma_f32_16x16x32_bf16 v[96:99], v[156:159], v[180:183], v[96:99]
	v_mfma_f32_16x16x32_bf16 v[84:87], v[148:151], v[188:191], v[84:87]
	v_mfma_f32_16x16x32_bf16 v[80:83], v[156:159], v[188:191], v[80:83]
	v_mfma_f32_16x16x32_bf16 v[124:127], v[152:155], v[168:171], v[124:127]
	v_mfma_f32_16x16x32_bf16 v[120:123], v[160:163], v[168:171], v[120:123]
	v_mfma_f32_16x16x32_bf16 v[116:119], v[152:155], v[176:179], v[116:119]
	v_mfma_f32_16x16x32_bf16 v[112:115], v[160:163], v[176:179], v[112:115]
	v_mfma_f32_16x16x32_bf16 v[100:103], v[152:155], v[184:187], v[100:103]
	v_mfma_f32_16x16x32_bf16 v[96:99], v[160:163], v[184:187], v[96:99]
	v_mfma_f32_16x16x32_bf16 v[84:87], v[152:155], v[192:195], v[84:87]
	v_mfma_f32_16x16x32_bf16 v[80:83], v[160:163], v[192:195], v[80:83]
	s_barrier
	s_mov_b32 m0, s38
	v_lshl_add_u64 v[212:213], s[18:19], 0, v[130:131]
	ds_read_b128 v[196:199], v145
	ds_read_b128 v[200:203], v145 offset:1024
	ds_read_b128 v[204:207], v145 offset:2048
	ds_read_b128 v[208:211], v145 offset:3072
	global_load_lds_dwordx4 v[212:213], off
	v_lshl_add_u64 v[214:215], s[18:19], 0, v[128:129]
	s_mov_b32 m0, s39
	s_nop 0
	global_load_lds_dwordx4 v[214:215], off
	s_barrier
	s_waitcnt lgkmcnt(0)
	v_mfma_f32_16x16x32_bf16 v[108:111], v[196:199], v[164:167], v[108:111]
	v_mfma_f32_16x16x32_bf16 v[104:107], v[204:207], v[164:167], v[104:107]
	v_mfma_f32_16x16x32_bf16 v[92:95], v[196:199], v[172:175], v[92:95]
	v_mfma_f32_16x16x32_bf16 v[88:91], v[204:207], v[172:175], v[88:91]
	v_mfma_f32_16x16x32_bf16 v[76:79], v[196:199], v[180:183], v[76:79]
	v_mfma_f32_16x16x32_bf16 v[72:75], v[204:207], v[180:183], v[72:75]
	v_mfma_f32_16x16x32_bf16 v[68:71], v[196:199], v[188:191], v[68:71]
	v_mfma_f32_16x16x32_bf16 v[64:67], v[204:207], v[188:191], v[64:67]
	v_mfma_f32_16x16x32_bf16 v[108:111], v[200:203], v[168:171], v[108:111]
	v_mfma_f32_16x16x32_bf16 v[104:107], v[208:211], v[168:171], v[104:107]
	v_mfma_f32_16x16x32_bf16 v[92:95], v[200:203], v[176:179], v[92:95]
	v_mfma_f32_16x16x32_bf16 v[88:91], v[208:211], v[176:179], v[88:91]
	v_mfma_f32_16x16x32_bf16 v[76:79], v[200:203], v[184:187], v[76:79]
	v_mfma_f32_16x16x32_bf16 v[72:75], v[208:211], v[184:187], v[72:75]
	s_mov_b32 m0, s28
	v_lshl_add_u64 v[216:217], s[20:21], 0, v[130:131]
	v_mfma_f32_16x16x32_bf16 v[68:71], v[200:203], v[192:195], v[68:71]
	v_mfma_f32_16x16x32_bf16 v[64:67], v[208:211], v[192:195], v[64:67]
	s_barrier
	ds_read_b128 v[164:167], v144 offset:16384
	ds_read_b128 v[168:171], v144 offset:17408
	ds_read_b128 v[172:175], v144 offset:18432
	ds_read_b128 v[176:179], v144 offset:19456
	ds_read_b128 v[180:183], v144 offset:20480
	ds_read_b128 v[184:187], v144 offset:21504
	ds_read_b128 v[188:191], v144 offset:22528
	ds_read_b128 v[192:195], v144 offset:23552
	global_load_lds_dwordx4 v[216:217], off
	v_lshl_add_u64 v[218:219], s[20:21], 0, v[128:129]
	s_mov_b32 m0, s29
	s_nop 0
	global_load_lds_dwordx4 v[218:219], off
	s_barrier
	s_waitcnt lgkmcnt(0)
	v_mfma_f32_16x16x32_bf16 v[60:63], v[148:151], v[164:167], v[60:63]
	v_mfma_f32_16x16x32_bf16 v[56:59], v[156:159], v[164:167], v[56:59]
	v_mfma_f32_16x16x32_bf16 v[52:55], v[148:151], v[172:175], v[52:55]
	v_mfma_f32_16x16x32_bf16 v[48:51], v[156:159], v[172:175], v[48:51]
	v_mfma_f32_16x16x32_bf16 v[36:39], v[148:151], v[180:183], v[36:39]
	v_mfma_f32_16x16x32_bf16 v[32:35], v[156:159], v[180:183], v[32:35]
	v_mfma_f32_16x16x32_bf16 v[20:23], v[148:151], v[188:191], v[20:23]
	v_mfma_f32_16x16x32_bf16 v[16:19], v[156:159], v[188:191], v[16:19]
	v_mfma_f32_16x16x32_bf16 v[60:63], v[152:155], v[168:171], v[60:63]
	v_mfma_f32_16x16x32_bf16 v[56:59], v[160:163], v[168:171], v[56:59]
	v_mfma_f32_16x16x32_bf16 v[52:55], v[152:155], v[176:179], v[52:55]
	v_mfma_f32_16x16x32_bf16 v[48:51], v[160:163], v[176:179], v[48:51]
	v_mfma_f32_16x16x32_bf16 v[36:39], v[152:155], v[184:187], v[36:39]
	v_mfma_f32_16x16x32_bf16 v[32:35], v[160:163], v[184:187], v[32:35]
	v_mfma_f32_16x16x32_bf16 v[20:23], v[152:155], v[192:195], v[20:23]
	v_mfma_f32_16x16x32_bf16 v[16:19], v[160:163], v[192:195], v[16:19]
	s_barrier
	s_add_u32 s14, s18, 0xb0000
	s_addc_u32 s15, s19, 0
	s_mov_b32 m0, s40
	v_lshl_add_u64 v[148:149], s[14:15], 0, v[130:131]
	global_load_lds_dwordx4 v[148:149], off
	v_lshl_add_u64 v[148:149], s[14:15], 0, v[128:129]
	s_mov_b32 m0, s41
	s_nop 0
	global_load_lds_dwordx4 v[148:149], off
	s_waitcnt vmcnt(6)
	s_barrier
; #define STG(P, GB) do { const char* _gb = (GB); \
;     _Pragma("unroll") for (int _i = 0; _i < 2; ++_i) { \
;       __builtin_amdgcn_global_load_lds((const unsigned*)(_gb + voff[_i]), \
;         (LAS unsigned*)((LAS char*)(P) + ldsw + _i * 8192), 16, 0, 0); } } while (0)
; #define LDA(dst, b, h) _Pragma("unroll") for (int m = 0; m < 4; ++m) _Pragma("unroll") for (int k = 0; k < 2; ++k) \
;     dst[m][k] = *(const LAS bf16x8*)((LAS char*)SA(b, h) + aoff + m * 2048 + k * 1024)
; #define LDB(dst, b, h) _Pragma("unroll") for (int n = 0; n < 2; ++n) _Pragma("unroll") for (int k = 0; k < 2; ++k) \
;     dst[n][k] = *(const LAS bf16x8*)((LAS char*)SB(b, h) + boff + n * 2048 + k * 1024)
; #define MMA(ai, bj, At_, Bt_) do { __builtin_amdgcn_s_setprio(1); \
;     _Pragma("unroll") for (int m = 0; m < 4; ++m) _Pragma("unroll") for (int n = 0; n < 2; ++n) _Pragma("unroll") for (int k = 0; k < 2; ++k) \
;       acc[ai][bj][m][n] = __builtin_amdgcn_mfma_f32_16x16x32_bf16(Bt_[n][k], At_[m][k], acc[ai][bj][m][n], 0, 0, 0); \
;     __builtin_amdgcn_s_setprio(0); } while (0)
; #define WAIT_V(n) asm volatile("s_waitcnt vmcnt(" #n ")" ::: "memory")
; #define WAIT_L(n) asm volatile("s_waitcnt lgkmcnt(" #n ")" ::: "memory")
; #define BAR __builtin_amdgcn_s_barrier()
; #define SCHED __builtin_amdgcn_sched_barrier(0)
; __device__ __forceinline__ void gemm_phase(const bf16_t* __restrict__ A, const bf16_t* __restrict__ Bt, bf16_t* __restrict__ C, int M, int N, int K,
;                                            int ldc, const int EPI, char* smem, const int wid_u) {
;     ...
;       WAIT_V(6); BAR; MMA(1, 1, At, B1); BAR;
;       LDB(B0, 1, 0); SCHED; LDA(At, 1, 0); STG(SA(0, 1), a2 + hstep);
;       WAIT_L(8); BAR; WAIT_L(0); MMA(0, 0, At, B0); BAR; SCHED;
;       LDB(B1, 1, 1); STG(SB(1, 0), b3);
;       BAR; WAIT_L(0); MMA(0, 1, At, B1); BAR;
;       LDA(At, 1, 1); STG(SA(1, 0), a3);
	v_mfma_f32_16x16x32_bf16 v[44:47], v[196:199], v[164:167], v[44:47]
	v_mfma_f32_16x16x32_bf16 v[40:43], v[204:207], v[164:167], v[40:43]
	v_mfma_f32_16x16x32_bf16 v[28:31], v[196:199], v[172:175], v[28:31]
	v_mfma_f32_16x16x32_bf16 v[24:27], v[204:207], v[172:175], v[24:27]
	v_mfma_f32_16x16x32_bf16 v[12:15], v[196:199], v[180:183], v[12:15]
	v_mfma_f32_16x16x32_bf16 v[8:11], v[204:207], v[180:183], v[8:11]
	v_mfma_f32_16x16x32_bf16 v[4:7], v[196:199], v[188:191], v[4:7]
	v_mfma_f32_16x16x32_bf16 v[0:3], v[204:207], v[188:191], v[0:3]
	v_mfma_f32_16x16x32_bf16 v[44:47], v[200:203], v[168:171], v[44:47]
	v_mfma_f32_16x16x32_bf16 v[40:43], v[208:211], v[168:171], v[40:43]
	v_mfma_f32_16x16x32_bf16 v[28:31], v[200:203], v[176:179], v[28:31]
	v_mfma_f32_16x16x32_bf16 v[24:27], v[208:211], v[176:179], v[24:27]
	v_mfma_f32_16x16x32_bf16 v[12:15], v[200:203], v[184:187], v[12:15]
	v_mfma_f32_16x16x32_bf16 v[8:11], v[208:211], v[184:187], v[8:11]
	v_mfma_f32_16x16x32_bf16 v[4:7], v[200:203], v[192:195], v[4:7]
	v_mfma_f32_16x16x32_bf16 v[0:3], v[208:211], v[192:195], v[0:3]
	s_barrier
	ds_read_b128 v[148:151], v146
	ds_read_b128 v[152:155], v146 offset:1024
	ds_read_b128 v[156:159], v146 offset:2048
	ds_read_b128 v[160:163], v146 offset:3072
	s_add_u32 s14, s20, 0xb0000
	s_addc_u32 s15, s21, 0
	s_mov_b32 m0, s30
	v_lshl_add_u64 v[196:197], s[14:15], 0, v[130:131]
	ds_read_b128 v[164:167], v144 offset:32768
	ds_read_b128 v[168:171], v144 offset:33792
	ds_read_b128 v[172:175], v144 offset:34816
	ds_read_b128 v[176:179], v144 offset:35840
	ds_read_b128 v[180:183], v144 offset:36864
	ds_read_b128 v[184:187], v144 offset:37888
	ds_read_b128 v[188:191], v144 offset:38912
	ds_read_b128 v[192:195], v144 offset:39936
	global_load_lds_dwordx4 v[196:197], off
	v_lshl_add_u64 v[196:197], s[14:15], 0, v[128:129]
	s_mov_b32 m0, s31
	s_nop 0
	global_load_lds_dwordx4 v[196:197], off
	s_waitcnt lgkmcnt(8)
	s_barrier
	s_waitcnt lgkmcnt(0)
	v_mfma_f32_16x16x32_bf16 v[124:127], v[148:151], v[164:167], v[124:127]
	v_mfma_f32_16x16x32_bf16 v[120:123], v[156:159], v[164:167], v[120:123]
	v_mfma_f32_16x16x32_bf16 v[116:119], v[148:151], v[172:175], v[116:119]
	v_mfma_f32_16x16x32_bf16 v[112:115], v[156:159], v[172:175], v[112:115]
	v_mfma_f32_16x16x32_bf16 v[100:103], v[148:151], v[180:183], v[100:103]
	v_mfma_f32_16x16x32_bf16 v[96:99], v[156:159], v[180:183], v[96:99]
	v_mfma_f32_16x16x32_bf16 v[84:87], v[148:151], v[188:191], v[84:87]
	v_mfma_f32_16x16x32_bf16 v[80:83], v[156:159], v[188:191], v[80:83]
	v_mfma_f32_16x16x32_bf16 v[124:127], v[152:155], v[168:171], v[124:127]
	v_mfma_f32_16x16x32_bf16 v[120:123], v[160:163], v[168:171], v[120:123]
	v_mfma_f32_16x16x32_bf16 v[116:119], v[152:155], v[176:179], v[116:119]
	v_mfma_f32_16x16x32_bf16 v[112:115], v[160:163], v[176:179], v[112:115]
	v_mfma_f32_16x16x32_bf16 v[100:103], v[152:155], v[184:187], v[100:103]
	v_mfma_f32_16x16x32_bf16 v[96:99], v[160:163], v[184:187], v[96:99]
	v_mfma_f32_16x16x32_bf16 v[84:87], v[152:155], v[192:195], v[84:87]
	v_mfma_f32_16x16x32_bf16 v[80:83], v[160:163], v[192:195], v[80:83]
	s_barrier
	s_mov_b32 m0, s45
	v_lshl_add_u64 v[212:213], v[212:213], 0, s[12:13]
	ds_read_b128 v[196:199], v147
	ds_read_b128 v[200:203], v147 offset:1024
	ds_read_b128 v[204:207], v147 offset:2048
	ds_read_b128 v[208:211], v147 offset:3072
	global_load_lds_dwordx4 v[212:213], off
	v_lshl_add_u64 v[212:213], v[214:215], 0, s[12:13]
	s_mov_b32 m0, s46
	s_nop 0
	global_load_lds_dwordx4 v[212:213], off
	s_barrier
	s_waitcnt lgkmcnt(0)
	v_mfma_f32_16x16x32_bf16 v[108:111], v[196:199], v[164:167], v[108:111]
	v_mfma_f32_16x16x32_bf16 v[104:107], v[204:207], v[164:167], v[104:107]
	v_mfma_f32_16x16x32_bf16 v[92:95], v[196:199], v[172:175], v[92:95]
	v_mfma_f32_16x16x32_bf16 v[88:91], v[204:207], v[172:175], v[88:91]
	v_mfma_f32_16x16x32_bf16 v[76:79], v[196:199], v[180:183], v[76:79]
	v_mfma_f32_16x16x32_bf16 v[72:75], v[204:207], v[180:183], v[72:75]
	v_mfma_f32_16x16x32_bf16 v[68:71], v[196:199], v[188:191], v[68:71]
	v_mfma_f32_16x16x32_bf16 v[64:67], v[204:207], v[188:191], v[64:67]
	v_mfma_f32_16x16x32_bf16 v[108:111], v[200:203], v[168:171], v[108:111]
	v_mfma_f32_16x16x32_bf16 v[104:107], v[208:211], v[168:171], v[104:107]
	v_mfma_f32_16x16x32_bf16 v[92:95], v[200:203], v[176:179], v[92:95]
	v_mfma_f32_16x16x32_bf16 v[88:91], v[208:211], v[176:179], v[88:91]
	v_mfma_f32_16x16x32_bf16 v[76:79], v[200:203], v[184:187], v[76:79]
	v_mfma_f32_16x16x32_bf16 v[72:75], v[208:211], v[184:187], v[72:75]
	s_mov_b32 m0, s34
	v_lshl_add_u64 v[212:213], v[216:217], 0, s[12:13]
	v_mfma_f32_16x16x32_bf16 v[68:71], v[200:203], v[192:195], v[68:71]
	v_mfma_f32_16x16x32_bf16 v[64:67], v[208:211], v[192:195], v[64:67]
	s_barrier
	ds_read_b128 v[164:167], v144 offset:49152
	ds_read_b128 v[168:171], v144 offset:50176
	ds_read_b128 v[172:175], v144 offset:51200
	ds_read_b128 v[176:179], v144 offset:52224
	ds_read_b128 v[180:183], v144 offset:53248
	ds_read_b128 v[184:187], v144 offset:54272
	ds_read_b128 v[188:191], v144 offset:55296
	ds_read_b128 v[192:195], v144 offset:56320
	global_load_lds_dwordx4 v[212:213], off
	v_lshl_add_u64 v[212:213], v[218:219], 0, s[12:13]
	s_mov_b32 m0, s35
	s_nop 0
	global_load_lds_dwordx4 v[212:213], off
	s_barrier
; #define STG(P, GB) do { const char* _gb = (GB); \
;     _Pragma("unroll") for (int _i = 0; _i < 2; ++_i) { \
;       __builtin_amdgcn_global_load_lds((const unsigned*)(_gb + voff[_i]), \
;         (LAS unsigned*)((LAS char*)(P) + ldsw + _i * 8192), 16, 0, 0); } } while (0)
; #define MMA(ai, bj, At_, Bt_) do { __builtin_amdgcn_s_setprio(1); \
;     _Pragma("unroll") for (int m = 0; m < 4; ++m) _Pragma("unroll") for (int n = 0; n < 2; ++n) _Pragma("unroll") for (int k = 0; k < 2; ++k) \
;       acc[ai][bj][m][n] = __builtin_amdgcn_mfma_f32_16x16x32_bf16(Bt_[n][k], At_[m][k], acc[ai][bj][m][n], 0, 0, 0); \
;     __builtin_amdgcn_s_setprio(0); } while (0)
; #define WAIT_V(n) asm volatile("s_waitcnt vmcnt(" #n ")" ::: "memory")
; #define WAIT_L(n) asm volatile("s_waitcnt lgkmcnt(" #n ")" ::: "memory")
; #define BAR __builtin_amdgcn_s_barrier()
; #define SCHED __builtin_amdgcn_sched_barrier(0)
; __device__ __forceinline__ void gemm_phase(const bf16_t* __restrict__ A, const bf16_t* __restrict__ Bt, bf16_t* __restrict__ C, int M, int N, int K,
;                                            int ldc, const int EPI, char* smem, const int wid_u) {
;     ...
;       BAR; WAIT_L(0); MMA(1, 0, At, B0); BAR; SCHED;
;       STG(SB(1, 1), b3 + hstep);
;       WAIT_V(6); BAR; MMA(1, 1, At, B1); BAR;
;     }
	s_waitcnt lgkmcnt(0)
	v_mfma_f32_16x16x32_bf16 v[60:63], v[148:151], v[164:167], v[60:63]
	v_mfma_f32_16x16x32_bf16 v[56:59], v[156:159], v[164:167], v[56:59]
	v_mfma_f32_16x16x32_bf16 v[52:55], v[148:151], v[172:175], v[52:55]
	v_mfma_f32_16x16x32_bf16 v[48:51], v[156:159], v[172:175], v[48:51]
	v_mfma_f32_16x16x32_bf16 v[36:39], v[148:151], v[180:183], v[36:39]
	v_mfma_f32_16x16x32_bf16 v[32:35], v[156:159], v[180:183], v[32:35]
	v_mfma_f32_16x16x32_bf16 v[20:23], v[148:151], v[188:191], v[20:23]
	v_mfma_f32_16x16x32_bf16 v[16:19], v[156:159], v[188:191], v[16:19]
	v_mfma_f32_16x16x32_bf16 v[60:63], v[152:155], v[168:171], v[60:63]
	v_mfma_f32_16x16x32_bf16 v[56:59], v[160:163], v[168:171], v[56:59]
	v_mfma_f32_16x16x32_bf16 v[52:55], v[152:155], v[176:179], v[52:55]
	v_mfma_f32_16x16x32_bf16 v[48:51], v[160:163], v[176:179], v[48:51]
	v_mfma_f32_16x16x32_bf16 v[36:39], v[152:155], v[184:187], v[36:39]
	v_mfma_f32_16x16x32_bf16 v[32:35], v[160:163], v[184:187], v[32:35]
	v_mfma_f32_16x16x32_bf16 v[20:23], v[152:155], v[192:195], v[20:23]
	v_mfma_f32_16x16x32_bf16 v[16:19], v[160:163], v[192:195], v[16:19]
	s_barrier
	s_add_u32 s14, s18, 0xb0080
	s_addc_u32 s15, s19, 0
	s_add_i32 s18, s44, s27
	v_lshl_add_u64 v[148:149], s[14:15], 0, v[130:131]
	s_mov_b32 m0, s18
	s_nop 0
	global_load_lds_dwordx4 v[148:149], off
	v_lshl_add_u64 v[148:149], s[14:15], 0, v[128:129]
	s_add_i32 m0, s18, 0x2000
	s_nop 0
	global_load_lds_dwordx4 v[148:149], off
	s_waitcnt vmcnt(6)
	s_barrier
	v_mfma_f32_16x16x32_bf16 v[44:47], v[196:199], v[164:167], v[44:47]
	v_mfma_f32_16x16x32_bf16 v[40:43], v[204:207], v[164:167], v[40:43]
	v_mfma_f32_16x16x32_bf16 v[28:31], v[196:199], v[172:175], v[28:31]
	v_mfma_f32_16x16x32_bf16 v[24:27], v[204:207], v[172:175], v[24:27]
	v_mfma_f32_16x16x32_bf16 v[12:15], v[196:199], v[180:183], v[12:15]
	v_mfma_f32_16x16x32_bf16 v[8:11], v[204:207], v[180:183], v[8:11]
	v_mfma_f32_16x16x32_bf16 v[4:7], v[196:199], v[188:191], v[4:7]
	v_mfma_f32_16x16x32_bf16 v[0:3], v[204:207], v[188:191], v[0:3]
	v_mfma_f32_16x16x32_bf16 v[44:47], v[200:203], v[168:171], v[44:47]
	v_mfma_f32_16x16x32_bf16 v[40:43], v[208:211], v[168:171], v[40:43]
	v_mfma_f32_16x16x32_bf16 v[28:31], v[200:203], v[176:179], v[28:31]
	v_mfma_f32_16x16x32_bf16 v[24:27], v[208:211], v[176:179], v[24:27]
	v_mfma_f32_16x16x32_bf16 v[12:15], v[200:203], v[184:187], v[12:15]
	v_mfma_f32_16x16x32_bf16 v[8:11], v[208:211], v[184:187], v[8:11]
	s_add_i32 s53, s53, 2
	s_add_u32 s51, s51, 0x100
	s_addc_u32 s52, s52, 0
	s_cmp_gt_u32 s53, 41
	s_mov_b64 s[14:15], s[16:17]
	v_mfma_f32_16x16x32_bf16 v[4:7], v[200:203], v[192:195], v[4:7]
	v_mfma_f32_16x16x32_bf16 v[0:3], v[208:211], v[192:195], v[0:3]
	s_barrier
	s_cbranch_scc0 .LBB0_213
; #define WAIT_V(n) asm volatile("s_waitcnt vmcnt(" #n ")" ::: "memory")
; #define BAR __builtin_amdgcn_s_barrier()
; __device__ __forceinline__ void gemm_phase(const bf16_t* __restrict__ A, const bf16_t* __restrict__ Bt, bf16_t* __restrict__ C, int M, int N, int K,
;                                            int ldc, const int EPI, char* smem, const int wid_u) {
;     ...
;       const int brow = pm * BM, bcol = pn * BM;
; #pragma unroll
;       for (int ai = 0; ai < 2; ++ai)
; #pragma unroll
;         for (int m = 0; m < 4; ++m) {
;           const size_t row = (size_t)(brow + ai * HALF + wr * 64 + m * 16 + fr);
;           if (EPI == 0) {
; #pragma unroll
;             for (int bj = 0; bj < 2; ++bj) {
;               const f32x4 v0 = acc[ai][bj][m][0], v1 = acc[ai][bj][m][1];
;               uint4 u; u.x = cvt_pk_bf16(v0[0], v0[1]); u.y = cvt_pk_bf16(v0[2], v0[3]); u.z = cvt_pk_bf16(v1[0], v1[1]); u.w = cvt_pk_bf16(v1[2], v1[3]);
;               *(uint4*)(C + row * ldc + bcol + bj * HALF + wc * 32 + fq * 8) = u;
;             }
;           } else {
;             float o[8];
; #pragma unroll
;             for (int n = 0; n < 2; ++n) {
;               const f32x4 a = acc[ai][0][m][n], b = acc[ai][1][m][n];
; #pragma unroll
;               for (int j = 0; j < 4; ++j) o[n * 4 + j] = a[j] * __builtin_amdgcn_rcpf(1.f + __expf(-a[j])) * b[j];
;             }
;             *(uint4*)(C + row * ldc + (bcol >> 1) + wc * 32 + fq * 8) = pack8(o);
;           }
;         }
;     }
;     if (!has_next) break;
; #pragma unroll
;     for (int a = 0; a < 2; ++a)
; #pragma unroll
;       for (int b = 0; b < 2; ++b)
; #pragma unroll
;         for (int m = 0; m < 4; ++m)
; #pragma unroll
;           for (int n = 0; n < 2; ++n) acc[a][b][m][n] = (f32x4){0.f, 0.f, 0.f, 0.f};
;     pm = npm; pn = npn; cA = nA; cB = nB; ++ui;
;   }
;   WAIT_V(0);
;   if (wr == 0) BAR;
;   BAR;
	v_lshl_add_u32 v148, s10, 8, v142
	v_cvt_pk_bf16_f32 v68, v68, v69
	v_cvt_pk_bf16_f32 v69, v70, v71
	v_cvt_pk_bf16_f32 v70, v64, v65
	v_add_u32_e32 v64, 0x80, v148
	s_lshl_b32 s10, s50, 9
	v_ashrrev_i32_e32 v149, 31, v148
	v_cvt_pk_bf16_f32 v108, v108, v109
	v_cvt_pk_bf16_f32 v109, v110, v111
	v_cvt_pk_bf16_f32 v110, v104, v105
	v_or_b32_e32 v104, 16, v148
	v_ashrrev_i32_e32 v65, 31, v64
	v_cvt_pk_bf16_f32 v44, v44, v45
	v_cvt_pk_bf16_f32 v45, v46, v47
	v_cvt_pk_bf16_f32 v46, v40, v41
	v_add_u32_e32 v40, 0x90, v148
	v_lshl_add_u64 v[150:151], v[132:133], 0, s[10:11]
	v_lshlrev_b64 v[152:153], 11, v[148:149]
	v_ashrrev_i32_e32 v105, 31, v104
	v_cvt_pk_bf16_f32 v92, v92, v93
	v_cvt_pk_bf16_f32 v93, v94, v95
	v_cvt_pk_bf16_f32 v94, v88, v89
	v_or_b32_e32 v88, 32, v148
	v_lshlrev_b64 v[64:65], 11, v[64:65]
	v_ashrrev_i32_e32 v41, 31, v40
	v_cvt_pk_bf16_f32 v28, v28, v29
	v_cvt_pk_bf16_f32 v29, v30, v31
	v_cvt_pk_bf16_f32 v30, v24, v25
	v_add_u32_e32 v24, 0xa0, v148
	v_lshl_add_u64 v[152:153], v[150:151], 0, v[152:153]
	v_cvt_pk_bf16_f32 v111, v106, v107
	v_lshlrev_b64 v[104:105], 11, v[104:105]
	v_ashrrev_i32_e32 v89, 31, v88
	v_cvt_pk_bf16_f32 v76, v76, v77
	v_cvt_pk_bf16_f32 v77, v78, v79
	v_cvt_pk_bf16_f32 v78, v72, v73
	v_or_b32_e32 v72, 48, v148
	v_lshl_add_u64 v[64:65], v[150:151], 0, v[64:65]
	v_cvt_pk_bf16_f32 v47, v42, v43
	v_lshlrev_b64 v[40:41], 11, v[40:41]
	v_ashrrev_i32_e32 v25, 31, v24
	v_cvt_pk_bf16_f32 v12, v12, v13
	v_cvt_pk_bf16_f32 v13, v14, v15
	v_cvt_pk_bf16_f32 v14, v8, v9
	v_add_u32_e32 v8, 0xb0, v148
	global_store_dwordx4 v[152:153], v[108:111], off offset:256
	v_cvt_pk_bf16_f32 v95, v90, v91
	v_lshlrev_b64 v[88:89], 11, v[88:89]
	v_lshl_add_u64 v[108:109], v[150:151], 0, v[104:105]
	v_ashrrev_i32_e32 v73, 31, v72
	global_store_dwordx4 v[64:65], v[44:47], off offset:256
	v_cvt_pk_bf16_f32 v31, v26, v27
	v_lshlrev_b64 v[24:25], 11, v[24:25]
	v_lshl_add_u64 v[44:45], v[150:151], 0, v[40:41]
	v_ashrrev_i32_e32 v9, 31, v8
	global_store_dwordx4 v[108:109], v[92:95], off offset:256
	v_cvt_pk_bf16_f32 v79, v74, v75
	v_lshlrev_b64 v[72:73], 11, v[72:73]
	v_lshl_add_u64 v[92:93], v[150:151], 0, v[88:89]
	global_store_dwordx4 v[44:45], v[28:31], off offset:256
	v_cvt_pk_bf16_f32 v15, v10, v11
	v_lshlrev_b64 v[8:9], 11, v[8:9]
	v_lshl_add_u64 v[28:29], v[150:151], 0, v[24:25]
	v_cvt_pk_bf16_f32 v124, v124, v125
	v_cvt_pk_bf16_f32 v125, v126, v127
	v_cvt_pk_bf16_f32 v126, v120, v121
	v_cvt_pk_bf16_f32 v127, v122, v123
	v_cvt_pk_bf16_f32 v104, v116, v117
	v_cvt_pk_bf16_f32 v105, v118, v119
	v_cvt_pk_bf16_f32 v106, v112, v113
	v_cvt_pk_bf16_f32 v107, v114, v115
	v_cvt_pk_bf16_f32 v88, v100, v101
	v_cvt_pk_bf16_f32 v89, v102, v103
	v_cvt_pk_bf16_f32 v90, v96, v97
	v_cvt_pk_bf16_f32 v91, v98, v99
	global_store_dwordx4 v[92:93], v[76:79], off offset:256
	v_cvt_pk_bf16_f32 v74, v80, v81
	v_cvt_pk_bf16_f32 v75, v82, v83
	v_lshl_add_u64 v[76:77], v[150:151], 0, v[72:73]
	v_cvt_pk_bf16_f32 v72, v84, v85
	v_cvt_pk_bf16_f32 v73, v86, v87
	v_cvt_pk_bf16_f32 v71, v66, v67
	v_cvt_pk_bf16_f32 v60, v60, v61
	v_cvt_pk_bf16_f32 v61, v62, v63
	v_cvt_pk_bf16_f32 v62, v56, v57
	v_cvt_pk_bf16_f32 v63, v58, v59
	v_cvt_pk_bf16_f32 v40, v52, v53
	v_cvt_pk_bf16_f32 v41, v54, v55
	v_cvt_pk_bf16_f32 v42, v48, v49
	v_cvt_pk_bf16_f32 v43, v50, v51
	v_cvt_pk_bf16_f32 v24, v36, v37
	v_cvt_pk_bf16_f32 v25, v38, v39
	v_cvt_pk_bf16_f32 v26, v32, v33
	v_cvt_pk_bf16_f32 v27, v34, v35
	global_store_dwordx4 v[28:29], v[12:15], off offset:256
	v_cvt_pk_bf16_f32 v10, v16, v17
	v_cvt_pk_bf16_f32 v11, v18, v19
	v_lshl_add_u64 v[12:13], v[150:151], 0, v[8:9]
	v_cvt_pk_bf16_f32 v8, v20, v21
	v_cvt_pk_bf16_f32 v9, v22, v23
	v_cvt_pk_bf16_f32 v4, v4, v5
	v_cvt_pk_bf16_f32 v5, v6, v7
	v_cvt_pk_bf16_f32 v6, v0, v1
	v_cvt_pk_bf16_f32 v7, v2, v3
	s_and_b64 vcc, exec, s[2:3]
	s_mov_b32 s10, s48
	s_mov_b32 s50, s49
	s_mov_b64 s[16:17], s[6:7]
	s_mov_b64 s[14:15], s[4:5]
	global_store_dwordx4 v[152:153], v[124:127], off
	global_store_dwordx4 v[108:109], v[104:107], off
	global_store_dwordx4 v[92:93], v[88:91], off
	global_store_dwordx4 v[76:77], v[72:75], off
	global_store_dwordx4 v[76:77], v[68:71], off offset:256
	global_store_dwordx4 v[64:65], v[60:63], off
	global_store_dwordx4 v[44:45], v[40:43], off
	global_store_dwordx4 v[28:29], v[24:27], off
	global_store_dwordx4 v[12:13], v[8:11], off
	global_store_dwordx4 v[12:13], v[4:7], off offset:256
	s_cbranch_vccz .LBB0_206
	s_waitcnt vmcnt(0)
	s_cmpk_gt_u32 s22, 0xff
	s_cbranch_scc1 .LBB0_217
	s_barrier

; #define STG(P, GB) do { const char* _gb = (GB); \
;     _Pragma("unroll") for (int _i = 0; _i < 2; ++_i) { \
;       __builtin_amdgcn_global_load_lds((const unsigned*)(_gb + voff[_i]), \
;         (LAS unsigned*)((LAS char*)(P) + ldsw + _i * 8192), 16, 0, 0); } } while (0)
; #define LDA(dst, b, h) _Pragma("unroll") for (int m = 0; m < 4; ++m) _Pragma("unroll") for (int k = 0; k < 2; ++k) \
;     dst[m][k] = *(const LAS bf16x8*)((LAS char*)SA(b, h) + aoff + m * 2048 + k * 1024)
; #define LDB(dst, b, h) _Pragma("unroll") for (int n = 0; n < 2; ++n) _Pragma("unroll") for (int k = 0; k < 2; ++k) \
;     dst[n][k] = *(const LAS bf16x8*)((LAS char*)SB(b, h) + boff + n * 2048 + k * 1024)
; #define MMA(ai, bj, At_, Bt_) do { __builtin_amdgcn_s_setprio(1); \
;     _Pragma("unroll") for (int m = 0; m < 4; ++m) _Pragma("unroll") for (int n = 0; n < 2; ++n) _Pragma("unroll") for (int k = 0; k < 2; ++k) \
;       acc[ai][bj][m][n] = __builtin_amdgcn_mfma_f32_16x16x32_bf16(Bt_[n][k], At_[m][k], acc[ai][bj][m][n], 0, 0, 0); \
;     __builtin_amdgcn_s_setprio(0); } while (0)
; #define WAIT_L(n) asm volatile("s_waitcnt lgkmcnt(" #n ")" ::: "memory")
; #define BAR __builtin_amdgcn_s_barrier()
; #define SCHED __builtin_amdgcn_sched_barrier(0)
; __device__ __forceinline__ void gemm_phase(const bf16_t* __restrict__ A, const bf16_t* __restrict__ Bt, bf16_t* __restrict__ C, int M, int N, int K,
;                                            int ldc, const int EPI, char* smem, const int wid_u) {
;     ...
;     for (int t = 0; t < nt; t += 2) {
;       const bool last = (t == nt - 2);
;       const char* a1 = cA + (size_t)(t + 1) * kstep;
;       const char* a2 = last ? nA : cA + (size_t)(t + 2) * kstep;
;       const char* b2 = last ? nB : cB + (size_t)(t + 2) * kstep;
;       const char* a3 = a2 + kstep;
;       const char* b3 = b2 + kstep;
;       LDB(B0, 0, 0); SCHED; LDA(At, 0, 0); STG(SA(1, 1), a1 + hstep);
;       WAIT_L(8); BAR; WAIT_L(0); MMA(0, 0, At, B0); BAR; SCHED;
;       LDB(B1, 0, 1); STG(SB(0, 0), b2);
;       BAR; WAIT_L(0); MMA(0, 1, At, B1); BAR;
;       LDA(At, 0, 1); STG(SA(0, 0), a2);
;       BAR; WAIT_L(0); MMA(1, 0, At, B0); BAR; SCHED;
.LBB0_334:
	ds_read_b128 v[148:151], v144
	ds_read_b128 v[152:155], v144 offset:1024
	ds_read_b128 v[156:159], v144 offset:2048
	ds_read_b128 v[160:163], v144 offset:3072
	s_add_u32 s18, s16, 0x100
	s_addc_u32 s19, s17, 0
	s_cmp_eq_u32 s51, 12
	s_cselect_b32 s23, s46, s19
	s_cselect_b32 s22, s47, s18
	s_cselect_b32 s21, s11, s50
	s_cselect_b32 s20, s48, s49
	v_lshl_add_u64 v[196:197], s[16:17], 0, v[136:137]
	s_add_i32 m0, s30, 0xc000
	ds_read_b128 v[164:167], v145
	ds_read_b128 v[168:171], v145 offset:1024
	ds_read_b128 v[172:175], v145 offset:2048
	ds_read_b128 v[176:179], v145 offset:3072
	ds_read_b128 v[180:183], v145 offset:4096
	ds_read_b128 v[184:187], v145 offset:5120
	ds_read_b128 v[188:191], v145 offset:6144
	ds_read_b128 v[192:195], v145 offset:7168
	global_load_lds_dwordx4 v[196:197], off
	v_lshl_add_u64 v[196:197], s[16:17], 0, v[134:135]
	s_add_i32 m0, s30, 0xe000
	s_nop 0
	global_load_lds_dwordx4 v[196:197], off
	s_waitcnt lgkmcnt(8)
	s_barrier
	s_waitcnt lgkmcnt(0)
	v_mfma_f32_16x16x32_bf16 v[124:127], v[148:151], v[164:167], v[124:127]
	v_mfma_f32_16x16x32_bf16 v[120:123], v[156:159], v[164:167], v[120:123]
	v_mfma_f32_16x16x32_bf16 v[116:119], v[148:151], v[172:175], v[116:119]
	v_mfma_f32_16x16x32_bf16 v[112:115], v[156:159], v[172:175], v[112:115]
	v_mfma_f32_16x16x32_bf16 v[100:103], v[148:151], v[180:183], v[100:103]
	v_mfma_f32_16x16x32_bf16 v[96:99], v[156:159], v[180:183], v[96:99]
	v_mfma_f32_16x16x32_bf16 v[84:87], v[148:151], v[188:191], v[84:87]
	v_mfma_f32_16x16x32_bf16 v[80:83], v[156:159], v[188:191], v[80:83]
	v_mfma_f32_16x16x32_bf16 v[124:127], v[152:155], v[168:171], v[124:127]
	v_mfma_f32_16x16x32_bf16 v[120:123], v[160:163], v[168:171], v[120:123]
	v_mfma_f32_16x16x32_bf16 v[116:119], v[152:155], v[176:179], v[116:119]
	v_mfma_f32_16x16x32_bf16 v[112:115], v[160:163], v[176:179], v[112:115]
	v_mfma_f32_16x16x32_bf16 v[100:103], v[152:155], v[184:187], v[100:103]
	v_mfma_f32_16x16x32_bf16 v[96:99], v[160:163], v[184:187], v[96:99]
	v_mfma_f32_16x16x32_bf16 v[84:87], v[152:155], v[192:195], v[84:87]
	v_mfma_f32_16x16x32_bf16 v[80:83], v[160:163], v[192:195], v[80:83]
	s_barrier
	s_add_i32 s16, s38, s29
	v_lshl_add_u64 v[212:213], s[20:21], 0, v[130:131]
	s_mov_b32 m0, s16
	ds_read_b128 v[196:199], v146
	ds_read_b128 v[200:203], v146 offset:1024
	ds_read_b128 v[204:207], v146 offset:2048
	ds_read_b128 v[208:211], v146 offset:3072
	global_load_lds_dwordx4 v[212:213], off
	v_lshl_add_u64 v[214:215], s[20:21], 0, v[128:129]
	s_add_i32 m0, s16, 0x2000
	s_nop 0
	global_load_lds_dwordx4 v[214:215], off
	s_barrier
	s_waitcnt lgkmcnt(0)
	v_mfma_f32_16x16x32_bf16 v[108:111], v[196:199], v[164:167], v[108:111]
	v_mfma_f32_16x16x32_bf16 v[104:107], v[204:207], v[164:167], v[104:107]
	v_mfma_f32_16x16x32_bf16 v[92:95], v[196:199], v[172:175], v[92:95]
	v_mfma_f32_16x16x32_bf16 v[88:91], v[204:207], v[172:175], v[88:91]
	v_mfma_f32_16x16x32_bf16 v[76:79], v[196:199], v[180:183], v[76:79]
	v_mfma_f32_16x16x32_bf16 v[72:75], v[204:207], v[180:183], v[72:75]
	v_mfma_f32_16x16x32_bf16 v[68:71], v[196:199], v[188:191], v[68:71]
	v_mfma_f32_16x16x32_bf16 v[64:67], v[204:207], v[188:191], v[64:67]
	v_mfma_f32_16x16x32_bf16 v[108:111], v[200:203], v[168:171], v[108:111]
	v_mfma_f32_16x16x32_bf16 v[104:107], v[208:211], v[168:171], v[104:107]
	v_mfma_f32_16x16x32_bf16 v[92:95], v[200:203], v[176:179], v[92:95]
	v_mfma_f32_16x16x32_bf16 v[88:91], v[208:211], v[176:179], v[88:91]
	v_mfma_f32_16x16x32_bf16 v[76:79], v[200:203], v[184:187], v[76:79]
	v_mfma_f32_16x16x32_bf16 v[72:75], v[208:211], v[184:187], v[72:75]
	s_mov_b32 m0, s30
	v_lshl_add_u64 v[216:217], s[22:23], 0, v[130:131]
	v_mfma_f32_16x16x32_bf16 v[68:71], v[200:203], v[192:195], v[68:71]
	v_mfma_f32_16x16x32_bf16 v[64:67], v[208:211], v[192:195], v[64:67]
	s_barrier
	ds_read_b128 v[164:167], v145 offset:16384
	ds_read_b128 v[168:171], v145 offset:17408
	ds_read_b128 v[172:175], v145 offset:18432
	ds_read_b128 v[176:179], v145 offset:19456
	ds_read_b128 v[180:183], v145 offset:20480
	ds_read_b128 v[184:187], v145 offset:21504
	ds_read_b128 v[188:191], v145 offset:22528
	ds_read_b128 v[192:195], v145 offset:23552
	global_load_lds_dwordx4 v[216:217], off
	v_lshl_add_u64 v[218:219], s[22:23], 0, v[128:129]
	s_mov_b32 m0, s31
	s_nop 0
	global_load_lds_dwordx4 v[218:219], off
	s_barrier
	s_waitcnt lgkmcnt(0)
	v_mfma_f32_16x16x32_bf16 v[60:63], v[148:151], v[164:167], v[60:63]
	v_mfma_f32_16x16x32_bf16 v[56:59], v[156:159], v[164:167], v[56:59]
	v_mfma_f32_16x16x32_bf16 v[52:55], v[148:151], v[172:175], v[52:55]
	v_mfma_f32_16x16x32_bf16 v[48:51], v[156:159], v[172:175], v[48:51]
	v_mfma_f32_16x16x32_bf16 v[36:39], v[148:151], v[180:183], v[36:39]
	v_mfma_f32_16x16x32_bf16 v[32:35], v[156:159], v[180:183], v[32:35]
	v_mfma_f32_16x16x32_bf16 v[20:23], v[148:151], v[188:191], v[20:23]
	v_mfma_f32_16x16x32_bf16 v[16:19], v[156:159], v[188:191], v[16:19]
	v_mfma_f32_16x16x32_bf16 v[60:63], v[152:155], v[168:171], v[60:63]
	v_mfma_f32_16x16x32_bf16 v[56:59], v[160:163], v[168:171], v[56:59]
	v_mfma_f32_16x16x32_bf16 v[52:55], v[152:155], v[176:179], v[52:55]
	v_mfma_f32_16x16x32_bf16 v[48:51], v[160:163], v[176:179], v[48:51]
	v_mfma_f32_16x16x32_bf16 v[36:39], v[152:155], v[184:187], v[36:39]
	v_mfma_f32_16x16x32_bf16 v[32:35], v[160:163], v[184:187], v[32:35]
	v_mfma_f32_16x16x32_bf16 v[20:23], v[152:155], v[192:195], v[20:23]
	v_mfma_f32_16x16x32_bf16 v[16:19], v[160:163], v[192:195], v[16:19]
	s_barrier
; #define STG(P, GB) do { const char* _gb = (GB); \
;     _Pragma("unroll") for (int _i = 0; _i < 2; ++_i) { \
;       __builtin_amdgcn_global_load_lds((const unsigned*)(_gb + voff[_i]), \
;         (LAS unsigned*)((LAS char*)(P) + ldsw + _i * 8192), 16, 0, 0); } } while (0)
; #define LDA(dst, b, h) _Pragma("unroll") for (int m = 0; m < 4; ++m) _Pragma("unroll") for (int k = 0; k < 2; ++k) \
;     dst[m][k] = *(const LAS bf16x8*)((LAS char*)SA(b, h) + aoff + m * 2048 + k * 1024)
; #define LDB(dst, b, h) _Pragma("unroll") for (int n = 0; n < 2; ++n) _Pragma("unroll") for (int k = 0; k < 2; ++k) \
;     dst[n][k] = *(const LAS bf16x8*)((LAS char*)SB(b, h) + boff + n * 2048 + k * 1024)
; #define MMA(ai, bj, At_, Bt_) do { __builtin_amdgcn_s_setprio(1); \
;     _Pragma("unroll") for (int m = 0; m < 4; ++m) _Pragma("unroll") for (int n = 0; n < 2; ++n) _Pragma("unroll") for (int k = 0; k < 2; ++k) \
;       acc[ai][bj][m][n] = __builtin_amdgcn_mfma_f32_16x16x32_bf16(Bt_[n][k], At_[m][k], acc[ai][bj][m][n], 0, 0, 0); \
;     __builtin_amdgcn_s_setprio(0); } while (0)
; #define WAIT_V(n) asm volatile("s_waitcnt vmcnt(" #n ")" ::: "memory")
; #define WAIT_L(n) asm volatile("s_waitcnt lgkmcnt(" #n ")" ::: "memory")
; #define BAR __builtin_amdgcn_s_barrier()
; #define SCHED __builtin_amdgcn_sched_barrier(0)
; __device__ __forceinline__ void gemm_phase(const bf16_t* __restrict__ A, const bf16_t* __restrict__ Bt, bf16_t* __restrict__ C, int M, int N, int K,
;                                            int ldc, const int EPI, char* smem, const int wid_u) {
;     ...
;       STG(SB(0, 1), b2 + hstep);
;       WAIT_V(6); BAR; MMA(1, 1, At, B1); BAR;
;       LDB(B0, 1, 0); SCHED; LDA(At, 1, 0); STG(SA(0, 1), a2 + hstep);
;       WAIT_L(8); BAR; WAIT_L(0); MMA(0, 0, At, B0); BAR; SCHED;
;       LDB(B1, 1, 1); STG(SB(1, 0), b3);
;       BAR; WAIT_L(0); MMA(0, 1, At, B1); BAR;
;       LDA(At, 1, 1); STG(SA(1, 0), a3);
	s_add_u32 s16, s20, 0x40000
	s_addc_u32 s17, s21, 0
	s_add_i32 s52, s39, s29
	v_lshl_add_u64 v[148:149], s[16:17], 0, v[130:131]
	s_mov_b32 m0, s52
	s_nop 0
	global_load_lds_dwordx4 v[148:149], off
	v_lshl_add_u64 v[148:149], s[16:17], 0, v[128:129]
	s_add_i32 m0, s52, 0x2000
	s_nop 0
	global_load_lds_dwordx4 v[148:149], off
	s_waitcnt vmcnt(6)
	s_barrier
	v_mfma_f32_16x16x32_bf16 v[44:47], v[196:199], v[164:167], v[44:47]
	v_mfma_f32_16x16x32_bf16 v[40:43], v[204:207], v[164:167], v[40:43]
	v_mfma_f32_16x16x32_bf16 v[28:31], v[196:199], v[172:175], v[28:31]
	v_mfma_f32_16x16x32_bf16 v[24:27], v[204:207], v[172:175], v[24:27]
	v_mfma_f32_16x16x32_bf16 v[12:15], v[196:199], v[180:183], v[12:15]
	v_mfma_f32_16x16x32_bf16 v[8:11], v[204:207], v[180:183], v[8:11]
	v_mfma_f32_16x16x32_bf16 v[4:7], v[196:199], v[188:191], v[4:7]
	v_mfma_f32_16x16x32_bf16 v[0:3], v[204:207], v[188:191], v[0:3]
	v_mfma_f32_16x16x32_bf16 v[44:47], v[200:203], v[168:171], v[44:47]
	v_mfma_f32_16x16x32_bf16 v[40:43], v[208:211], v[168:171], v[40:43]
	v_mfma_f32_16x16x32_bf16 v[28:31], v[200:203], v[176:179], v[28:31]
	v_mfma_f32_16x16x32_bf16 v[24:27], v[208:211], v[176:179], v[24:27]
	v_mfma_f32_16x16x32_bf16 v[12:15], v[200:203], v[184:187], v[12:15]
	v_mfma_f32_16x16x32_bf16 v[8:11], v[208:211], v[184:187], v[8:11]
	s_add_i32 s52, 0, 0x18000
	v_add_u32_e32 v147, s52, v143
	v_mfma_f32_16x16x32_bf16 v[4:7], v[200:203], v[192:195], v[4:7]
	v_mfma_f32_16x16x32_bf16 v[0:3], v[208:211], v[192:195], v[0:3]
	s_barrier
	ds_read_b128 v[148:151], v147
	ds_read_b128 v[152:155], v147 offset:1024
	ds_read_b128 v[156:159], v147 offset:2048
	ds_read_b128 v[160:163], v147 offset:3072
	s_add_u32 s16, s22, 0x40000
	s_addc_u32 s17, s23, 0
	s_mov_b32 m0, s34
	v_lshl_add_u64 v[196:197], s[16:17], 0, v[130:131]
	ds_read_b128 v[164:167], v145 offset:32768
	ds_read_b128 v[168:171], v145 offset:33792
	ds_read_b128 v[172:175], v145 offset:34816
	ds_read_b128 v[176:179], v145 offset:35840
	ds_read_b128 v[180:183], v145 offset:36864
	ds_read_b128 v[184:187], v145 offset:37888
	ds_read_b128 v[188:191], v145 offset:38912
	ds_read_b128 v[192:195], v145 offset:39936
	global_load_lds_dwordx4 v[196:197], off
	v_lshl_add_u64 v[196:197], s[16:17], 0, v[128:129]
	s_mov_b32 m0, s35
	s_nop 0
	global_load_lds_dwordx4 v[196:197], off
	s_waitcnt lgkmcnt(8)
	s_barrier
	s_waitcnt lgkmcnt(0)
	v_mfma_f32_16x16x32_bf16 v[124:127], v[148:151], v[164:167], v[124:127]
	v_mfma_f32_16x16x32_bf16 v[120:123], v[156:159], v[164:167], v[120:123]
	v_mfma_f32_16x16x32_bf16 v[116:119], v[148:151], v[172:175], v[116:119]
	v_mfma_f32_16x16x32_bf16 v[112:115], v[156:159], v[172:175], v[112:115]
	v_mfma_f32_16x16x32_bf16 v[100:103], v[148:151], v[180:183], v[100:103]
	v_mfma_f32_16x16x32_bf16 v[96:99], v[156:159], v[180:183], v[96:99]
	v_mfma_f32_16x16x32_bf16 v[84:87], v[148:151], v[188:191], v[84:87]
	v_mfma_f32_16x16x32_bf16 v[80:83], v[156:159], v[188:191], v[80:83]
	v_mfma_f32_16x16x32_bf16 v[124:127], v[152:155], v[168:171], v[124:127]
	v_mfma_f32_16x16x32_bf16 v[120:123], v[160:163], v[168:171], v[120:123]
	v_mfma_f32_16x16x32_bf16 v[116:119], v[152:155], v[176:179], v[116:119]
	v_mfma_f32_16x16x32_bf16 v[112:115], v[160:163], v[176:179], v[112:115]
	v_mfma_f32_16x16x32_bf16 v[100:103], v[152:155], v[184:187], v[100:103]
	v_mfma_f32_16x16x32_bf16 v[96:99], v[160:163], v[184:187], v[96:99]
	v_mfma_f32_16x16x32_bf16 v[84:87], v[152:155], v[192:195], v[84:87]
	v_mfma_f32_16x16x32_bf16 v[80:83], v[160:163], v[192:195], v[80:83]
	s_barrier
	s_add_i32 s22, 0, 0x1c000
	s_add_i32 s16, s52, s29
	v_add_u32_e32 v147, s22, v143
	v_lshl_add_u64 v[212:213], v[212:213], 0, s[8:9]
	s_mov_b32 m0, s16
	ds_read_b128 v[196:199], v147
	ds_read_b128 v[200:203], v147 offset:1024
	ds_read_b128 v[204:207], v147 offset:2048
	ds_read_b128 v[208:211], v147 offset:3072
	global_load_lds_dwordx4 v[212:213], off
	v_lshl_add_u64 v[212:213], v[214:215], 0, s[8:9]
	s_add_i32 m0, s16, 0x2000
	s_nop 0
	global_load_lds_dwordx4 v[212:213], off
	s_barrier
	s_waitcnt lgkmcnt(0)
	v_mfma_f32_16x16x32_bf16 v[108:111], v[196:199], v[164:167], v[108:111]
	v_mfma_f32_16x16x32_bf16 v[104:107], v[204:207], v[164:167], v[104:107]
	v_mfma_f32_16x16x32_bf16 v[92:95], v[196:199], v[172:175], v[92:95]
	v_mfma_f32_16x16x32_bf16 v[88:91], v[204:207], v[172:175], v[88:91]
	v_mfma_f32_16x16x32_bf16 v[76:79], v[196:199], v[180:183], v[76:79]
	v_mfma_f32_16x16x32_bf16 v[72:75], v[204:207], v[180:183], v[72:75]
	v_mfma_f32_16x16x32_bf16 v[68:71], v[196:199], v[188:191], v[68:71]
	v_mfma_f32_16x16x32_bf16 v[64:67], v[204:207], v[188:191], v[64:67]
	v_mfma_f32_16x16x32_bf16 v[108:111], v[200:203], v[168:171], v[108:111]
	v_mfma_f32_16x16x32_bf16 v[104:107], v[208:211], v[168:171], v[104:107]
	v_mfma_f32_16x16x32_bf16 v[92:95], v[200:203], v[176:179], v[92:95]
	v_mfma_f32_16x16x32_bf16 v[88:91], v[208:211], v[176:179], v[88:91]
	v_mfma_f32_16x16x32_bf16 v[76:79], v[200:203], v[184:187], v[76:79]
	v_mfma_f32_16x16x32_bf16 v[72:75], v[208:211], v[184:187], v[72:75]
	s_mov_b32 m0, s36
	v_lshl_add_u64 v[212:213], v[216:217], 0, s[8:9]
	v_mfma_f32_16x16x32_bf16 v[68:71], v[200:203], v[192:195], v[68:71]
	v_mfma_f32_16x16x32_bf16 v[64:67], v[208:211], v[192:195], v[64:67]
	s_barrier
	ds_read_b128 v[164:167], v145 offset:49152
	ds_read_b128 v[168:171], v145 offset:50176
	ds_read_b128 v[172:175], v145 offset:51200
	ds_read_b128 v[176:179], v145 offset:52224
	ds_read_b128 v[180:183], v145 offset:53248
	ds_read_b128 v[184:187], v145 offset:54272
	ds_read_b128 v[188:191], v145 offset:55296
	ds_read_b128 v[192:195], v145 offset:56320
	global_load_lds_dwordx4 v[212:213], off
	v_lshl_add_u64 v[212:213], v[218:219], 0, s[8:9]
	s_mov_b32 m0, s37
	s_nop 0
	global_load_lds_dwordx4 v[212:213], off
	s_barrier
; #define STG(P, GB) do { const char* _gb = (GB); \
;     _Pragma("unroll") for (int _i = 0; _i < 2; ++_i) { \
;       __builtin_amdgcn_global_load_lds((const unsigned*)(_gb + voff[_i]), \
;         (LAS unsigned*)((LAS char*)(P) + ldsw + _i * 8192), 16, 0, 0); } } while (0)
; #define WAIT_V(n) asm volatile("s_waitcnt vmcnt(" #n ")" ::: "memory")
; #define WAIT_L(n) asm volatile("s_waitcnt lgkmcnt(" #n ")" ::: "memory")
; #define BAR __builtin_amdgcn_s_barrier()
; __device__ __forceinline__ void gemm_phase(const bf16_t* __restrict__ A, const bf16_t* __restrict__ Bt, bf16_t* __restrict__ C, int M, int N, int K,
;                                            int ldc, const int EPI, char* smem, const int wid_u) {
;     ...
;       BAR; WAIT_L(0); MMA(1, 0, At, B0); BAR; SCHED;
;       STG(SB(1, 1), b3 + hstep);
;       WAIT_V(6); BAR; MMA(1, 1, At, B1); BAR;
;     }
;     {
;       const int brow = pm * BM, bcol = pn * BM;
; #pragma unroll
;       for (int ai = 0; ai < 2; ++ai)
; #pragma unroll
;         for (int m = 0; m < 4; ++m) {
;           const size_t row = (size_t)(brow + ai * HALF + wr * 64 + m * 16 + fr);
;           if (EPI == 0) {
; #pragma unroll
;             for (int bj = 0; bj < 2; ++bj) {
;               const f32x4 v0 = acc[ai][bj][m][0], v1 = acc[ai][bj][m][1];
;               uint4 u; u.x = cvt_pk_bf16(v0[0], v0[1]); u.y = cvt_pk_bf16(v0[2], v0[3]); u.z = cvt_pk_bf16(v1[0], v1[1]); u.w = cvt_pk_bf16(v1[2], v1[3]);
;               *(uint4*)(C + row * ldc + bcol + bj * HALF + wc * 32 + fq * 8) = u;
;             }
;           } else {
;             float o[8];
; #pragma unroll
;             for (int n = 0; n < 2; ++n) {
;               const f32x4 a = acc[ai][0][m][n], b = acc[ai][1][m][n];
; #pragma unroll
;               for (int j = 0; j < 4; ++j) o[n * 4 + j] = a[j] * __builtin_amdgcn_rcpf(1.f + __expf(-a[j])) * b[j];
;             }
;             *(uint4*)(C + row * ldc + (bcol >> 1) + wc * 32 + fq * 8) = pack8(o);
;           }
;         }
;     }
;     if (!has_next) break;
; #pragma unroll
;     for (int a = 0; a < 2; ++a)
; #pragma unroll
;       for (int b = 0; b < 2; ++b)
; #pragma unroll
;         for (int m = 0; m < 4; ++m)
; #pragma unroll
;           for (int n = 0; n < 2; ++n) acc[a][b][m][n] = (f32x4){0.f, 0.f, 0.f, 0.f};
;     pm = npm; pn = npn; cA = nA; cB = nB; ++ui;
;   }
;   WAIT_V(0);
;   if (wr == 0) BAR;
;   BAR;
	s_waitcnt lgkmcnt(0)
	v_mfma_f32_16x16x32_bf16 v[60:63], v[148:151], v[164:167], v[60:63]
	v_mfma_f32_16x16x32_bf16 v[56:59], v[156:159], v[164:167], v[56:59]
	v_mfma_f32_16x16x32_bf16 v[52:55], v[148:151], v[172:175], v[52:55]
	v_mfma_f32_16x16x32_bf16 v[48:51], v[156:159], v[172:175], v[48:51]
	v_mfma_f32_16x16x32_bf16 v[36:39], v[148:151], v[180:183], v[36:39]
	v_mfma_f32_16x16x32_bf16 v[32:35], v[156:159], v[180:183], v[32:35]
	v_mfma_f32_16x16x32_bf16 v[20:23], v[148:151], v[188:191], v[20:23]
	v_mfma_f32_16x16x32_bf16 v[16:19], v[156:159], v[188:191], v[16:19]
	v_mfma_f32_16x16x32_bf16 v[60:63], v[152:155], v[168:171], v[60:63]
	v_mfma_f32_16x16x32_bf16 v[56:59], v[160:163], v[168:171], v[56:59]
	v_mfma_f32_16x16x32_bf16 v[52:55], v[152:155], v[176:179], v[52:55]
	v_mfma_f32_16x16x32_bf16 v[48:51], v[160:163], v[176:179], v[48:51]
	v_mfma_f32_16x16x32_bf16 v[36:39], v[152:155], v[184:187], v[36:39]
	v_mfma_f32_16x16x32_bf16 v[32:35], v[160:163], v[184:187], v[32:35]
	v_mfma_f32_16x16x32_bf16 v[20:23], v[152:155], v[192:195], v[20:23]
	v_mfma_f32_16x16x32_bf16 v[16:19], v[160:163], v[192:195], v[16:19]
	s_barrier
	s_add_u32 s16, s20, 0x40080
	s_addc_u32 s17, s21, 0
	s_add_i32 s20, s22, s29
	v_lshl_add_u64 v[148:149], s[16:17], 0, v[130:131]
	s_mov_b32 m0, s20
	s_nop 0
	global_load_lds_dwordx4 v[148:149], off
	v_lshl_add_u64 v[148:149], s[16:17], 0, v[128:129]
	s_add_i32 m0, s20, 0x2000
	s_nop 0
	global_load_lds_dwordx4 v[148:149], off
	s_waitcnt vmcnt(6)
	s_barrier
	v_mfma_f32_16x16x32_bf16 v[44:47], v[196:199], v[164:167], v[44:47]
	v_mfma_f32_16x16x32_bf16 v[40:43], v[204:207], v[164:167], v[40:43]
	v_mfma_f32_16x16x32_bf16 v[28:31], v[196:199], v[172:175], v[28:31]
	v_mfma_f32_16x16x32_bf16 v[24:27], v[204:207], v[172:175], v[24:27]
	v_mfma_f32_16x16x32_bf16 v[12:15], v[196:199], v[180:183], v[12:15]
	v_mfma_f32_16x16x32_bf16 v[8:11], v[204:207], v[180:183], v[8:11]
	v_mfma_f32_16x16x32_bf16 v[4:7], v[196:199], v[188:191], v[4:7]
	v_mfma_f32_16x16x32_bf16 v[0:3], v[204:207], v[188:191], v[0:3]
	v_mfma_f32_16x16x32_bf16 v[44:47], v[200:203], v[168:171], v[44:47]
	v_mfma_f32_16x16x32_bf16 v[40:43], v[208:211], v[168:171], v[40:43]
	v_mfma_f32_16x16x32_bf16 v[28:31], v[200:203], v[176:179], v[28:31]
	v_mfma_f32_16x16x32_bf16 v[24:27], v[208:211], v[176:179], v[24:27]
	v_mfma_f32_16x16x32_bf16 v[12:15], v[200:203], v[184:187], v[12:15]
	v_mfma_f32_16x16x32_bf16 v[8:11], v[208:211], v[184:187], v[8:11]
	s_add_i32 s51, s51, 2
	s_add_u32 s49, s49, 0x100
	s_addc_u32 s50, s50, 0
	s_cmp_gt_u32 s51, 13
	s_mov_b64 s[16:17], s[18:19]
	v_mfma_f32_16x16x32_bf16 v[4:7], v[200:203], v[192:195], v[4:7]
	v_mfma_f32_16x16x32_bf16 v[0:3], v[208:211], v[192:195], v[0:3]
	s_barrier
	s_cbranch_scc0 .LBB0_334
	v_lshl_add_u32 v147, s44, 8, v142
	s_lshl_b32 s16, s45, 9
	s_mov_b32 s17, s7
	v_lshl_add_u64 v[148:149], v[132:133], 0, s[16:17]
	v_cvt_pk_bf16_f32 v68, v68, v69
	v_cvt_pk_bf16_f32 v69, v70, v71
	v_cvt_pk_bf16_f32 v70, v64, v65
	v_add_u32_e32 v64, 0x80, v147
	v_mad_i64_i32 v[150:151], s[16:17], v147, s40, v[148:149]
	v_cvt_pk_bf16_f32 v108, v108, v109
	v_cvt_pk_bf16_f32 v109, v110, v111
	v_cvt_pk_bf16_f32 v110, v104, v105
	v_cvt_pk_bf16_f32 v111, v106, v107
	v_or_b32_e32 v104, 16, v147
	v_mad_i64_i32 v[64:65], s[16:17], v64, s40, v[148:149]
	v_cvt_pk_bf16_f32 v44, v44, v45
	v_cvt_pk_bf16_f32 v45, v46, v47
	v_cvt_pk_bf16_f32 v46, v40, v41
	v_cvt_pk_bf16_f32 v47, v42, v43
	v_add_u32_e32 v40, 0x90, v147
	global_store_dwordx4 v[150:151], v[108:111], off offset:256
	v_cvt_pk_bf16_f32 v92, v92, v93
	v_cvt_pk_bf16_f32 v93, v94, v95
	v_mad_i64_i32 v[108:109], s[16:17], v104, s40, v[148:149]
	v_cvt_pk_bf16_f32 v94, v88, v89
	v_cvt_pk_bf16_f32 v95, v90, v91
	v_or_b32_e32 v88, 32, v147
	global_store_dwordx4 v[64:65], v[44:47], off offset:256
	v_cvt_pk_bf16_f32 v28, v28, v29
	v_cvt_pk_bf16_f32 v29, v30, v31
	v_mad_i64_i32 v[44:45], s[16:17], v40, s40, v[148:149]
	v_cvt_pk_bf16_f32 v30, v24, v25
	v_cvt_pk_bf16_f32 v31, v26, v27
	v_add_u32_e32 v24, 0xa0, v147
	global_store_dwordx4 v[108:109], v[92:95], off offset:256
	v_cvt_pk_bf16_f32 v76, v76, v77
	v_cvt_pk_bf16_f32 v77, v78, v79
	v_mad_i64_i32 v[92:93], s[16:17], v88, s40, v[148:149]
	v_cvt_pk_bf16_f32 v78, v72, v73
	v_cvt_pk_bf16_f32 v79, v74, v75
	v_or_b32_e32 v72, 48, v147
	global_store_dwordx4 v[44:45], v[28:31], off offset:256
	v_cvt_pk_bf16_f32 v12, v12, v13
	v_cvt_pk_bf16_f32 v13, v14, v15
	v_mad_i64_i32 v[28:29], s[16:17], v24, s40, v[148:149]
	v_cvt_pk_bf16_f32 v14, v8, v9
	v_cvt_pk_bf16_f32 v15, v10, v11
	v_add_u32_e32 v8, 0xb0, v147
	global_store_dwordx4 v[92:93], v[76:79], off offset:256
	global_store_dwordx4 v[28:29], v[12:15], off offset:256
	v_cvt_pk_bf16_f32 v124, v124, v125
	v_mad_i64_i32 v[76:77], s[16:17], v72, s40, v[148:149]
	v_mad_i64_i32 v[12:13], s[16:17], v8, s40, v[148:149]
	v_cvt_pk_bf16_f32 v125, v126, v127
	v_cvt_pk_bf16_f32 v126, v120, v121
	v_cvt_pk_bf16_f32 v127, v122, v123
	v_cvt_pk_bf16_f32 v104, v116, v117
	v_cvt_pk_bf16_f32 v105, v118, v119
	v_cvt_pk_bf16_f32 v106, v112, v113
	v_cvt_pk_bf16_f32 v107, v114, v115
	v_cvt_pk_bf16_f32 v88, v100, v101
	v_cvt_pk_bf16_f32 v89, v102, v103
	v_cvt_pk_bf16_f32 v90, v96, v97
	v_cvt_pk_bf16_f32 v91, v98, v99
	v_cvt_pk_bf16_f32 v72, v84, v85
	v_cvt_pk_bf16_f32 v73, v86, v87
	v_cvt_pk_bf16_f32 v74, v80, v81
	v_cvt_pk_bf16_f32 v75, v82, v83
	v_cvt_pk_bf16_f32 v71, v66, v67
	v_cvt_pk_bf16_f32 v60, v60, v61
	v_cvt_pk_bf16_f32 v61, v62, v63
	v_cvt_pk_bf16_f32 v62, v56, v57
	v_cvt_pk_bf16_f32 v63, v58, v59
	v_cvt_pk_bf16_f32 v40, v52, v53
	v_cvt_pk_bf16_f32 v41, v54, v55
	v_cvt_pk_bf16_f32 v42, v48, v49
	v_cvt_pk_bf16_f32 v43, v50, v51
	v_cvt_pk_bf16_f32 v24, v36, v37
	v_cvt_pk_bf16_f32 v25, v38, v39
	v_cvt_pk_bf16_f32 v26, v32, v33
	v_cvt_pk_bf16_f32 v27, v34, v35
	v_cvt_pk_bf16_f32 v8, v20, v21
	v_cvt_pk_bf16_f32 v9, v22, v23
	v_cvt_pk_bf16_f32 v10, v16, v17
	v_cvt_pk_bf16_f32 v11, v18, v19
	v_cvt_pk_bf16_f32 v4, v4, v5
	v_cvt_pk_bf16_f32 v5, v6, v7
	v_cvt_pk_bf16_f32 v6, v0, v1
	v_cvt_pk_bf16_f32 v7, v2, v3
	s_and_b64 vcc, exec, s[2:3]
	s_mov_b32 s44, s6
	s_mov_b32 s45, s10
	s_mov_b64 s[18:19], s[14:15]
	s_mov_b64 s[16:17], s[12:13]
	global_store_dwordx4 v[150:151], v[124:127], off
	global_store_dwordx4 v[108:109], v[104:107], off
	global_store_dwordx4 v[92:93], v[88:91], off
	global_store_dwordx4 v[76:77], v[72:75], off
	global_store_dwordx4 v[76:77], v[68:71], off offset:256
	global_store_dwordx4 v[64:65], v[60:63], off
	global_store_dwordx4 v[44:45], v[40:43], off
	global_store_dwordx4 v[28:29], v[24:27], off
	global_store_dwordx4 v[12:13], v[8:11], off
	global_store_dwordx4 v[12:13], v[4:7], off offset:256
	s_cbranch_vccz .LBB0_331
	s_waitcnt vmcnt(0)
	s_cmpk_gt_u32 s24, 0xff
	s_cbranch_scc1 .LBB0_338
	s_barrier

; #define STG(P, GB) do { const char* _gb = (GB); \
;     _Pragma("unroll") for (int _i = 0; _i < 2; ++_i) { \
;       __builtin_amdgcn_global_load_lds((const unsigned*)(_gb + voff[_i]), \
;         (LAS unsigned*)((LAS char*)(P) + ldsw + _i * 8192), 16, 0, 0); } } while (0)
; #define LDA(dst, b, h) _Pragma("unroll") for (int m = 0; m < 4; ++m) _Pragma("unroll") for (int k = 0; k < 2; ++k) \
;     dst[m][k] = *(const LAS bf16x8*)((LAS char*)SA(b, h) + aoff + m * 2048 + k * 1024)
; #define LDB(dst, b, h) _Pragma("unroll") for (int n = 0; n < 2; ++n) _Pragma("unroll") for (int k = 0; k < 2; ++k) \
;     dst[n][k] = *(const LAS bf16x8*)((LAS char*)SB(b, h) + boff + n * 2048 + k * 1024)
; #define MMA(ai, bj, At_, Bt_) do { __builtin_amdgcn_s_setprio(1); \
;     _Pragma("unroll") for (int m = 0; m < 4; ++m) _Pragma("unroll") for (int n = 0; n < 2; ++n) _Pragma("unroll") for (int k = 0; k < 2; ++k) \
;       acc[ai][bj][m][n] = __builtin_amdgcn_mfma_f32_16x16x32_bf16(Bt_[n][k], At_[m][k], acc[ai][bj][m][n], 0, 0, 0); \
;     __builtin_amdgcn_s_setprio(0); } while (0)
; #define WAIT_V(n) asm volatile("s_waitcnt vmcnt(" #n ")" ::: "memory")
; #define WAIT_L(n) asm volatile("s_waitcnt lgkmcnt(" #n ")" ::: "memory")
; #define BAR __builtin_amdgcn_s_barrier()
; #define SCHED __builtin_amdgcn_sched_barrier(0)
; __device__ __forceinline__ void gemm_phase(const bf16_t* __restrict__ A, const bf16_t* __restrict__ Bt, bf16_t* __restrict__ C, int M, int N, int K,
;                                            int ldc, const int EPI, char* smem, const int wid_u) {
;     ...
;     for (int t = 0; t < nt; t += 2) {
;       const bool last = (t == nt - 2);
;       const char* a1 = cA + (size_t)(t + 1) * kstep;
;       const char* a2 = last ? nA : cA + (size_t)(t + 2) * kstep;
;       const char* b2 = last ? nB : cB + (size_t)(t + 2) * kstep;
;       const char* a3 = a2 + kstep;
;       const char* b3 = b2 + kstep;
;       LDB(B0, 0, 0); SCHED; LDA(At, 0, 0); STG(SA(1, 1), a1 + hstep);
;       WAIT_L(8); BAR; WAIT_L(0); MMA(0, 0, At, B0); BAR; SCHED;
;       LDB(B1, 0, 1); STG(SB(0, 0), b2);
;       BAR; WAIT_L(0); MMA(0, 1, At, B1); BAR;
;       LDA(At, 0, 1); STG(SA(0, 0), a2);
;       BAR; WAIT_L(0); MMA(1, 0, At, B0); BAR; SCHED;
;       STG(SB(0, 1), b2 + hstep);
;       WAIT_V(6); BAR; MMA(1, 1, At, B1); BAR;
.LBB0_905:
	ds_read_b128 v[148:151], v144
	ds_read_b128 v[152:155], v144 offset:1024
	ds_read_b128 v[156:159], v144 offset:2048
	ds_read_b128 v[160:163], v144 offset:3072
	s_add_u32 s18, s16, 0x100
	s_addc_u32 s19, s17, 0
	s_cmp_eq_u32 s55, 12
	s_cselect_b32 s23, s49, s19
	s_cselect_b32 s22, s50, s18
	s_cselect_b32 s21, s51, s54
	s_cselect_b32 s20, s52, s53
	s_mov_b32 m0, s38
	v_lshl_add_u64 v[196:197], s[16:17], 0, v[136:137]
	ds_read_b128 v[164:167], v145
	ds_read_b128 v[168:171], v145 offset:1024
	ds_read_b128 v[172:175], v145 offset:2048
	ds_read_b128 v[176:179], v145 offset:3072
	ds_read_b128 v[180:183], v145 offset:4096
	ds_read_b128 v[184:187], v145 offset:5120
	ds_read_b128 v[188:191], v145 offset:6144
	ds_read_b128 v[192:195], v145 offset:7168
	global_load_lds_dwordx4 v[196:197], off
	v_lshl_add_u64 v[196:197], s[16:17], 0, v[134:135]
	s_mov_b32 m0, s39
	s_nop 0
	global_load_lds_dwordx4 v[196:197], off
	s_waitcnt lgkmcnt(8)
	s_barrier
	s_waitcnt lgkmcnt(0)
	v_mfma_f32_16x16x32_bf16 v[124:127], v[148:151], v[164:167], v[124:127]
	v_mfma_f32_16x16x32_bf16 v[120:123], v[156:159], v[164:167], v[120:123]
	v_mfma_f32_16x16x32_bf16 v[116:119], v[148:151], v[172:175], v[116:119]
	v_mfma_f32_16x16x32_bf16 v[112:115], v[156:159], v[172:175], v[112:115]
	v_mfma_f32_16x16x32_bf16 v[100:103], v[148:151], v[180:183], v[100:103]
	v_mfma_f32_16x16x32_bf16 v[96:99], v[156:159], v[180:183], v[96:99]
	v_mfma_f32_16x16x32_bf16 v[84:87], v[148:151], v[188:191], v[84:87]
	v_mfma_f32_16x16x32_bf16 v[80:83], v[156:159], v[188:191], v[80:83]
	v_mfma_f32_16x16x32_bf16 v[124:127], v[152:155], v[168:171], v[124:127]
	v_mfma_f32_16x16x32_bf16 v[120:123], v[160:163], v[168:171], v[120:123]
	v_mfma_f32_16x16x32_bf16 v[116:119], v[152:155], v[176:179], v[116:119]
	v_mfma_f32_16x16x32_bf16 v[112:115], v[160:163], v[176:179], v[112:115]
	v_mfma_f32_16x16x32_bf16 v[100:103], v[152:155], v[184:187], v[100:103]
	v_mfma_f32_16x16x32_bf16 v[96:99], v[160:163], v[184:187], v[96:99]
	v_mfma_f32_16x16x32_bf16 v[84:87], v[152:155], v[192:195], v[84:87]
	v_mfma_f32_16x16x32_bf16 v[80:83], v[160:163], v[192:195], v[80:83]
	s_barrier
	s_mov_b32 m0, s40
	v_lshl_add_u64 v[212:213], s[20:21], 0, v[130:131]
	ds_read_b128 v[196:199], v146
	ds_read_b128 v[200:203], v146 offset:1024
	ds_read_b128 v[204:207], v146 offset:2048
	ds_read_b128 v[208:211], v146 offset:3072
	global_load_lds_dwordx4 v[212:213], off
	v_lshl_add_u64 v[214:215], s[20:21], 0, v[128:129]
	s_mov_b32 m0, s41
	s_nop 0
	global_load_lds_dwordx4 v[214:215], off
	s_barrier
	s_waitcnt lgkmcnt(0)
	v_mfma_f32_16x16x32_bf16 v[108:111], v[196:199], v[164:167], v[108:111]
	v_mfma_f32_16x16x32_bf16 v[104:107], v[204:207], v[164:167], v[104:107]
	v_mfma_f32_16x16x32_bf16 v[92:95], v[196:199], v[172:175], v[92:95]
	v_mfma_f32_16x16x32_bf16 v[88:91], v[204:207], v[172:175], v[88:91]
	v_mfma_f32_16x16x32_bf16 v[76:79], v[196:199], v[180:183], v[76:79]
	v_mfma_f32_16x16x32_bf16 v[72:75], v[204:207], v[180:183], v[72:75]
	v_mfma_f32_16x16x32_bf16 v[68:71], v[196:199], v[188:191], v[68:71]
	v_mfma_f32_16x16x32_bf16 v[64:67], v[204:207], v[188:191], v[64:67]
	v_mfma_f32_16x16x32_bf16 v[108:111], v[200:203], v[168:171], v[108:111]
	v_mfma_f32_16x16x32_bf16 v[104:107], v[208:211], v[168:171], v[104:107]
	v_mfma_f32_16x16x32_bf16 v[92:95], v[200:203], v[176:179], v[92:95]
	v_mfma_f32_16x16x32_bf16 v[88:91], v[208:211], v[176:179], v[88:91]
	v_mfma_f32_16x16x32_bf16 v[76:79], v[200:203], v[184:187], v[76:79]
	v_mfma_f32_16x16x32_bf16 v[72:75], v[208:211], v[184:187], v[72:75]
	s_mov_b32 m0, s30
	v_lshl_add_u64 v[216:217], s[22:23], 0, v[130:131]
	v_mfma_f32_16x16x32_bf16 v[68:71], v[200:203], v[192:195], v[68:71]
	v_mfma_f32_16x16x32_bf16 v[64:67], v[208:211], v[192:195], v[64:67]
	s_barrier
	ds_read_b128 v[164:167], v145 offset:16384
	ds_read_b128 v[168:171], v145 offset:17408
	ds_read_b128 v[172:175], v145 offset:18432
	ds_read_b128 v[176:179], v145 offset:19456
	ds_read_b128 v[180:183], v145 offset:20480
	ds_read_b128 v[184:187], v145 offset:21504
	ds_read_b128 v[188:191], v145 offset:22528
	ds_read_b128 v[192:195], v145 offset:23552
	global_load_lds_dwordx4 v[216:217], off
	v_lshl_add_u64 v[218:219], s[22:23], 0, v[128:129]
	s_mov_b32 m0, s31
	s_nop 0
	global_load_lds_dwordx4 v[218:219], off
	s_barrier
	s_waitcnt lgkmcnt(0)
	v_mfma_f32_16x16x32_bf16 v[60:63], v[148:151], v[164:167], v[60:63]
	v_mfma_f32_16x16x32_bf16 v[56:59], v[156:159], v[164:167], v[56:59]
	v_mfma_f32_16x16x32_bf16 v[52:55], v[148:151], v[172:175], v[52:55]
	v_mfma_f32_16x16x32_bf16 v[48:51], v[156:159], v[172:175], v[48:51]
	v_mfma_f32_16x16x32_bf16 v[36:39], v[148:151], v[180:183], v[36:39]
	v_mfma_f32_16x16x32_bf16 v[32:35], v[156:159], v[180:183], v[32:35]
	v_mfma_f32_16x16x32_bf16 v[20:23], v[148:151], v[188:191], v[20:23]
	v_mfma_f32_16x16x32_bf16 v[16:19], v[156:159], v[188:191], v[16:19]
	v_mfma_f32_16x16x32_bf16 v[60:63], v[152:155], v[168:171], v[60:63]
	v_mfma_f32_16x16x32_bf16 v[56:59], v[160:163], v[168:171], v[56:59]
	v_mfma_f32_16x16x32_bf16 v[52:55], v[152:155], v[176:179], v[52:55]
	v_mfma_f32_16x16x32_bf16 v[48:51], v[160:163], v[176:179], v[48:51]
	v_mfma_f32_16x16x32_bf16 v[36:39], v[152:155], v[184:187], v[36:39]
	v_mfma_f32_16x16x32_bf16 v[32:35], v[160:163], v[184:187], v[32:35]
	v_mfma_f32_16x16x32_bf16 v[20:23], v[152:155], v[192:195], v[20:23]
	v_mfma_f32_16x16x32_bf16 v[16:19], v[160:163], v[192:195], v[16:19]
	s_barrier
	s_add_u32 s16, s20, 0x40000
	s_addc_u32 s17, s21, 0
	s_mov_b32 m0, s44
	v_lshl_add_u64 v[148:149], s[16:17], 0, v[130:131]
	global_load_lds_dwordx4 v[148:149], off
	v_lshl_add_u64 v[148:149], s[16:17], 0, v[128:129]
	s_add_i32 m0, s44, 0x2000
	s_nop 0
	global_load_lds_dwordx4 v[148:149], off
	s_waitcnt vmcnt(6)
	s_barrier
; #define STG(P, GB) do { const char* _gb = (GB); \
;     _Pragma("unroll") for (int _i = 0; _i < 2; ++_i) { \
;       __builtin_amdgcn_global_load_lds((const unsigned*)(_gb + voff[_i]), \
;         (LAS unsigned*)((LAS char*)(P) + ldsw + _i * 8192), 16, 0, 0); } } while (0)
; #define LDA(dst, b, h) _Pragma("unroll") for (int m = 0; m < 4; ++m) _Pragma("unroll") for (int k = 0; k < 2; ++k) \
;     dst[m][k] = *(const LAS bf16x8*)((LAS char*)SA(b, h) + aoff + m * 2048 + k * 1024)
; #define LDB(dst, b, h) _Pragma("unroll") for (int n = 0; n < 2; ++n) _Pragma("unroll") for (int k = 0; k < 2; ++k) \
;     dst[n][k] = *(const LAS bf16x8*)((LAS char*)SB(b, h) + boff + n * 2048 + k * 1024)
; #define MMA(ai, bj, At_, Bt_) do { __builtin_amdgcn_s_setprio(1); \
;     _Pragma("unroll") for (int m = 0; m < 4; ++m) _Pragma("unroll") for (int n = 0; n < 2; ++n) _Pragma("unroll") for (int k = 0; k < 2; ++k) \
;       acc[ai][bj][m][n] = __builtin_amdgcn_mfma_f32_16x16x32_bf16(Bt_[n][k], At_[m][k], acc[ai][bj][m][n], 0, 0, 0); \
;     __builtin_amdgcn_s_setprio(0); } while (0)
; #define WAIT_V(n) asm volatile("s_waitcnt vmcnt(" #n ")" ::: "memory")
; #define WAIT_L(n) asm volatile("s_waitcnt lgkmcnt(" #n ")" ::: "memory")
; #define BAR __builtin_amdgcn_s_barrier()
; #define SCHED __builtin_amdgcn_sched_barrier(0)
; __device__ __forceinline__ void gemm_phase(const bf16_t* __restrict__ A, const bf16_t* __restrict__ Bt, bf16_t* __restrict__ C, int M, int N, int K,
;                                            int ldc, const int EPI, char* smem, const int wid_u) {
;     ...
;       WAIT_V(6); BAR; MMA(1, 1, At, B1); BAR;
;       LDB(B0, 1, 0); SCHED; LDA(At, 1, 0); STG(SA(0, 1), a2 + hstep);
;       WAIT_L(8); BAR; WAIT_L(0); MMA(0, 0, At, B0); BAR; SCHED;
;       LDB(B1, 1, 1); STG(SB(1, 0), b3);
;       BAR; WAIT_L(0); MMA(0, 1, At, B1); BAR;
;       LDA(At, 1, 1); STG(SA(1, 0), a3);
	v_mfma_f32_16x16x32_bf16 v[44:47], v[196:199], v[164:167], v[44:47]
	v_mfma_f32_16x16x32_bf16 v[40:43], v[204:207], v[164:167], v[40:43]
	v_mfma_f32_16x16x32_bf16 v[28:31], v[196:199], v[172:175], v[28:31]
	v_mfma_f32_16x16x32_bf16 v[24:27], v[204:207], v[172:175], v[24:27]
	v_mfma_f32_16x16x32_bf16 v[12:15], v[196:199], v[180:183], v[12:15]
	v_mfma_f32_16x16x32_bf16 v[8:11], v[204:207], v[180:183], v[8:11]
	v_mfma_f32_16x16x32_bf16 v[4:7], v[196:199], v[188:191], v[4:7]
	v_mfma_f32_16x16x32_bf16 v[0:3], v[204:207], v[188:191], v[0:3]
	v_mfma_f32_16x16x32_bf16 v[44:47], v[200:203], v[168:171], v[44:47]
	v_mfma_f32_16x16x32_bf16 v[40:43], v[208:211], v[168:171], v[40:43]
	v_mfma_f32_16x16x32_bf16 v[28:31], v[200:203], v[176:179], v[28:31]
	v_mfma_f32_16x16x32_bf16 v[24:27], v[208:211], v[176:179], v[24:27]
	v_mfma_f32_16x16x32_bf16 v[12:15], v[200:203], v[184:187], v[12:15]
	v_mfma_f32_16x16x32_bf16 v[8:11], v[208:211], v[184:187], v[8:11]
	s_add_i32 s56, 0, 0x18000
	v_add_u32_e32 v147, s56, v143
	v_mfma_f32_16x16x32_bf16 v[4:7], v[200:203], v[192:195], v[4:7]
	v_mfma_f32_16x16x32_bf16 v[0:3], v[208:211], v[192:195], v[0:3]
	s_barrier
	ds_read_b128 v[148:151], v147
	ds_read_b128 v[152:155], v147 offset:1024
	ds_read_b128 v[156:159], v147 offset:2048
	ds_read_b128 v[160:163], v147 offset:3072
	s_add_u32 s16, s22, 0x40000
	s_addc_u32 s17, s23, 0
	s_mov_b32 m0, s34
	v_lshl_add_u64 v[196:197], s[16:17], 0, v[130:131]
	ds_read_b128 v[164:167], v145 offset:32768
	ds_read_b128 v[168:171], v145 offset:33792
	ds_read_b128 v[172:175], v145 offset:34816
	ds_read_b128 v[176:179], v145 offset:35840
	ds_read_b128 v[180:183], v145 offset:36864
	ds_read_b128 v[184:187], v145 offset:37888
	ds_read_b128 v[188:191], v145 offset:38912
	ds_read_b128 v[192:195], v145 offset:39936
	global_load_lds_dwordx4 v[196:197], off
	v_lshl_add_u64 v[196:197], s[16:17], 0, v[128:129]
	s_mov_b32 m0, s35
	s_nop 0
	global_load_lds_dwordx4 v[196:197], off
	s_waitcnt lgkmcnt(8)
	s_barrier
	s_waitcnt lgkmcnt(0)
	v_mfma_f32_16x16x32_bf16 v[124:127], v[148:151], v[164:167], v[124:127]
	v_mfma_f32_16x16x32_bf16 v[120:123], v[156:159], v[164:167], v[120:123]
	v_mfma_f32_16x16x32_bf16 v[116:119], v[148:151], v[172:175], v[116:119]
	v_mfma_f32_16x16x32_bf16 v[112:115], v[156:159], v[172:175], v[112:115]
	v_mfma_f32_16x16x32_bf16 v[100:103], v[148:151], v[180:183], v[100:103]
	v_mfma_f32_16x16x32_bf16 v[96:99], v[156:159], v[180:183], v[96:99]
	v_mfma_f32_16x16x32_bf16 v[84:87], v[148:151], v[188:191], v[84:87]
	v_mfma_f32_16x16x32_bf16 v[80:83], v[156:159], v[188:191], v[80:83]
	v_mfma_f32_16x16x32_bf16 v[124:127], v[152:155], v[168:171], v[124:127]
	v_mfma_f32_16x16x32_bf16 v[120:123], v[160:163], v[168:171], v[120:123]
	v_mfma_f32_16x16x32_bf16 v[116:119], v[152:155], v[176:179], v[116:119]
	v_mfma_f32_16x16x32_bf16 v[112:115], v[160:163], v[176:179], v[112:115]
	v_mfma_f32_16x16x32_bf16 v[100:103], v[152:155], v[184:187], v[100:103]
	v_mfma_f32_16x16x32_bf16 v[96:99], v[160:163], v[184:187], v[96:99]
	v_mfma_f32_16x16x32_bf16 v[84:87], v[152:155], v[192:195], v[84:87]
	v_mfma_f32_16x16x32_bf16 v[80:83], v[160:163], v[192:195], v[80:83]
	s_barrier
	s_add_i32 s22, 0, 0x1c000
	s_add_i32 s16, s56, s29
	v_add_u32_e32 v147, s22, v143
	v_lshl_add_u64 v[212:213], v[212:213], 0, s[10:11]
	s_mov_b32 m0, s16
	ds_read_b128 v[196:199], v147
	ds_read_b128 v[200:203], v147 offset:1024
	ds_read_b128 v[204:207], v147 offset:2048
	ds_read_b128 v[208:211], v147 offset:3072
	global_load_lds_dwordx4 v[212:213], off
	v_lshl_add_u64 v[212:213], v[214:215], 0, s[10:11]
	s_add_i32 m0, s16, 0x2000
	s_nop 0
	global_load_lds_dwordx4 v[212:213], off
	s_barrier
	s_waitcnt lgkmcnt(0)
	v_mfma_f32_16x16x32_bf16 v[108:111], v[196:199], v[164:167], v[108:111]
	v_mfma_f32_16x16x32_bf16 v[104:107], v[204:207], v[164:167], v[104:107]
	v_mfma_f32_16x16x32_bf16 v[92:95], v[196:199], v[172:175], v[92:95]
	v_mfma_f32_16x16x32_bf16 v[88:91], v[204:207], v[172:175], v[88:91]
	v_mfma_f32_16x16x32_bf16 v[76:79], v[196:199], v[180:183], v[76:79]
	v_mfma_f32_16x16x32_bf16 v[72:75], v[204:207], v[180:183], v[72:75]
	v_mfma_f32_16x16x32_bf16 v[68:71], v[196:199], v[188:191], v[68:71]
	v_mfma_f32_16x16x32_bf16 v[64:67], v[204:207], v[188:191], v[64:67]
	v_mfma_f32_16x16x32_bf16 v[108:111], v[200:203], v[168:171], v[108:111]
	v_mfma_f32_16x16x32_bf16 v[104:107], v[208:211], v[168:171], v[104:107]
	v_mfma_f32_16x16x32_bf16 v[92:95], v[200:203], v[176:179], v[92:95]
	v_mfma_f32_16x16x32_bf16 v[88:91], v[208:211], v[176:179], v[88:91]
	v_mfma_f32_16x16x32_bf16 v[76:79], v[200:203], v[184:187], v[76:79]
	v_mfma_f32_16x16x32_bf16 v[72:75], v[208:211], v[184:187], v[72:75]
	s_mov_b32 m0, s36
	v_lshl_add_u64 v[212:213], v[216:217], 0, s[10:11]
	v_mfma_f32_16x16x32_bf16 v[68:71], v[200:203], v[192:195], v[68:71]
	v_mfma_f32_16x16x32_bf16 v[64:67], v[208:211], v[192:195], v[64:67]
	s_barrier
	ds_read_b128 v[164:167], v145 offset:49152
	ds_read_b128 v[168:171], v145 offset:50176
	ds_read_b128 v[172:175], v145 offset:51200
	ds_read_b128 v[176:179], v145 offset:52224
	ds_read_b128 v[180:183], v145 offset:53248
	ds_read_b128 v[184:187], v145 offset:54272
	ds_read_b128 v[188:191], v145 offset:55296
	ds_read_b128 v[192:195], v145 offset:56320
	global_load_lds_dwordx4 v[212:213], off
	v_lshl_add_u64 v[212:213], v[218:219], 0, s[10:11]
	s_mov_b32 m0, s37
	s_nop 0
	global_load_lds_dwordx4 v[212:213], off
	s_barrier
; #define STG(P, GB) do { const char* _gb = (GB); \
;     _Pragma("unroll") for (int _i = 0; _i < 2; ++_i) { \
;       __builtin_amdgcn_global_load_lds((const unsigned*)(_gb + voff[_i]), \
;         (LAS unsigned*)((LAS char*)(P) + ldsw + _i * 8192), 16, 0, 0); } } while (0)
; #define MMA(ai, bj, At_, Bt_) do { __builtin_amdgcn_s_setprio(1); \
;     _Pragma("unroll") for (int m = 0; m < 4; ++m) _Pragma("unroll") for (int n = 0; n < 2; ++n) _Pragma("unroll") for (int k = 0; k < 2; ++k) \
;       acc[ai][bj][m][n] = __builtin_amdgcn_mfma_f32_16x16x32_bf16(Bt_[n][k], At_[m][k], acc[ai][bj][m][n], 0, 0, 0); \
;     __builtin_amdgcn_s_setprio(0); } while (0)
; #define WAIT_V(n) asm volatile("s_waitcnt vmcnt(" #n ")" ::: "memory")
; #define WAIT_L(n) asm volatile("s_waitcnt lgkmcnt(" #n ")" ::: "memory")
; #define BAR __builtin_amdgcn_s_barrier()
; #define SCHED __builtin_amdgcn_sched_barrier(0)
; __device__ __forceinline__ void gemm_phase(const bf16_t* __restrict__ A, const bf16_t* __restrict__ Bt, bf16_t* __restrict__ C, int M, int N, int K,
;                                            int ldc, const int EPI, char* smem, const int wid_u) {
;     ...
;       BAR; WAIT_L(0); MMA(1, 0, At, B0); BAR; SCHED;
;       STG(SB(1, 1), b3 + hstep);
;       WAIT_V(6); BAR; MMA(1, 1, At, B1); BAR;
;     }
	s_waitcnt lgkmcnt(0)
	v_mfma_f32_16x16x32_bf16 v[60:63], v[148:151], v[164:167], v[60:63]
	v_mfma_f32_16x16x32_bf16 v[56:59], v[156:159], v[164:167], v[56:59]
	v_mfma_f32_16x16x32_bf16 v[52:55], v[148:151], v[172:175], v[52:55]
	v_mfma_f32_16x16x32_bf16 v[48:51], v[156:159], v[172:175], v[48:51]
	v_mfma_f32_16x16x32_bf16 v[36:39], v[148:151], v[180:183], v[36:39]
	v_mfma_f32_16x16x32_bf16 v[32:35], v[156:159], v[180:183], v[32:35]
	v_mfma_f32_16x16x32_bf16 v[20:23], v[148:151], v[188:191], v[20:23]
	v_mfma_f32_16x16x32_bf16 v[16:19], v[156:159], v[188:191], v[16:19]
	v_mfma_f32_16x16x32_bf16 v[60:63], v[152:155], v[168:171], v[60:63]
	v_mfma_f32_16x16x32_bf16 v[56:59], v[160:163], v[168:171], v[56:59]
	v_mfma_f32_16x16x32_bf16 v[52:55], v[152:155], v[176:179], v[52:55]
	v_mfma_f32_16x16x32_bf16 v[48:51], v[160:163], v[176:179], v[48:51]
	v_mfma_f32_16x16x32_bf16 v[36:39], v[152:155], v[184:187], v[36:39]
	v_mfma_f32_16x16x32_bf16 v[32:35], v[160:163], v[184:187], v[32:35]
	v_mfma_f32_16x16x32_bf16 v[20:23], v[152:155], v[192:195], v[20:23]
	v_mfma_f32_16x16x32_bf16 v[16:19], v[160:163], v[192:195], v[16:19]
	s_barrier
	s_add_u32 s16, s20, 0x40080
	s_addc_u32 s17, s21, 0
	s_add_i32 s20, s22, s29
	v_lshl_add_u64 v[148:149], s[16:17], 0, v[130:131]
	s_mov_b32 m0, s20
	s_nop 0
	global_load_lds_dwordx4 v[148:149], off
	v_lshl_add_u64 v[148:149], s[16:17], 0, v[128:129]
	s_add_i32 m0, s20, 0x2000
	s_nop 0
	global_load_lds_dwordx4 v[148:149], off
	s_waitcnt vmcnt(6)
	s_barrier
	v_mfma_f32_16x16x32_bf16 v[44:47], v[196:199], v[164:167], v[44:47]
	v_mfma_f32_16x16x32_bf16 v[40:43], v[204:207], v[164:167], v[40:43]
	v_mfma_f32_16x16x32_bf16 v[28:31], v[196:199], v[172:175], v[28:31]
	v_mfma_f32_16x16x32_bf16 v[24:27], v[204:207], v[172:175], v[24:27]
	v_mfma_f32_16x16x32_bf16 v[12:15], v[196:199], v[180:183], v[12:15]
	v_mfma_f32_16x16x32_bf16 v[8:11], v[204:207], v[180:183], v[8:11]
	v_mfma_f32_16x16x32_bf16 v[4:7], v[196:199], v[188:191], v[4:7]
	v_mfma_f32_16x16x32_bf16 v[0:3], v[204:207], v[188:191], v[0:3]
	v_mfma_f32_16x16x32_bf16 v[44:47], v[200:203], v[168:171], v[44:47]
	v_mfma_f32_16x16x32_bf16 v[40:43], v[208:211], v[168:171], v[40:43]
	v_mfma_f32_16x16x32_bf16 v[28:31], v[200:203], v[176:179], v[28:31]
	v_mfma_f32_16x16x32_bf16 v[24:27], v[208:211], v[176:179], v[24:27]
	v_mfma_f32_16x16x32_bf16 v[12:15], v[200:203], v[184:187], v[12:15]
	v_mfma_f32_16x16x32_bf16 v[8:11], v[208:211], v[184:187], v[8:11]
	s_add_i32 s55, s55, 2
	s_add_u32 s53, s53, 0x100
	s_addc_u32 s54, s54, 0
	s_cmp_gt_u32 s55, 13
	s_mov_b64 s[16:17], s[18:19]
	v_mfma_f32_16x16x32_bf16 v[4:7], v[200:203], v[192:195], v[4:7]
	v_mfma_f32_16x16x32_bf16 v[0:3], v[208:211], v[192:195], v[0:3]
	s_barrier
	s_cbranch_scc0 .LBB0_905
; #define WAIT_V(n) asm volatile("s_waitcnt vmcnt(" #n ")" ::: "memory")
; #define BAR __builtin_amdgcn_s_barrier()
; __device__ __forceinline__ void gemm_phase(const bf16_t* __restrict__ A, const bf16_t* __restrict__ Bt, bf16_t* __restrict__ C, int M, int N, int K,
;                                            int ldc, const int EPI, char* smem, const int wid_u) {
;     ...
;       const int brow = pm * BM, bcol = pn * BM;
; #pragma unroll
;       for (int ai = 0; ai < 2; ++ai)
; #pragma unroll
;         for (int m = 0; m < 4; ++m) {
;           const size_t row = (size_t)(brow + ai * HALF + wr * 64 + m * 16 + fr);
;           if (EPI == 0) {
; #pragma unroll
;             for (int bj = 0; bj < 2; ++bj) {
;               const f32x4 v0 = acc[ai][bj][m][0], v1 = acc[ai][bj][m][1];
;               uint4 u; u.x = cvt_pk_bf16(v0[0], v0[1]); u.y = cvt_pk_bf16(v0[2], v0[3]); u.z = cvt_pk_bf16(v1[0], v1[1]); u.w = cvt_pk_bf16(v1[2], v1[3]);
;               *(uint4*)(C + row * ldc + bcol + bj * HALF + wc * 32 + fq * 8) = u;
;             }
;           } else {
;             float o[8];
; #pragma unroll
;             for (int n = 0; n < 2; ++n) {
;               const f32x4 a = acc[ai][0][m][n], b = acc[ai][1][m][n];
; #pragma unroll
;               for (int j = 0; j < 4; ++j) o[n * 4 + j] = a[j] * __builtin_amdgcn_rcpf(1.f + __expf(-a[j])) * b[j];
;             }
;             *(uint4*)(C + row * ldc + (bcol >> 1) + wc * 32 + fq * 8) = pack8(o);
;           }
;         }
;     }
;     if (!has_next) break;
; #pragma unroll
;     for (int a = 0; a < 2; ++a)
; #pragma unroll
;       for (int b = 0; b < 2; ++b)
; #pragma unroll
;         for (int m = 0; m < 4; ++m)
; #pragma unroll
;           for (int n = 0; n < 2; ++n) acc[a][b][m][n] = (f32x4){0.f, 0.f, 0.f, 0.f};
;     pm = npm; pn = npn; cA = nA; cB = nB; ++ui;
;   }
;   WAIT_V(0);
;   if (wr == 0) BAR;
;   BAR;
	v_lshl_add_u32 v148, s47, 8, v142
	v_cvt_pk_bf16_f32 v68, v68, v69
	v_cvt_pk_bf16_f32 v69, v70, v71
	v_cvt_pk_bf16_f32 v70, v64, v65
	v_add_u32_e32 v64, 0x80, v148
	s_lshl_b32 s16, s48, 9
	s_mov_b32 s17, s9
	v_ashrrev_i32_e32 v149, 31, v148
	v_cvt_pk_bf16_f32 v108, v108, v109
	v_cvt_pk_bf16_f32 v109, v110, v111
	v_cvt_pk_bf16_f32 v110, v104, v105
	v_or_b32_e32 v104, 16, v148
	v_ashrrev_i32_e32 v65, 31, v64
	v_cvt_pk_bf16_f32 v44, v44, v45
	v_cvt_pk_bf16_f32 v45, v46, v47
	v_cvt_pk_bf16_f32 v46, v40, v41
	v_add_u32_e32 v40, 0x90, v148
	v_lshl_add_u64 v[150:151], v[132:133], 0, s[16:17]
	v_lshlrev_b64 v[152:153], 11, v[148:149]
	v_ashrrev_i32_e32 v105, 31, v104
	v_cvt_pk_bf16_f32 v92, v92, v93
	v_cvt_pk_bf16_f32 v93, v94, v95
	v_cvt_pk_bf16_f32 v94, v88, v89
	v_or_b32_e32 v88, 32, v148
	v_lshlrev_b64 v[64:65], 11, v[64:65]
	v_ashrrev_i32_e32 v41, 31, v40
	v_cvt_pk_bf16_f32 v28, v28, v29
	v_cvt_pk_bf16_f32 v29, v30, v31
	v_cvt_pk_bf16_f32 v30, v24, v25
	v_add_u32_e32 v24, 0xa0, v148
	v_lshl_add_u64 v[152:153], v[150:151], 0, v[152:153]
	v_cvt_pk_bf16_f32 v111, v106, v107
	v_lshlrev_b64 v[104:105], 11, v[104:105]
	v_ashrrev_i32_e32 v89, 31, v88
	v_cvt_pk_bf16_f32 v76, v76, v77
	v_cvt_pk_bf16_f32 v77, v78, v79
	v_cvt_pk_bf16_f32 v78, v72, v73
	v_or_b32_e32 v72, 48, v148
	v_lshl_add_u64 v[64:65], v[150:151], 0, v[64:65]
	v_cvt_pk_bf16_f32 v47, v42, v43
	v_lshlrev_b64 v[40:41], 11, v[40:41]
	v_ashrrev_i32_e32 v25, 31, v24
	v_cvt_pk_bf16_f32 v12, v12, v13
	v_cvt_pk_bf16_f32 v13, v14, v15
	v_cvt_pk_bf16_f32 v14, v8, v9
	v_add_u32_e32 v8, 0xb0, v148
	global_store_dwordx4 v[152:153], v[108:111], off offset:256
	v_cvt_pk_bf16_f32 v95, v90, v91
	v_lshlrev_b64 v[88:89], 11, v[88:89]
	v_lshl_add_u64 v[108:109], v[150:151], 0, v[104:105]
	v_ashrrev_i32_e32 v73, 31, v72
	global_store_dwordx4 v[64:65], v[44:47], off offset:256
	v_cvt_pk_bf16_f32 v31, v26, v27
	v_lshlrev_b64 v[24:25], 11, v[24:25]
	v_lshl_add_u64 v[44:45], v[150:151], 0, v[40:41]
	v_ashrrev_i32_e32 v9, 31, v8
	global_store_dwordx4 v[108:109], v[92:95], off offset:256
	v_cvt_pk_bf16_f32 v79, v74, v75
	v_lshlrev_b64 v[72:73], 11, v[72:73]
	v_lshl_add_u64 v[92:93], v[150:151], 0, v[88:89]
	global_store_dwordx4 v[44:45], v[28:31], off offset:256
	v_cvt_pk_bf16_f32 v15, v10, v11
	v_lshlrev_b64 v[8:9], 11, v[8:9]
	v_lshl_add_u64 v[28:29], v[150:151], 0, v[24:25]
	v_cvt_pk_bf16_f32 v124, v124, v125
	v_cvt_pk_bf16_f32 v125, v126, v127
	v_cvt_pk_bf16_f32 v126, v120, v121
	v_cvt_pk_bf16_f32 v127, v122, v123
	v_cvt_pk_bf16_f32 v104, v116, v117
	v_cvt_pk_bf16_f32 v105, v118, v119
	v_cvt_pk_bf16_f32 v106, v112, v113
	v_cvt_pk_bf16_f32 v107, v114, v115
	v_cvt_pk_bf16_f32 v88, v100, v101
	v_cvt_pk_bf16_f32 v89, v102, v103
	v_cvt_pk_bf16_f32 v90, v96, v97
	v_cvt_pk_bf16_f32 v91, v98, v99
	global_store_dwordx4 v[92:93], v[76:79], off offset:256
	v_cvt_pk_bf16_f32 v74, v80, v81
	v_cvt_pk_bf16_f32 v75, v82, v83
	v_lshl_add_u64 v[76:77], v[150:151], 0, v[72:73]
	v_cvt_pk_bf16_f32 v72, v84, v85
	v_cvt_pk_bf16_f32 v73, v86, v87
	v_cvt_pk_bf16_f32 v71, v66, v67
	v_cvt_pk_bf16_f32 v60, v60, v61
	v_cvt_pk_bf16_f32 v61, v62, v63
	v_cvt_pk_bf16_f32 v62, v56, v57
	v_cvt_pk_bf16_f32 v63, v58, v59
	v_cvt_pk_bf16_f32 v40, v52, v53
	v_cvt_pk_bf16_f32 v41, v54, v55
	v_cvt_pk_bf16_f32 v42, v48, v49
	v_cvt_pk_bf16_f32 v43, v50, v51
	v_cvt_pk_bf16_f32 v24, v36, v37
	v_cvt_pk_bf16_f32 v25, v38, v39
	v_cvt_pk_bf16_f32 v26, v32, v33
	v_cvt_pk_bf16_f32 v27, v34, v35
	global_store_dwordx4 v[28:29], v[12:15], off offset:256
	v_cvt_pk_bf16_f32 v10, v16, v17
	v_cvt_pk_bf16_f32 v11, v18, v19
	v_lshl_add_u64 v[12:13], v[150:151], 0, v[8:9]
	v_cvt_pk_bf16_f32 v8, v20, v21
	v_cvt_pk_bf16_f32 v9, v22, v23
	v_cvt_pk_bf16_f32 v4, v4, v5
	v_cvt_pk_bf16_f32 v5, v6, v7
	v_cvt_pk_bf16_f32 v6, v0, v1
	v_cvt_pk_bf16_f32 v7, v2, v3
	s_and_b64 vcc, exec, s[4:5]
	s_mov_b32 s47, s8
	s_mov_b32 s48, s46
	s_mov_b64 s[18:19], s[14:15]
	s_mov_b64 s[16:17], s[12:13]
	global_store_dwordx4 v[152:153], v[124:127], off
	global_store_dwordx4 v[108:109], v[104:107], off
	global_store_dwordx4 v[92:93], v[88:91], off
	global_store_dwordx4 v[76:77], v[72:75], off
	global_store_dwordx4 v[76:77], v[68:71], off offset:256
	global_store_dwordx4 v[64:65], v[60:63], off
	global_store_dwordx4 v[44:45], v[40:43], off
	global_store_dwordx4 v[28:29], v[24:27], off
	global_store_dwordx4 v[12:13], v[8:11], off
	global_store_dwordx4 v[12:13], v[4:7], off offset:256
	s_cbranch_vccz .LBB0_902
	s_waitcnt vmcnt(0)
	s_cmpk_gt_u32 s24, 0xff
	s_cbranch_scc1 .LBB0_909
	s_barrier

; #define STG(P, GB) do { const char* _gb = (GB); \
;     _Pragma("unroll") for (int _i = 0; _i < 2; ++_i) { \
;       __builtin_amdgcn_global_load_lds((const unsigned*)(_gb + voff[_i]), \
;         (LAS unsigned*)((LAS char*)(P) + ldsw + _i * 8192), 16, 0, 0); } } while (0)
; #define LDA(dst, b, h) _Pragma("unroll") for (int m = 0; m < 4; ++m) _Pragma("unroll") for (int k = 0; k < 2; ++k) \
;     dst[m][k] = *(const LAS bf16x8*)((LAS char*)SA(b, h) + aoff + m * 2048 + k * 1024)
; #define LDB(dst, b, h) _Pragma("unroll") for (int n = 0; n < 2; ++n) _Pragma("unroll") for (int k = 0; k < 2; ++k) \
;     dst[n][k] = *(const LAS bf16x8*)((LAS char*)SB(b, h) + boff + n * 2048 + k * 1024)
; #define MMA(ai, bj, At_, Bt_) do { __builtin_amdgcn_s_setprio(1); \
;     _Pragma("unroll") for (int m = 0; m < 4; ++m) _Pragma("unroll") for (int n = 0; n < 2; ++n) _Pragma("unroll") for (int k = 0; k < 2; ++k) \
;       acc[ai][bj][m][n] = __builtin_amdgcn_mfma_f32_16x16x32_bf16(Bt_[n][k], At_[m][k], acc[ai][bj][m][n], 0, 0, 0); \
;     __builtin_amdgcn_s_setprio(0); } while (0)
; #define WAIT_L(n) asm volatile("s_waitcnt lgkmcnt(" #n ")" ::: "memory")
; #define BAR __builtin_amdgcn_s_barrier()
; #define SCHED __builtin_amdgcn_sched_barrier(0)
; __device__ __forceinline__ void gemm_phase(const bf16_t* __restrict__ A, const bf16_t* __restrict__ Bt, bf16_t* __restrict__ C, int M, int N, int K,
;                                            int ldc, const int EPI, char* smem, const int wid_u) {
;     ...
;     for (int t = 0; t < nt; t += 2) {
;       const bool last = (t == nt - 2);
;       const char* a1 = cA + (size_t)(t + 1) * kstep;
;       const char* a2 = last ? nA : cA + (size_t)(t + 2) * kstep;
;       const char* b2 = last ? nB : cB + (size_t)(t + 2) * kstep;
;       const char* a3 = a2 + kstep;
;       const char* b3 = b2 + kstep;
;       LDB(B0, 0, 0); SCHED; LDA(At, 0, 0); STG(SA(1, 1), a1 + hstep);
;       WAIT_L(8); BAR; WAIT_L(0); MMA(0, 0, At, B0); BAR; SCHED;
;       LDB(B1, 0, 1); STG(SB(0, 0), b2);
;       BAR; WAIT_L(0); MMA(0, 1, At, B1); BAR;
;       LDA(At, 0, 1); STG(SA(0, 0), a2);
;       BAR; WAIT_L(0); MMA(1, 0, At, B0); BAR; SCHED;
.LBB0_1026:
	ds_read_b128 v[150:153], v146
	ds_read_b128 v[154:157], v146 offset:1024
	ds_read_b128 v[158:161], v146 offset:2048
	ds_read_b128 v[162:165], v146 offset:3072
	s_add_u32 s20, s18, 0x100
	s_addc_u32 s21, s19, 0
	s_cmp_eq_u32 s53, 12
	s_cselect_b32 s25, s48, s21
	s_cselect_b32 s24, s49, s20
	s_cselect_b32 s23, s13, s52
	s_cselect_b32 s22, s50, s51
	v_lshl_add_u64 v[142:143], s[18:19], 0, v[136:137]
	s_add_i32 m0, s34, 0xc000
	ds_read_b128 v[166:169], v147
	ds_read_b128 v[170:173], v147 offset:1024
	ds_read_b128 v[174:177], v147 offset:2048
	ds_read_b128 v[178:181], v147 offset:3072
	ds_read_b128 v[182:185], v147 offset:4096
	ds_read_b128 v[186:189], v147 offset:5120
	ds_read_b128 v[190:193], v147 offset:6144
	ds_read_b128 v[194:197], v147 offset:7168
	global_load_lds_dwordx4 v[142:143], off
	v_lshl_add_u64 v[142:143], s[18:19], 0, v[134:135]
	s_add_i32 m0, s34, 0xe000
	s_nop 0
	global_load_lds_dwordx4 v[142:143], off
	s_waitcnt lgkmcnt(8)
	s_barrier
	s_waitcnt lgkmcnt(0)
	v_mfma_f32_16x16x32_bf16 v[124:127], v[150:153], v[166:169], v[124:127]
	v_mfma_f32_16x16x32_bf16 v[120:123], v[158:161], v[166:169], v[120:123]
	v_mfma_f32_16x16x32_bf16 v[108:111], v[150:153], v[174:177], v[108:111]
	v_mfma_f32_16x16x32_bf16 v[104:107], v[158:161], v[174:177], v[104:107]
	v_mfma_f32_16x16x32_bf16 v[92:95], v[150:153], v[182:185], v[92:95]
	v_mfma_f32_16x16x32_bf16 v[88:91], v[158:161], v[182:185], v[88:91]
	v_mfma_f32_16x16x32_bf16 v[76:79], v[150:153], v[190:193], v[76:79]
	v_mfma_f32_16x16x32_bf16 v[72:75], v[158:161], v[190:193], v[72:75]
	v_mfma_f32_16x16x32_bf16 v[124:127], v[154:157], v[170:173], v[124:127]
	v_mfma_f32_16x16x32_bf16 v[120:123], v[162:165], v[170:173], v[120:123]
	v_mfma_f32_16x16x32_bf16 v[108:111], v[154:157], v[178:181], v[108:111]
	v_mfma_f32_16x16x32_bf16 v[104:107], v[162:165], v[178:181], v[104:107]
	v_mfma_f32_16x16x32_bf16 v[92:95], v[154:157], v[186:189], v[92:95]
	v_mfma_f32_16x16x32_bf16 v[88:91], v[162:165], v[186:189], v[88:91]
	v_mfma_f32_16x16x32_bf16 v[76:79], v[154:157], v[194:197], v[76:79]
	v_mfma_f32_16x16x32_bf16 v[72:75], v[162:165], v[194:197], v[72:75]
	s_barrier
	s_add_i32 s18, s40, s31
	v_lshl_add_u64 v[142:143], s[22:23], 0, v[130:131]
	s_mov_b32 m0, s18
	ds_read_b128 v[198:201], v148
	ds_read_b128 v[202:205], v148 offset:1024
	ds_read_b128 v[206:209], v148 offset:2048
	ds_read_b128 v[210:213], v148 offset:3072
	global_load_lds_dwordx4 v[142:143], off
	v_lshl_add_u64 v[214:215], s[22:23], 0, v[128:129]
	s_add_i32 m0, s18, 0x2000
	s_nop 0
	global_load_lds_dwordx4 v[214:215], off
	s_barrier
	s_waitcnt lgkmcnt(0)
	v_mfma_f32_16x16x32_bf16 v[116:119], v[198:201], v[166:169], v[116:119]
	v_mfma_f32_16x16x32_bf16 v[112:115], v[206:209], v[166:169], v[112:115]
	v_mfma_f32_16x16x32_bf16 v[100:103], v[198:201], v[174:177], v[100:103]
	v_mfma_f32_16x16x32_bf16 v[96:99], v[206:209], v[174:177], v[96:99]
	v_mfma_f32_16x16x32_bf16 v[84:87], v[198:201], v[182:185], v[84:87]
	v_mfma_f32_16x16x32_bf16 v[80:83], v[206:209], v[182:185], v[80:83]
	v_mfma_f32_16x16x32_bf16 v[68:71], v[198:201], v[190:193], v[68:71]
	v_mfma_f32_16x16x32_bf16 v[64:67], v[206:209], v[190:193], v[64:67]
	v_mfma_f32_16x16x32_bf16 v[116:119], v[202:205], v[170:173], v[116:119]
	v_mfma_f32_16x16x32_bf16 v[112:115], v[210:213], v[170:173], v[112:115]
	v_mfma_f32_16x16x32_bf16 v[100:103], v[202:205], v[178:181], v[100:103]
	v_mfma_f32_16x16x32_bf16 v[96:99], v[210:213], v[178:181], v[96:99]
	v_mfma_f32_16x16x32_bf16 v[84:87], v[202:205], v[186:189], v[84:87]
	v_mfma_f32_16x16x32_bf16 v[80:83], v[210:213], v[186:189], v[80:83]
	s_mov_b32 m0, s34
	v_lshl_add_u64 v[216:217], s[24:25], 0, v[130:131]
	v_mfma_f32_16x16x32_bf16 v[68:71], v[202:205], v[194:197], v[68:71]
	v_mfma_f32_16x16x32_bf16 v[64:67], v[210:213], v[194:197], v[64:67]
	s_barrier
	ds_read_b128 v[166:169], v147 offset:16384
	ds_read_b128 v[170:173], v147 offset:17408
	ds_read_b128 v[174:177], v147 offset:18432
	ds_read_b128 v[178:181], v147 offset:19456
	ds_read_b128 v[182:185], v147 offset:20480
	ds_read_b128 v[186:189], v147 offset:21504
	ds_read_b128 v[190:193], v147 offset:22528
	ds_read_b128 v[194:197], v147 offset:23552
	global_load_lds_dwordx4 v[216:217], off
	v_lshl_add_u64 v[218:219], s[24:25], 0, v[128:129]
	s_mov_b32 m0, s35
	s_nop 0
	global_load_lds_dwordx4 v[218:219], off
	s_barrier
	s_waitcnt lgkmcnt(0)
	v_mfma_f32_16x16x32_bf16 v[60:63], v[150:153], v[166:169], v[60:63]
	v_mfma_f32_16x16x32_bf16 v[56:59], v[158:161], v[166:169], v[56:59]
	v_mfma_f32_16x16x32_bf16 v[44:47], v[150:153], v[174:177], v[44:47]
	v_mfma_f32_16x16x32_bf16 v[40:43], v[158:161], v[174:177], v[40:43]
	v_mfma_f32_16x16x32_bf16 v[28:31], v[150:153], v[182:185], v[28:31]
	v_mfma_f32_16x16x32_bf16 v[24:27], v[158:161], v[182:185], v[24:27]
	v_mfma_f32_16x16x32_bf16 v[12:15], v[150:153], v[190:193], v[12:15]
	v_mfma_f32_16x16x32_bf16 v[8:11], v[158:161], v[190:193], v[8:11]
	v_mfma_f32_16x16x32_bf16 v[60:63], v[154:157], v[170:173], v[60:63]
	v_mfma_f32_16x16x32_bf16 v[56:59], v[162:165], v[170:173], v[56:59]
	v_mfma_f32_16x16x32_bf16 v[44:47], v[154:157], v[178:181], v[44:47]
	v_mfma_f32_16x16x32_bf16 v[40:43], v[162:165], v[178:181], v[40:43]
	v_mfma_f32_16x16x32_bf16 v[28:31], v[154:157], v[186:189], v[28:31]
	v_mfma_f32_16x16x32_bf16 v[24:27], v[162:165], v[186:189], v[24:27]
	v_mfma_f32_16x16x32_bf16 v[12:15], v[154:157], v[194:197], v[12:15]
	v_mfma_f32_16x16x32_bf16 v[8:11], v[162:165], v[194:197], v[8:11]
	s_barrier
; #define STG(P, GB) do { const char* _gb = (GB); \
;     _Pragma("unroll") for (int _i = 0; _i < 2; ++_i) { \
;       __builtin_amdgcn_global_load_lds((const unsigned*)(_gb + voff[_i]), \
;         (LAS unsigned*)((LAS char*)(P) + ldsw + _i * 8192), 16, 0, 0); } } while (0)
; #define LDA(dst, b, h) _Pragma("unroll") for (int m = 0; m < 4; ++m) _Pragma("unroll") for (int k = 0; k < 2; ++k) \
;     dst[m][k] = *(const LAS bf16x8*)((LAS char*)SA(b, h) + aoff + m * 2048 + k * 1024)
; #define LDB(dst, b, h) _Pragma("unroll") for (int n = 0; n < 2; ++n) _Pragma("unroll") for (int k = 0; k < 2; ++k) \
;     dst[n][k] = *(const LAS bf16x8*)((LAS char*)SB(b, h) + boff + n * 2048 + k * 1024)
; #define MMA(ai, bj, At_, Bt_) do { __builtin_amdgcn_s_setprio(1); \
;     _Pragma("unroll") for (int m = 0; m < 4; ++m) _Pragma("unroll") for (int n = 0; n < 2; ++n) _Pragma("unroll") for (int k = 0; k < 2; ++k) \
;       acc[ai][bj][m][n] = __builtin_amdgcn_mfma_f32_16x16x32_bf16(Bt_[n][k], At_[m][k], acc[ai][bj][m][n], 0, 0, 0); \
;     __builtin_amdgcn_s_setprio(0); } while (0)
; #define WAIT_V(n) asm volatile("s_waitcnt vmcnt(" #n ")" ::: "memory")
; #define WAIT_L(n) asm volatile("s_waitcnt lgkmcnt(" #n ")" ::: "memory")
; #define BAR __builtin_amdgcn_s_barrier()
; #define SCHED __builtin_amdgcn_sched_barrier(0)
; __device__ __forceinline__ void gemm_phase(const bf16_t* __restrict__ A, const bf16_t* __restrict__ Bt, bf16_t* __restrict__ C, int M, int N, int K,
;                                            int ldc, const int EPI, char* smem, const int wid_u) {
;     ...
;       STG(SB(0, 1), b2 + hstep);
;       WAIT_V(6); BAR; MMA(1, 1, At, B1); BAR;
;       LDB(B0, 1, 0); SCHED; LDA(At, 1, 0); STG(SA(0, 1), a2 + hstep);
;       WAIT_L(8); BAR; WAIT_L(0); MMA(0, 0, At, B0); BAR; SCHED;
;       LDB(B1, 1, 1); STG(SB(1, 0), b3);
;       BAR; WAIT_L(0); MMA(0, 1, At, B1); BAR;
;       LDA(At, 1, 1); STG(SA(1, 0), a3);
	s_add_u32 s18, s22, 0x40000
	s_addc_u32 s19, s23, 0
	s_add_i32 s54, s41, s31
	v_lshl_add_u64 v[150:151], s[18:19], 0, v[130:131]
	s_mov_b32 m0, s54
	s_nop 0
	global_load_lds_dwordx4 v[150:151], off
	v_lshl_add_u64 v[150:151], s[18:19], 0, v[128:129]
	s_add_i32 m0, s54, 0x2000
	s_nop 0
	global_load_lds_dwordx4 v[150:151], off
	s_waitcnt vmcnt(6)
	s_barrier
	v_mfma_f32_16x16x32_bf16 v[52:55], v[198:201], v[166:169], v[52:55]
	v_mfma_f32_16x16x32_bf16 v[48:51], v[206:209], v[166:169], v[48:51]
	v_mfma_f32_16x16x32_bf16 v[36:39], v[198:201], v[174:177], v[36:39]
	v_mfma_f32_16x16x32_bf16 v[32:35], v[206:209], v[174:177], v[32:35]
	v_mfma_f32_16x16x32_bf16 v[20:23], v[198:201], v[182:185], v[20:23]
	v_mfma_f32_16x16x32_bf16 v[16:19], v[206:209], v[182:185], v[16:19]
	v_mfma_f32_16x16x32_bf16 v[4:7], v[198:201], v[190:193], v[4:7]
	v_mfma_f32_16x16x32_bf16 v[0:3], v[206:209], v[190:193], v[0:3]
	v_mfma_f32_16x16x32_bf16 v[52:55], v[202:205], v[170:173], v[52:55]
	v_mfma_f32_16x16x32_bf16 v[48:51], v[210:213], v[170:173], v[48:51]
	v_mfma_f32_16x16x32_bf16 v[36:39], v[202:205], v[178:181], v[36:39]
	v_mfma_f32_16x16x32_bf16 v[32:35], v[210:213], v[178:181], v[32:35]
	v_mfma_f32_16x16x32_bf16 v[20:23], v[202:205], v[186:189], v[20:23]
	v_mfma_f32_16x16x32_bf16 v[16:19], v[210:213], v[186:189], v[16:19]
	s_add_i32 s54, 0, 0x18000
	v_add_u32_e32 v149, s54, v145
	v_mfma_f32_16x16x32_bf16 v[4:7], v[202:205], v[194:197], v[4:7]
	v_mfma_f32_16x16x32_bf16 v[0:3], v[210:213], v[194:197], v[0:3]
	s_barrier
	ds_read_b128 v[150:153], v149
	ds_read_b128 v[154:157], v149 offset:1024
	ds_read_b128 v[158:161], v149 offset:2048
	ds_read_b128 v[162:165], v149 offset:3072
	s_add_u32 s18, s24, 0x40000
	s_addc_u32 s19, s25, 0
	s_mov_b32 m0, s36
	v_lshl_add_u64 v[198:199], s[18:19], 0, v[130:131]
	ds_read_b128 v[166:169], v147 offset:32768
	ds_read_b128 v[170:173], v147 offset:33792
	ds_read_b128 v[174:177], v147 offset:34816
	ds_read_b128 v[178:181], v147 offset:35840
	ds_read_b128 v[182:185], v147 offset:36864
	ds_read_b128 v[186:189], v147 offset:37888
	ds_read_b128 v[190:193], v147 offset:38912
	ds_read_b128 v[194:197], v147 offset:39936
	global_load_lds_dwordx4 v[198:199], off
	v_lshl_add_u64 v[198:199], s[18:19], 0, v[128:129]
	s_mov_b32 m0, s37
	s_nop 0
	global_load_lds_dwordx4 v[198:199], off
	s_waitcnt lgkmcnt(8)
	s_barrier
	s_waitcnt lgkmcnt(0)
	v_mfma_f32_16x16x32_bf16 v[124:127], v[150:153], v[166:169], v[124:127]
	v_mfma_f32_16x16x32_bf16 v[120:123], v[158:161], v[166:169], v[120:123]
	v_mfma_f32_16x16x32_bf16 v[108:111], v[150:153], v[174:177], v[108:111]
	v_mfma_f32_16x16x32_bf16 v[104:107], v[158:161], v[174:177], v[104:107]
	v_mfma_f32_16x16x32_bf16 v[92:95], v[150:153], v[182:185], v[92:95]
	v_mfma_f32_16x16x32_bf16 v[88:91], v[158:161], v[182:185], v[88:91]
	v_mfma_f32_16x16x32_bf16 v[76:79], v[150:153], v[190:193], v[76:79]
	v_mfma_f32_16x16x32_bf16 v[72:75], v[158:161], v[190:193], v[72:75]
	v_mfma_f32_16x16x32_bf16 v[124:127], v[154:157], v[170:173], v[124:127]
	v_mfma_f32_16x16x32_bf16 v[120:123], v[162:165], v[170:173], v[120:123]
	v_mfma_f32_16x16x32_bf16 v[108:111], v[154:157], v[178:181], v[108:111]
	v_mfma_f32_16x16x32_bf16 v[104:107], v[162:165], v[178:181], v[104:107]
	v_mfma_f32_16x16x32_bf16 v[92:95], v[154:157], v[186:189], v[92:95]
	v_mfma_f32_16x16x32_bf16 v[88:91], v[162:165], v[186:189], v[88:91]
	v_mfma_f32_16x16x32_bf16 v[76:79], v[154:157], v[194:197], v[76:79]
	v_mfma_f32_16x16x32_bf16 v[72:75], v[162:165], v[194:197], v[72:75]
	s_barrier
	s_add_i32 s24, 0, 0x1c000
	s_add_i32 s18, s54, s31
	v_add_u32_e32 v149, s24, v145
	v_lshl_add_u64 v[142:143], v[142:143], 0, s[10:11]
	s_mov_b32 m0, s18
	ds_read_b128 v[198:201], v149
	ds_read_b128 v[202:205], v149 offset:1024
	ds_read_b128 v[206:209], v149 offset:2048
	ds_read_b128 v[210:213], v149 offset:3072
	global_load_lds_dwordx4 v[142:143], off
	v_lshl_add_u64 v[142:143], v[214:215], 0, s[10:11]
	s_add_i32 m0, s18, 0x2000
	s_nop 0
	global_load_lds_dwordx4 v[142:143], off
	s_barrier
	s_waitcnt lgkmcnt(0)
	v_mfma_f32_16x16x32_bf16 v[116:119], v[198:201], v[166:169], v[116:119]
	v_mfma_f32_16x16x32_bf16 v[112:115], v[206:209], v[166:169], v[112:115]
	v_mfma_f32_16x16x32_bf16 v[100:103], v[198:201], v[174:177], v[100:103]
	v_mfma_f32_16x16x32_bf16 v[96:99], v[206:209], v[174:177], v[96:99]
	v_mfma_f32_16x16x32_bf16 v[84:87], v[198:201], v[182:185], v[84:87]
	v_mfma_f32_16x16x32_bf16 v[80:83], v[206:209], v[182:185], v[80:83]
	v_mfma_f32_16x16x32_bf16 v[68:71], v[198:201], v[190:193], v[68:71]
	v_mfma_f32_16x16x32_bf16 v[64:67], v[206:209], v[190:193], v[64:67]
	v_mfma_f32_16x16x32_bf16 v[116:119], v[202:205], v[170:173], v[116:119]
	v_mfma_f32_16x16x32_bf16 v[112:115], v[210:213], v[170:173], v[112:115]
	v_mfma_f32_16x16x32_bf16 v[100:103], v[202:205], v[178:181], v[100:103]
	v_mfma_f32_16x16x32_bf16 v[96:99], v[210:213], v[178:181], v[96:99]
	v_mfma_f32_16x16x32_bf16 v[84:87], v[202:205], v[186:189], v[84:87]
	v_mfma_f32_16x16x32_bf16 v[80:83], v[210:213], v[186:189], v[80:83]
	s_mov_b32 m0, s38
	v_lshl_add_u64 v[142:143], v[216:217], 0, s[10:11]
	v_mfma_f32_16x16x32_bf16 v[68:71], v[202:205], v[194:197], v[68:71]
	v_mfma_f32_16x16x32_bf16 v[64:67], v[210:213], v[194:197], v[64:67]
	s_barrier
	ds_read_b128 v[166:169], v147 offset:49152
	ds_read_b128 v[170:173], v147 offset:50176
	ds_read_b128 v[174:177], v147 offset:51200
	ds_read_b128 v[178:181], v147 offset:52224
	ds_read_b128 v[182:185], v147 offset:53248
	ds_read_b128 v[186:189], v147 offset:54272
	ds_read_b128 v[190:193], v147 offset:55296
	ds_read_b128 v[194:197], v147 offset:56320
	global_load_lds_dwordx4 v[142:143], off
	v_lshl_add_u64 v[142:143], v[218:219], 0, s[10:11]
	s_mov_b32 m0, s39
	s_nop 0
	global_load_lds_dwordx4 v[142:143], off
	s_barrier
; #define STG(P, GB) do { const char* _gb = (GB); \
;     _Pragma("unroll") for (int _i = 0; _i < 2; ++_i) { \
;       __builtin_amdgcn_global_load_lds((const unsigned*)(_gb + voff[_i]), \
;         (LAS unsigned*)((LAS char*)(P) + ldsw + _i * 8192), 16, 0, 0); } } while (0)
; #define MMA(ai, bj, At_, Bt_) do { __builtin_amdgcn_s_setprio(1); \
;     _Pragma("unroll") for (int m = 0; m < 4; ++m) _Pragma("unroll") for (int n = 0; n < 2; ++n) _Pragma("unroll") for (int k = 0; k < 2; ++k) \
;       acc[ai][bj][m][n] = __builtin_amdgcn_mfma_f32_16x16x32_bf16(Bt_[n][k], At_[m][k], acc[ai][bj][m][n], 0, 0, 0); \
;     __builtin_amdgcn_s_setprio(0); } while (0)
; #define WAIT_V(n) asm volatile("s_waitcnt vmcnt(" #n ")" ::: "memory")
; #define WAIT_L(n) asm volatile("s_waitcnt lgkmcnt(" #n ")" ::: "memory")
; #define BAR __builtin_amdgcn_s_barrier()
; #define SCHED __builtin_amdgcn_sched_barrier(0)
; __device__ __forceinline__ void gemm_phase(const bf16_t* __restrict__ A, const bf16_t* __restrict__ Bt, bf16_t* __restrict__ C, int M, int N, int K,
;                                            int ldc, const int EPI, char* smem, const int wid_u) {
;     ...
;       BAR; WAIT_L(0); MMA(1, 0, At, B0); BAR; SCHED;
;       STG(SB(1, 1), b3 + hstep);
;       WAIT_V(6); BAR; MMA(1, 1, At, B1); BAR;
;     }
;     {
;       const int brow = pm * BM, bcol = pn * BM;
; #pragma unroll
;       for (int ai = 0; ai < 2; ++ai)
; #pragma unroll
;         for (int m = 0; m < 4; ++m) {
;           const size_t row = (size_t)(brow + ai * HALF + wr * 64 + m * 16 + fr);
;           if (EPI == 0) {
; #pragma unroll
;             for (int bj = 0; bj < 2; ++bj) {
;               const f32x4 v0 = acc[ai][bj][m][0], v1 = acc[ai][bj][m][1];
;               uint4 u; u.x = cvt_pk_bf16(v0[0], v0[1]); u.y = cvt_pk_bf16(v0[2], v0[3]); u.z = cvt_pk_bf16(v1[0], v1[1]); u.w = cvt_pk_bf16(v1[2], v1[3]);
;               *(uint4*)(C + row * ldc + bcol + bj * HALF + wc * 32 + fq * 8) = u;
;             }
;           } else {
;             float o[8];
; #pragma unroll
;             for (int n = 0; n < 2; ++n) {
;               const f32x4 a = acc[ai][0][m][n], b = acc[ai][1][m][n];
; #pragma unroll
;               for (int j = 0; j < 4; ++j) o[n * 4 + j] = a[j] * __builtin_amdgcn_rcpf(1.f + __expf(-a[j])) * b[j];
;             }
;             *(uint4*)(C + row * ldc + (bcol >> 1) + wc * 32 + fq * 8) = pack8(o);
	s_waitcnt lgkmcnt(0)
	v_mfma_f32_16x16x32_bf16 v[60:63], v[150:153], v[166:169], v[60:63]
	v_mfma_f32_16x16x32_bf16 v[56:59], v[158:161], v[166:169], v[56:59]
	v_mfma_f32_16x16x32_bf16 v[44:47], v[150:153], v[174:177], v[44:47]
	v_mfma_f32_16x16x32_bf16 v[40:43], v[158:161], v[174:177], v[40:43]
	v_mfma_f32_16x16x32_bf16 v[28:31], v[150:153], v[182:185], v[28:31]
	v_mfma_f32_16x16x32_bf16 v[24:27], v[158:161], v[182:185], v[24:27]
	v_mfma_f32_16x16x32_bf16 v[12:15], v[150:153], v[190:193], v[12:15]
	v_mfma_f32_16x16x32_bf16 v[8:11], v[158:161], v[190:193], v[8:11]
	v_mfma_f32_16x16x32_bf16 v[60:63], v[154:157], v[170:173], v[60:63]
	v_mfma_f32_16x16x32_bf16 v[56:59], v[162:165], v[170:173], v[56:59]
	v_mfma_f32_16x16x32_bf16 v[44:47], v[154:157], v[178:181], v[44:47]
	v_mfma_f32_16x16x32_bf16 v[40:43], v[162:165], v[178:181], v[40:43]
	v_mfma_f32_16x16x32_bf16 v[28:31], v[154:157], v[186:189], v[28:31]
	v_mfma_f32_16x16x32_bf16 v[24:27], v[162:165], v[186:189], v[24:27]
	v_mfma_f32_16x16x32_bf16 v[12:15], v[154:157], v[194:197], v[12:15]
	v_mfma_f32_16x16x32_bf16 v[8:11], v[162:165], v[194:197], v[8:11]
	s_barrier
	s_add_u32 s18, s22, 0x40080
	s_addc_u32 s19, s23, 0
	s_add_i32 s22, s24, s31
	v_lshl_add_u64 v[142:143], s[18:19], 0, v[130:131]
	s_mov_b32 m0, s22
	s_nop 0
	global_load_lds_dwordx4 v[142:143], off
	v_lshl_add_u64 v[142:143], s[18:19], 0, v[128:129]
	s_add_i32 m0, s22, 0x2000
	s_nop 0
	global_load_lds_dwordx4 v[142:143], off
	s_waitcnt vmcnt(6)
	s_barrier
	v_mfma_f32_16x16x32_bf16 v[52:55], v[198:201], v[166:169], v[52:55]
	v_mfma_f32_16x16x32_bf16 v[48:51], v[206:209], v[166:169], v[48:51]
	v_mfma_f32_16x16x32_bf16 v[36:39], v[198:201], v[174:177], v[36:39]
	v_mfma_f32_16x16x32_bf16 v[32:35], v[206:209], v[174:177], v[32:35]
	v_mfma_f32_16x16x32_bf16 v[20:23], v[198:201], v[182:185], v[20:23]
	v_mfma_f32_16x16x32_bf16 v[16:19], v[206:209], v[182:185], v[16:19]
	v_mfma_f32_16x16x32_bf16 v[4:7], v[198:201], v[190:193], v[4:7]
	v_mfma_f32_16x16x32_bf16 v[0:3], v[206:209], v[190:193], v[0:3]
	v_mfma_f32_16x16x32_bf16 v[52:55], v[202:205], v[170:173], v[52:55]
	v_mfma_f32_16x16x32_bf16 v[48:51], v[210:213], v[170:173], v[48:51]
	v_mfma_f32_16x16x32_bf16 v[36:39], v[202:205], v[178:181], v[36:39]
	v_mfma_f32_16x16x32_bf16 v[32:35], v[210:213], v[178:181], v[32:35]
	v_mfma_f32_16x16x32_bf16 v[20:23], v[202:205], v[186:189], v[20:23]
	v_mfma_f32_16x16x32_bf16 v[16:19], v[210:213], v[186:189], v[16:19]
	s_add_i32 s53, s53, 2
	s_add_u32 s51, s51, 0x100
	s_addc_u32 s52, s52, 0
	s_cmp_gt_u32 s53, 13
	s_mov_b64 s[18:19], s[20:21]
	v_mfma_f32_16x16x32_bf16 v[4:7], v[202:205], v[194:197], v[4:7]
	v_mfma_f32_16x16x32_bf16 v[0:3], v[210:213], v[194:197], v[0:3]
	s_barrier
	s_cbranch_scc0 .LBB0_1026
	v_mul_f32_e32 v142, 0xbfb8aa3b, v124
	v_exp_f32_e32 v142, v142
	v_mul_f32_e32 v143, 0xbfb8aa3b, v125
	v_exp_f32_e32 v143, v143
	s_lshl_b32 s18, s46, 8
	v_add_f32_e32 v142, 1.0, v142
	v_rcp_f32_e32 v150, v142
	v_add_f32_e32 v142, 1.0, v143
	v_rcp_f32_e32 v151, v142
	s_mov_b32 s19, s9
	v_lshl_add_u32 v149, s47, 8, v144
	v_lshl_add_u64 v[142:143], v[132:133], 0, s[18:19]
	v_pk_mul_f32 v[124:125], v[124:125], v[150:151]
	v_mul_f32_e32 v150, 0xbfb8aa3b, v126
	v_mul_f32_e32 v151, 0xbfb8aa3b, v127
	v_exp_f32_e32 v150, v150
	v_exp_f32_e32 v151, v151
	v_pk_mul_f32 v[116:117], v[124:125], v[116:117]
	s_and_b64 vcc, exec, s[4:5]
	v_add_f32_e32 v124, 1.0, v150
	v_add_f32_e32 v125, 1.0, v151
	v_mul_f32_e32 v150, 0xbfb8aa3b, v120
	v_mul_f32_e32 v151, 0xbfb8aa3b, v121
	v_rcp_f32_e32 v124, v124
	v_rcp_f32_e32 v125, v125
	v_exp_f32_e32 v150, v150
	v_exp_f32_e32 v151, v151
	s_mov_b32 s47, s8
	v_pk_mul_f32 v[124:125], v[126:127], v[124:125]
	v_add_f32_e32 v126, 1.0, v150
	v_add_f32_e32 v127, 1.0, v151
	v_mul_f32_e32 v150, 0xbfb8aa3b, v122
	v_mul_f32_e32 v151, 0xbfb8aa3b, v123
	v_exp_f32_e32 v150, v150
	v_exp_f32_e32 v151, v151
	v_rcp_f32_e32 v126, v126
	v_rcp_f32_e32 v127, v127
	v_add_f32_e32 v150, 1.0, v150
	v_add_f32_e32 v151, 1.0, v151
	v_rcp_f32_e32 v150, v150
	v_rcp_f32_e32 v151, v151
	v_pk_mul_f32 v[120:121], v[120:121], v[126:127]
	v_pk_mul_f32 v[118:119], v[124:125], v[118:119]
	v_pk_mul_f32 v[120:121], v[120:121], v[112:113]
	v_pk_mul_f32 v[112:113], v[122:123], v[150:151]
	s_mov_b32 s46, s12
	v_pk_mul_f32 v[122:123], v[112:113], v[114:115]
	v_mul_f32_e32 v115, 0xbfb8aa3b, v108
	v_cvt_pk_bf16_f32 v112, v116, v117
	v_exp_f32_e32 v116, v115
	v_mul_f32_e32 v115, 0xbfb8aa3b, v109
	v_exp_f32_e32 v117, v115
	v_cvt_pk_bf16_f32 v113, v118, v119
	v_cvt_pk_bf16_f32 v114, v120, v121
	v_cvt_pk_bf16_f32 v115, v122, v123
	v_add_f32_e32 v116, 1.0, v116
	v_add_f32_e32 v117, 1.0, v117
	v_mad_i64_i32 v[118:119], s[18:19], v149, s44, v[142:143]
	v_rcp_f32_e32 v116, v116
	v_rcp_f32_e32 v117, v117
	global_store_dwordx4 v[118:119], v[112:115], off
	s_mov_b64 s[20:21], s[16:17]
	v_pk_mul_f32 v[108:109], v[108:109], v[116:117]
	v_mul_f32_e32 v112, 0xbfb8aa3b, v110
	v_mul_f32_e32 v113, 0xbfb8aa3b, v111
	v_exp_f32_e32 v112, v112
	v_exp_f32_e32 v113, v113
	v_pk_mul_f32 v[100:101], v[108:109], v[100:101]
	v_or_b32_e32 v114, 16, v149
	v_add_f32_e32 v108, 1.0, v112
	v_add_f32_e32 v109, 1.0, v113
	v_mul_f32_e32 v112, 0xbfb8aa3b, v104
	v_mul_f32_e32 v113, 0xbfb8aa3b, v105
	v_rcp_f32_e32 v108, v108
	v_rcp_f32_e32 v109, v109
	v_exp_f32_e32 v112, v112
	v_exp_f32_e32 v113, v113
	v_pk_mul_f32 v[108:109], v[110:111], v[108:109]
	v_add_f32_e32 v110, 1.0, v112
	v_add_f32_e32 v111, 1.0, v113
	v_mul_f32_e32 v112, 0xbfb8aa3b, v106
	v_mul_f32_e32 v113, 0xbfb8aa3b, v107
	v_exp_f32_e32 v112, v112
	v_exp_f32_e32 v113, v113
	v_rcp_f32_e32 v110, v110
	v_rcp_f32_e32 v111, v111
	v_add_f32_e32 v112, 1.0, v112
; __device__ __forceinline__ void gemm_phase(const bf16_t* __restrict__ A, const bf16_t* __restrict__ Bt, bf16_t* __restrict__ C, int M, int N, int K,
;                                            int ldc, const int EPI, char* smem, const int wid_u) {
;     ...
;       for (int ai = 0; ai < 2; ++ai)
; #pragma unroll
;         for (int m = 0; m < 4; ++m) {
;           const size_t row = (size_t)(brow + ai * HALF + wr * 64 + m * 16 + fr);
;           if (EPI == 0) {
; #pragma unroll
;             for (int bj = 0; bj < 2; ++bj) {
;               const f32x4 v0 = acc[ai][bj][m][0], v1 = acc[ai][bj][m][1];
;               uint4 u; u.x = cvt_pk_bf16(v0[0], v0[1]); u.y = cvt_pk_bf16(v0[2], v0[3]); u.z = cvt_pk_bf16(v1[0], v1[1]); u.w = cvt_pk_bf16(v1[2], v1[3]);
;               *(uint4*)(C + row * ldc + bcol + bj * HALF + wc * 32 + fq * 8) = u;
;             }
;           } else {
;             float o[8];
; #pragma unroll
;             for (int n = 0; n < 2; ++n) {
;               const f32x4 a = acc[ai][0][m][n], b = acc[ai][1][m][n];
; #pragma unroll
;               for (int j = 0; j < 4; ++j) o[n * 4 + j] = a[j] * __builtin_amdgcn_rcpf(1.f + __expf(-a[j])) * b[j];
;             }
;             *(uint4*)(C + row * ldc + (bcol >> 1) + wc * 32 + fq * 8) = pack8(o);
	v_add_f32_e32 v113, 1.0, v113
	v_rcp_f32_e32 v112, v112
	v_rcp_f32_e32 v113, v113
	v_pk_mul_f32 v[104:105], v[104:105], v[110:111]
	v_pk_mul_f32 v[102:103], v[108:109], v[102:103]
	v_pk_mul_f32 v[104:105], v[104:105], v[96:97]
	v_pk_mul_f32 v[96:97], v[106:107], v[112:113]
	s_nop 0
	v_pk_mul_f32 v[106:107], v[96:97], v[98:99]
	v_mul_f32_e32 v99, 0xbfb8aa3b, v92
	v_cvt_pk_bf16_f32 v96, v100, v101
	v_exp_f32_e32 v100, v99
	v_mul_f32_e32 v99, 0xbfb8aa3b, v93
	v_exp_f32_e32 v101, v99
	v_cvt_pk_bf16_f32 v97, v102, v103
	v_cvt_pk_bf16_f32 v98, v104, v105
	v_cvt_pk_bf16_f32 v99, v106, v107
	v_add_f32_e32 v100, 1.0, v100
	v_add_f32_e32 v101, 1.0, v101
	v_mad_i64_i32 v[102:103], s[18:19], v114, s44, v[142:143]
	v_rcp_f32_e32 v100, v100
	v_rcp_f32_e32 v101, v101
	global_store_dwordx4 v[102:103], v[96:99], off
	v_pk_mul_f32 v[92:93], v[92:93], v[100:101]
	s_nop 0
	v_mul_f32_e32 v96, 0xbfb8aa3b, v94
	v_mul_f32_e32 v97, 0xbfb8aa3b, v95
	v_exp_f32_e32 v96, v96
	v_exp_f32_e32 v97, v97
	v_pk_mul_f32 v[84:85], v[92:93], v[84:85]
	v_or_b32_e32 v98, 32, v149
	v_add_f32_e32 v92, 1.0, v96
	v_add_f32_e32 v93, 1.0, v97
	v_mul_f32_e32 v96, 0xbfb8aa3b, v88
	v_mul_f32_e32 v97, 0xbfb8aa3b, v89
	v_rcp_f32_e32 v92, v92
	v_rcp_f32_e32 v93, v93
	v_exp_f32_e32 v96, v96
	v_exp_f32_e32 v97, v97
	v_pk_mul_f32 v[92:93], v[94:95], v[92:93]
	v_add_f32_e32 v94, 1.0, v96
	v_add_f32_e32 v95, 1.0, v97
	v_mul_f32_e32 v96, 0xbfb8aa3b, v90
	v_mul_f32_e32 v97, 0xbfb8aa3b, v91
	v_exp_f32_e32 v96, v96
	v_exp_f32_e32 v97, v97
	v_rcp_f32_e32 v94, v94
	v_rcp_f32_e32 v95, v95
	v_add_f32_e32 v96, 1.0, v96
	v_add_f32_e32 v97, 1.0, v97
	v_rcp_f32_e32 v96, v96
	v_rcp_f32_e32 v97, v97
	v_pk_mul_f32 v[88:89], v[88:89], v[94:95]
	v_pk_mul_f32 v[86:87], v[92:93], v[86:87]
	v_pk_mul_f32 v[88:89], v[88:89], v[80:81]
	v_pk_mul_f32 v[80:81], v[90:91], v[96:97]
	s_nop 0
	v_pk_mul_f32 v[90:91], v[80:81], v[82:83]
	v_mul_f32_e32 v83, 0xbfb8aa3b, v76
	v_cvt_pk_bf16_f32 v80, v84, v85
	v_exp_f32_e32 v84, v83
	v_mul_f32_e32 v83, 0xbfb8aa3b, v77
	v_exp_f32_e32 v85, v83
	v_cvt_pk_bf16_f32 v81, v86, v87
	v_cvt_pk_bf16_f32 v82, v88, v89
	v_cvt_pk_bf16_f32 v83, v90, v91
	v_add_f32_e32 v84, 1.0, v84
	v_add_f32_e32 v85, 1.0, v85
	v_mad_i64_i32 v[86:87], s[18:19], v98, s44, v[142:143]
	v_rcp_f32_e32 v84, v84
	v_rcp_f32_e32 v85, v85
	global_store_dwordx4 v[86:87], v[80:83], off
	v_pk_mul_f32 v[76:77], v[76:77], v[84:85]
	s_nop 0
	v_mul_f32_e32 v80, 0xbfb8aa3b, v78
	v_mul_f32_e32 v81, 0xbfb8aa3b, v79
	v_exp_f32_e32 v80, v80
	v_exp_f32_e32 v81, v81
	v_pk_mul_f32 v[68:69], v[76:77], v[68:69]
	v_or_b32_e32 v82, 48, v149
	v_add_f32_e32 v76, 1.0, v80
	v_add_f32_e32 v77, 1.0, v81
	v_mul_f32_e32 v80, 0xbfb8aa3b, v72
	v_mul_f32_e32 v81, 0xbfb8aa3b, v73
	v_rcp_f32_e32 v76, v76
	v_rcp_f32_e32 v77, v77
	v_exp_f32_e32 v80, v80
	v_exp_f32_e32 v81, v81
	v_pk_mul_f32 v[76:77], v[78:79], v[76:77]
	v_add_f32_e32 v78, 1.0, v80
	v_add_f32_e32 v79, 1.0, v81
	v_mul_f32_e32 v80, 0xbfb8aa3b, v74
	v_mul_f32_e32 v81, 0xbfb8aa3b, v75
	v_exp_f32_e32 v80, v80
	v_exp_f32_e32 v81, v81
	v_rcp_f32_e32 v78, v78
	v_rcp_f32_e32 v79, v79
	v_add_f32_e32 v80, 1.0, v80
	v_add_f32_e32 v81, 1.0, v81
	v_rcp_f32_e32 v80, v80
	v_rcp_f32_e32 v81, v81
	v_pk_mul_f32 v[72:73], v[72:73], v[78:79]
	v_pk_mul_f32 v[70:71], v[76:77], v[70:71]
	v_pk_mul_f32 v[72:73], v[72:73], v[64:65]
	v_pk_mul_f32 v[64:65], v[74:75], v[80:81]
	s_nop 0
	v_pk_mul_f32 v[74:75], v[64:65], v[66:67]
	v_mul_f32_e32 v67, 0xbfb8aa3b, v60
	v_cvt_pk_bf16_f32 v64, v68, v69
	v_exp_f32_e32 v68, v67
	v_mul_f32_e32 v67, 0xbfb8aa3b, v61
	v_exp_f32_e32 v69, v67
	v_cvt_pk_bf16_f32 v65, v70, v71
	v_cvt_pk_bf16_f32 v66, v72, v73
	v_cvt_pk_bf16_f32 v67, v74, v75
	v_add_f32_e32 v68, 1.0, v68
	v_add_f32_e32 v69, 1.0, v69
	v_mad_i64_i32 v[70:71], s[18:19], v82, s44, v[142:143]
	v_rcp_f32_e32 v68, v68
	v_rcp_f32_e32 v69, v69
	global_store_dwordx4 v[70:71], v[64:67], off
	v_pk_mul_f32 v[60:61], v[60:61], v[68:69]
	s_nop 0
	v_mul_f32_e32 v64, 0xbfb8aa3b, v62
	v_mul_f32_e32 v65, 0xbfb8aa3b, v63
	v_exp_f32_e32 v64, v64
	v_exp_f32_e32 v65, v65
	v_pk_mul_f32 v[52:53], v[60:61], v[52:53]
	v_add_u32_e32 v66, 0x80, v149
	v_add_f32_e32 v60, 1.0, v64
	v_add_f32_e32 v61, 1.0, v65
	v_mul_f32_e32 v64, 0xbfb8aa3b, v56
	v_mul_f32_e32 v65, 0xbfb8aa3b, v57
	v_rcp_f32_e32 v60, v60
	v_rcp_f32_e32 v61, v61
	v_exp_f32_e32 v64, v64
	v_exp_f32_e32 v65, v65
	v_pk_mul_f32 v[60:61], v[62:63], v[60:61]
	v_add_f32_e32 v62, 1.0, v64
	v_add_f32_e32 v63, 1.0, v65
	v_mul_f32_e32 v64, 0xbfb8aa3b, v58
	v_mul_f32_e32 v65, 0xbfb8aa3b, v59
	v_exp_f32_e32 v64, v64
	v_exp_f32_e32 v65, v65
	v_rcp_f32_e32 v62, v62
	v_rcp_f32_e32 v63, v63
	v_add_f32_e32 v64, 1.0, v64
	v_add_f32_e32 v65, 1.0, v65
	v_rcp_f32_e32 v64, v64
	v_rcp_f32_e32 v65, v65
	v_pk_mul_f32 v[56:57], v[56:57], v[62:63]
	v_pk_mul_f32 v[54:55], v[60:61], v[54:55]
	v_pk_mul_f32 v[56:57], v[56:57], v[48:49]
	v_pk_mul_f32 v[48:49], v[58:59], v[64:65]
	s_nop 0
	v_pk_mul_f32 v[58:59], v[48:49], v[50:51]
; #define WAIT_V(n) asm volatile("s_waitcnt vmcnt(" #n ")" ::: "memory")
; #define BAR __builtin_amdgcn_s_barrier()
; __device__ __forceinline__ void gemm_phase(const bf16_t* __restrict__ A, const bf16_t* __restrict__ Bt, bf16_t* __restrict__ C, int M, int N, int K,
;                                            int ldc, const int EPI, char* smem, const int wid_u) {
;     ...
;       for (int ai = 0; ai < 2; ++ai)
; #pragma unroll
;         for (int m = 0; m < 4; ++m) {
;           const size_t row = (size_t)(brow + ai * HALF + wr * 64 + m * 16 + fr);
;           if (EPI == 0) {
; #pragma unroll
;             for (int bj = 0; bj < 2; ++bj) {
;               const f32x4 v0 = acc[ai][bj][m][0], v1 = acc[ai][bj][m][1];
;               uint4 u; u.x = cvt_pk_bf16(v0[0], v0[1]); u.y = cvt_pk_bf16(v0[2], v0[3]); u.z = cvt_pk_bf16(v1[0], v1[1]); u.w = cvt_pk_bf16(v1[2], v1[3]);
;               *(uint4*)(C + row * ldc + bcol + bj * HALF + wc * 32 + fq * 8) = u;
;             }
;           } else {
;             float o[8];
; #pragma unroll
;             for (int n = 0; n < 2; ++n) {
;               const f32x4 a = acc[ai][0][m][n], b = acc[ai][1][m][n];
; #pragma unroll
;               for (int j = 0; j < 4; ++j) o[n * 4 + j] = a[j] * __builtin_amdgcn_rcpf(1.f + __expf(-a[j])) * b[j];
;             }
;             *(uint4*)(C + row * ldc + (bcol >> 1) + wc * 32 + fq * 8) = pack8(o);
;           }
;         }
;     }
;     if (!has_next) break;
; #pragma unroll
;     for (int a = 0; a < 2; ++a)
; #pragma unroll
;       for (int b = 0; b < 2; ++b)
; #pragma unroll
;         for (int m = 0; m < 4; ++m)
; #pragma unroll
;           for (int n = 0; n < 2; ++n) acc[a][b][m][n] = (f32x4){0.f, 0.f, 0.f, 0.f};
;     pm = npm; pn = npn; cA = nA; cB = nB; ++ui;
;   }
;   WAIT_V(0);
;   if (wr == 0) BAR;
;   BAR;
	v_mul_f32_e32 v51, 0xbfb8aa3b, v44
	v_cvt_pk_bf16_f32 v48, v52, v53
	v_exp_f32_e32 v52, v51
	v_mul_f32_e32 v51, 0xbfb8aa3b, v45
	v_exp_f32_e32 v53, v51
	v_cvt_pk_bf16_f32 v49, v54, v55
	v_cvt_pk_bf16_f32 v50, v56, v57
	v_cvt_pk_bf16_f32 v51, v58, v59
	v_add_f32_e32 v52, 1.0, v52
	v_add_f32_e32 v53, 1.0, v53
	v_mad_i64_i32 v[54:55], s[18:19], v66, s44, v[142:143]
	v_rcp_f32_e32 v52, v52
	v_rcp_f32_e32 v53, v53
	global_store_dwordx4 v[54:55], v[48:51], off
	v_pk_mul_f32 v[44:45], v[44:45], v[52:53]
	s_nop 0
	v_mul_f32_e32 v48, 0xbfb8aa3b, v46
	v_mul_f32_e32 v49, 0xbfb8aa3b, v47
	v_exp_f32_e32 v48, v48
	v_exp_f32_e32 v49, v49
	v_pk_mul_f32 v[36:37], v[44:45], v[36:37]
	v_add_u32_e32 v50, 0x90, v149
	v_add_f32_e32 v44, 1.0, v48
	v_add_f32_e32 v45, 1.0, v49
	v_mul_f32_e32 v48, 0xbfb8aa3b, v40
	v_mul_f32_e32 v49, 0xbfb8aa3b, v41
	v_rcp_f32_e32 v44, v44
	v_rcp_f32_e32 v45, v45
	v_exp_f32_e32 v48, v48
	v_exp_f32_e32 v49, v49
	v_pk_mul_f32 v[44:45], v[46:47], v[44:45]
	v_add_f32_e32 v46, 1.0, v48
	v_add_f32_e32 v47, 1.0, v49
	v_mul_f32_e32 v48, 0xbfb8aa3b, v42
	v_mul_f32_e32 v49, 0xbfb8aa3b, v43
	v_exp_f32_e32 v48, v48
	v_exp_f32_e32 v49, v49
	v_rcp_f32_e32 v46, v46
	v_rcp_f32_e32 v47, v47
	v_add_f32_e32 v48, 1.0, v48
	v_add_f32_e32 v49, 1.0, v49
	v_rcp_f32_e32 v48, v48
	v_rcp_f32_e32 v49, v49
	v_pk_mul_f32 v[40:41], v[40:41], v[46:47]
	v_pk_mul_f32 v[38:39], v[44:45], v[38:39]
	v_pk_mul_f32 v[40:41], v[40:41], v[32:33]
	v_pk_mul_f32 v[32:33], v[42:43], v[48:49]
	s_nop 0
	v_pk_mul_f32 v[42:43], v[32:33], v[34:35]
	v_mul_f32_e32 v35, 0xbfb8aa3b, v28
	v_cvt_pk_bf16_f32 v32, v36, v37
	v_exp_f32_e32 v36, v35
	v_mul_f32_e32 v35, 0xbfb8aa3b, v29
	v_exp_f32_e32 v37, v35
	v_cvt_pk_bf16_f32 v33, v38, v39
	v_cvt_pk_bf16_f32 v34, v40, v41
	v_cvt_pk_bf16_f32 v35, v42, v43
	v_add_f32_e32 v36, 1.0, v36
	v_add_f32_e32 v37, 1.0, v37
	v_mad_i64_i32 v[38:39], s[18:19], v50, s44, v[142:143]
	v_rcp_f32_e32 v36, v36
	v_rcp_f32_e32 v37, v37
	global_store_dwordx4 v[38:39], v[32:35], off
	v_pk_mul_f32 v[28:29], v[28:29], v[36:37]
	s_nop 0
	v_mul_f32_e32 v32, 0xbfb8aa3b, v30
	v_mul_f32_e32 v33, 0xbfb8aa3b, v31
	v_exp_f32_e32 v32, v32
	v_exp_f32_e32 v33, v33
	v_pk_mul_f32 v[20:21], v[28:29], v[20:21]
	v_add_u32_e32 v34, 0xa0, v149
	v_add_f32_e32 v28, 1.0, v32
	v_add_f32_e32 v29, 1.0, v33
	v_mul_f32_e32 v32, 0xbfb8aa3b, v24
	v_mul_f32_e32 v33, 0xbfb8aa3b, v25
	v_rcp_f32_e32 v28, v28
	v_rcp_f32_e32 v29, v29
	v_exp_f32_e32 v32, v32
	v_exp_f32_e32 v33, v33
	v_pk_mul_f32 v[28:29], v[30:31], v[28:29]
	v_add_f32_e32 v30, 1.0, v32
	v_add_f32_e32 v31, 1.0, v33
	v_mul_f32_e32 v32, 0xbfb8aa3b, v26
	v_mul_f32_e32 v33, 0xbfb8aa3b, v27
	v_exp_f32_e32 v32, v32
	v_exp_f32_e32 v33, v33
	v_rcp_f32_e32 v30, v30
	v_rcp_f32_e32 v31, v31
	v_add_f32_e32 v32, 1.0, v32
	v_add_f32_e32 v33, 1.0, v33
	v_rcp_f32_e32 v32, v32
	v_rcp_f32_e32 v33, v33
	v_pk_mul_f32 v[24:25], v[24:25], v[30:31]
	v_pk_mul_f32 v[22:23], v[28:29], v[22:23]
	v_pk_mul_f32 v[24:25], v[24:25], v[16:17]
	v_pk_mul_f32 v[16:17], v[26:27], v[32:33]
	s_nop 0
	v_pk_mul_f32 v[26:27], v[16:17], v[18:19]
	v_mul_f32_e32 v19, 0xbfb8aa3b, v12
	v_cvt_pk_bf16_f32 v16, v20, v21
	v_exp_f32_e32 v20, v19
	v_mul_f32_e32 v19, 0xbfb8aa3b, v13
	v_exp_f32_e32 v21, v19
	v_cvt_pk_bf16_f32 v17, v22, v23
	v_cvt_pk_bf16_f32 v18, v24, v25
	v_cvt_pk_bf16_f32 v19, v26, v27
	v_add_f32_e32 v20, 1.0, v20
	v_add_f32_e32 v21, 1.0, v21
	v_mad_i64_i32 v[22:23], s[18:19], v34, s44, v[142:143]
	v_rcp_f32_e32 v20, v20
	v_rcp_f32_e32 v21, v21
	global_store_dwordx4 v[22:23], v[16:19], off
	v_pk_mul_f32 v[12:13], v[12:13], v[20:21]
	s_nop 0
	v_mul_f32_e32 v16, 0xbfb8aa3b, v14
	v_mul_f32_e32 v17, 0xbfb8aa3b, v15
	v_exp_f32_e32 v16, v16
	v_exp_f32_e32 v17, v17
	v_pk_mul_f32 v[4:5], v[12:13], v[4:5]
	v_add_u32_e32 v18, 0xb0, v149
	v_add_f32_e32 v12, 1.0, v16
	v_add_f32_e32 v13, 1.0, v17
	v_mul_f32_e32 v16, 0xbfb8aa3b, v8
	v_mul_f32_e32 v17, 0xbfb8aa3b, v9
	v_rcp_f32_e32 v12, v12
	v_rcp_f32_e32 v13, v13
	v_exp_f32_e32 v16, v16
	v_exp_f32_e32 v17, v17
	v_pk_mul_f32 v[12:13], v[14:15], v[12:13]
	v_add_f32_e32 v14, 1.0, v16
	v_add_f32_e32 v15, 1.0, v17
	v_mul_f32_e32 v16, 0xbfb8aa3b, v10
	v_mul_f32_e32 v17, 0xbfb8aa3b, v11
	v_exp_f32_e32 v16, v16
	v_exp_f32_e32 v17, v17
	v_rcp_f32_e32 v14, v14
	v_rcp_f32_e32 v15, v15
	v_add_f32_e32 v16, 1.0, v16
	v_add_f32_e32 v17, 1.0, v17
	v_rcp_f32_e32 v16, v16
	v_rcp_f32_e32 v17, v17
	v_pk_mul_f32 v[8:9], v[8:9], v[14:15]
	v_pk_mul_f32 v[6:7], v[12:13], v[6:7]
	v_pk_mul_f32 v[8:9], v[8:9], v[0:1]
	v_pk_mul_f32 v[0:1], v[10:11], v[16:17]
	s_nop 0
	v_pk_mul_f32 v[10:11], v[0:1], v[2:3]
	v_cvt_pk_bf16_f32 v0, v4, v5
	v_mad_i64_i32 v[4:5], s[18:19], v18, s44, v[142:143]
	v_cvt_pk_bf16_f32 v1, v6, v7
	v_cvt_pk_bf16_f32 v2, v8, v9
	v_cvt_pk_bf16_f32 v3, v10, v11
	s_mov_b64 s[18:19], s[14:15]
	global_store_dwordx4 v[4:5], v[0:3], off
	s_cbranch_vccz .LBB0_1023
	s_waitcnt vmcnt(0)
	s_cmpk_gt_u32 s26, 0xff
	s_cbranch_scc1 .LBB0_1030
	s_barrier
